# PH7 ssq loads issued one unit ahead; PH12 mid-epilogue vmcnt(0) drain relaxed to vmcnt(12); flat->global memory ops in EpiResidual/EpiPle epilogues (on v34)
# baseline (speedup 1.0000x reference)
; __device__ __forceinline__ int lane_id_asm() { int l; asm volatile("v_mbcnt_lo_u32_b32 %0, -1, 0\n\tv_mbcnt_hi_u32_b32 %0, -1, %0" : "=v"(l)); return l; }
; __device__ __forceinline__ u32x4 pack8(f32x4 a, f32x4 b) { u32x4 w; w.x = pk2(a[0], a[1]); w.y = pk2(a[2], a[3]); w.z = pk2(b[0], b[1]); w.w = pk2(b[2], b[3]); return w; }
;     __device__ __forceinline__ void operator()(const Acc& acc, const pg8::Unit& u, int wid) const {
;         const int lane_ = lane_id_asm(), wr = wid >> 2, wc = wid & 3, fr = lane_ & 15, fq = lane_ >> 4;
;         const int row0 = u.pm * 256 + wr * 64 + fr, col0 = u.pn * 256 + wc * 32 + 8 * fq;
;         float r2[8];
; #pragma unroll
;         for (int i = 0; i < 8; ++i) r2[i] = ssq2 ? ssq2[row0 + (i >> 2) * 128 + (i & 3) * 16] : 0.f;
;         u32x4 bv[2][4][2];
; #pragma unroll
;         for (int ai = 0; ai < 2; ++ai)
; #pragma unroll
;             for (int m = 0; m < 4; ++m)
; #pragma unroll
;                 for (int bj = 0; bj < 2; ++bj) bv[ai][m][bj] = *(const u32x4*)(base + (size_t)(row0 + ai * 128 + m * 16) * 1024 + col0 + bj * 128);
; #pragma unroll
;         for (int ai = 0; ai < 2; ++ai) {
; #pragma unroll
;             for (int m = 0; m < 4; ++m) {
;                 const int row = row0 + ai * 128 + m * 16; float sq = 0.f;
;                 const float rr = ssq2 ? __builtin_amdgcn_rcpf(r2[ai * 4 + m] * (1.f / 1024.f) + EPS) : 1.f;
; #pragma unroll
;                 for (int bj = 0; bj < 2; ++bj) {
;                     const u32x4 b4 = bv[ai][m][bj];
;                     const f32x4 o0 = (f32x4){bflo(b4.x), bfhi(b4.x), bflo(b4.y), bfhi(b4.y)} + acc[ai][bj][m][0] * rr;
;                     const f32x4 o1 = (f32x4){bflo(b4.z), bfhi(b4.z), bflo(b4.w), bfhi(b4.w)} + acc[ai][bj][m][1] * rr;
;                     *(u32x4*)(hb + (size_t)row * 1024 + col0 + bj * 128) = pack8(o0, o1);
;                     sq += (o0[0] * o0[0] + o0[1] * o0[1]) + (o0[2] * o0[2] + o0[3] * o0[3]) + (o1[0] * o1[0] + o1[1] * o1[1]) + (o1[2] * o1[2] + o1[3] * o1[3]);
;                 }
;                 if (ssq_out) { sq += __shfl_xor(sq, 16); sq += __shfl_xor(sq, 32); if (fq == 0) atomicAdd(ssq_out + row, sq); }
.LBB0_404:
	v_mbcnt_lo_u32_b32 v250, -1, 0
	v_mbcnt_hi_u32_b32 v250, -1, v250
	s_lshl_b32 s0, s0, 8
	v_ashrrev_i32_e32 v120, 1, v250
	s_lshl_b32 s1, s24, 8
	v_and_b32_e32 v120, -8, v120
	s_or_b32 s0, s0, s69
	s_add_i32 s1, s1, s66
	v_add_u32_e32 v208, s0, v120
	v_and_or_b32 v238, v250, 15, s1
	v_ashrrev_i32_e32 v209, 31, v208
	v_lshlrev_b64 v[240:241], 1, v[208:209]
	v_ashrrev_i32_e32 v239, 31, v238
	v_lshl_add_u64 v[120:121], s[42:43], 0, v[240:241]
	v_lshlrev_b64 v[242:243], 11, v[238:239]
	v_lshl_add_u64 v[122:123], v[120:121], 0, v[242:243]
	global_load_dwordx4 v[188:191], v[122:123], off
	global_load_dwordx4 v[184:187], v[122:123], off offset:256
	v_or_b32_e32 v234, 16, v238
	v_ashrrev_i32_e32 v235, 31, v234
	v_or_b32_e32 v230, 32, v238
	v_lshlrev_b64 v[236:237], 11, v[234:235]
	v_ashrrev_i32_e32 v231, 31, v230
	v_or_b32_e32 v226, 48, v238
	v_add_u32_e32 v220, 0x80, v238
	v_lshl_add_u64 v[122:123], v[120:121], 0, v[236:237]
	v_lshlrev_b64 v[232:233], 11, v[230:231]
	v_ashrrev_i32_e32 v227, 31, v226
	v_ashrrev_i32_e32 v221, 31, v220
	global_load_dwordx4 v[180:183], v[122:123], off
	global_load_dwordx4 v[176:179], v[122:123], off offset:256
	v_lshl_add_u64 v[122:123], v[120:121], 0, v[232:233]
	v_lshlrev_b64 v[228:229], 11, v[226:227]
	v_add_u32_e32 v218, 0x90, v238
	global_load_dwordx4 v[172:175], v[122:123], off
	global_load_dwordx4 v[168:171], v[122:123], off offset:256
	v_lshl_add_u64 v[122:123], v[120:121], 0, v[228:229]
	v_lshlrev_b64 v[224:225], 11, v[220:221]
	v_ashrrev_i32_e32 v219, 31, v218
	v_add_u32_e32 v214, 0xa0, v238
	v_add_u32_e32 v210, 0xb0, v238
	global_load_dwordx4 v[164:167], v[122:123], off
	global_load_dwordx4 v[160:163], v[122:123], off offset:256
	v_lshl_add_u64 v[122:123], v[120:121], 0, v[224:225]
	v_lshlrev_b64 v[222:223], 11, v[218:219]
	v_ashrrev_i32_e32 v215, 31, v214
	v_ashrrev_i32_e32 v211, 31, v210
	global_load_dwordx4 v[156:159], v[122:123], off
	global_load_dwordx4 v[152:155], v[122:123], off offset:256
	v_lshl_add_u64 v[122:123], v[120:121], 0, v[222:223]
	v_lshlrev_b64 v[216:217], 11, v[214:215]
	v_lshlrev_b64 v[212:213], 11, v[210:211]
	global_load_dwordx4 v[148:151], v[122:123], off
	global_load_dwordx4 v[144:147], v[122:123], off offset:256
	v_lshl_add_u64 v[122:123], v[120:121], 0, v[216:217]
	v_lshl_add_u64 v[120:121], v[120:121], 0, v[212:213]
	global_load_dwordx4 v[136:139], v[122:123], off
	global_load_dwordx4 v[124:127], v[122:123], off offset:256
	global_load_dwordx4 v[132:135], v[120:121], off
	s_nop 0
	global_load_dwordx4 v[120:123], v[120:121], off offset:256
	v_cmp_gt_u32_e32 vcc, 16, v250
	v_lshl_add_u64 v[242:243], s[42:43], 0, v[242:243]
	v_lshl_add_u64 v[240:241], v[242:243], 0, v[240:241]
	s_waitcnt vmcnt(0) lgkmcnt(0)
	v_lshlrev_b32_e32 v250, 16, v188
	v_and_b32_e32 v251, 0xffff0000, v188
	v_lshlrev_b32_e32 v188, 16, v189
	v_and_b32_e32 v189, 0xffff0000, v189
	v_pk_add_f32 v[142:143], v[142:143], v[188:189]
	v_lshlrev_b32_e32 v188, 16, v190
	v_and_b32_e32 v189, 0xffff0000, v190
	v_lshlrev_b32_e32 v190, 16, v191
	v_and_b32_e32 v191, 0xffff0000, v191
	v_pk_add_f32 v[140:141], v[140:141], v[250:251]
	v_pk_add_f32 v[190:191], v[130:131], v[190:191]
	v_pk_add_f32 v[188:189], v[128:129], v[188:189]
	v_cvt_pk_bf16_f32 v128, v140, v141
	v_cvt_pk_bf16_f32 v129, v142, v143
	v_cvt_pk_bf16_f32 v130, v188, v189
	v_cvt_pk_bf16_f32 v131, v190, v191
	global_store_dwordx4 v[240:241], v[128:131], off
	s_nop 1
	v_lshlrev_b32_e32 v128, 16, v184
	v_and_b32_e32 v129, 0xffff0000, v184
	v_lshlrev_b32_e32 v130, 16, v185
	v_and_b32_e32 v131, 0xffff0000, v185
	v_pk_add_f32 v[118:119], v[118:119], v[130:131]
	v_pk_add_f32 v[116:117], v[116:117], v[128:129]
	v_lshlrev_b32_e32 v128, 16, v186
	v_and_b32_e32 v129, 0xffff0000, v186
	v_lshlrev_b32_e32 v130, 16, v187
	v_and_b32_e32 v131, 0xffff0000, v187
	v_pk_add_f32 v[130:131], v[114:115], v[130:131]
	v_pk_add_f32 v[128:129], v[112:113], v[128:129]
	v_cvt_pk_bf16_f32 v112, v116, v117
	v_cvt_pk_bf16_f32 v113, v118, v119
	v_cvt_pk_bf16_f32 v114, v128, v129
	v_cvt_pk_bf16_f32 v115, v130, v131
	global_store_dwordx4 v[240:241], v[112:115], off offset:256
	s_nop 1
	v_mul_f32_e32 v114, v141, v141
	v_mul_f32_e32 v115, v143, v143
	v_fmac_f32_e32 v114, v140, v140
	v_fmac_f32_e32 v115, v142, v142
	v_mul_f32_e32 v113, v189, v189
	v_add_f32_e32 v114, v114, v115
	v_mul_f32_e32 v115, v117, v117
	v_mul_f32_e32 v112, v191, v191
	v_fmac_f32_e32 v113, v188, v188
	v_fmac_f32_e32 v115, v116, v116
	v_mul_f32_e32 v116, v119, v119
	v_fmac_f32_e32 v112, v190, v190
	v_add_f32_e32 v113, v113, v114
	v_mul_f32_e32 v114, v129, v129
	v_fmac_f32_e32 v116, v118, v118
	v_add_f32_e32 v112, v112, v113
	v_mul_f32_e32 v113, v131, v131
	v_fmac_f32_e32 v114, v128, v128
	v_add_f32_e32 v115, v115, v116
	v_fmac_f32_e32 v113, v130, v130
	v_add_f32_e32 v114, v114, v115
	v_add_f32_e32 v113, v113, v114
	v_and_b32_e32 v114, 64, v249
	v_add_f32_e32 v113, v112, v113
	v_xor_b32_e32 v112, 16, v249
	v_add_u32_e32 v115, 64, v114
	v_cmp_lt_i32_e64 s[0:1], v112, v115
	s_nop 1
	v_cndmask_b32_e64 v112, v249, v112, s[0:1]
	v_lshlrev_b32_e32 v112, 2, v112
	ds_bpermute_b32 v114, v112, v113
	s_waitcnt lgkmcnt(0)
	v_add_f32_e32 v114, v113, v114
	v_xor_b32_e32 v113, 32, v249
	v_cmp_lt_i32_e64 s[0:1], v113, v115
	s_nop 1
	v_cndmask_b32_e64 v113, v249, v113, s[0:1]
	v_lshlrev_b32_e32 v113, 2, v113
	ds_bpermute_b32 v115, v113, v114
	s_and_saveexec_b64 s[0:1], vcc
	s_cbranch_execz .LBB0_406
	v_lshl_add_u64 v[116:117], v[238:239], 2, s[48:49]
	s_waitcnt lgkmcnt(0)
	v_add_f32_e32 v114, v114, v115
	global_atomic_add_f32 v[116:117], v114, off
; __device__ __forceinline__ u32x4 pack8(f32x4 a, f32x4 b) { u32x4 w; w.x = pk2(a[0], a[1]); w.y = pk2(a[2], a[3]); w.z = pk2(b[0], b[1]); w.w = pk2(b[2], b[3]); return w; }
;     __device__ __forceinline__ void operator()(const Acc& acc, const pg8::Unit& u, int wid) const {
;     ...
;         for (int ai = 0; ai < 2; ++ai) {
; #pragma unroll
;             for (int m = 0; m < 4; ++m) {
;                 const int row = row0 + ai * 128 + m * 16; float sq = 0.f;
;                 const float rr = ssq2 ? __builtin_amdgcn_rcpf(r2[ai * 4 + m] * (1.f / 1024.f) + EPS) : 1.f;
; #pragma unroll
;                 for (int bj = 0; bj < 2; ++bj) {
;                     const u32x4 b4 = bv[ai][m][bj];
;                     const f32x4 o0 = (f32x4){bflo(b4.x), bfhi(b4.x), bflo(b4.y), bfhi(b4.y)} + acc[ai][bj][m][0] * rr;
;                     const f32x4 o1 = (f32x4){bflo(b4.z), bfhi(b4.z), bflo(b4.w), bfhi(b4.w)} + acc[ai][bj][m][1] * rr;
;                     *(u32x4*)(hb + (size_t)row * 1024 + col0 + bj * 128) = pack8(o0, o1);
;                     sq += (o0[0] * o0[0] + o0[1] * o0[1]) + (o0[2] * o0[2] + o0[3] * o0[3]) + (o1[0] * o1[0] + o1[1] * o1[1]) + (o1[2] * o1[2] + o1[3] * o1[3]);
;                 }
;                 if (ssq_out) { sq += __shfl_xor(sq, 16); sq += __shfl_xor(sq, 32); if (fq == 0) atomicAdd(ssq_out + row, sq); }
.LBB0_406:
	s_or_b64 exec, exec, s[0:1]
	v_lshlrev_b32_e32 v114, 16, v180
	s_waitcnt lgkmcnt(0)
	v_and_b32_e32 v115, 0xffff0000, v180
	v_lshlrev_b32_e32 v116, 16, v181
	v_and_b32_e32 v117, 0xffff0000, v181
	v_lshlrev_b32_e32 v128, 16, v177
	v_and_b32_e32 v129, 0xffff0000, v177
	v_pk_add_f32 v[110:111], v[110:111], v[116:117]
	v_pk_add_f32 v[108:109], v[108:109], v[114:115]
	v_lshlrev_b32_e32 v114, 16, v182
	v_and_b32_e32 v115, 0xffff0000, v182
	v_lshlrev_b32_e32 v118, 16, v176
	v_and_b32_e32 v119, 0xffff0000, v176
	v_pk_add_f32 v[102:103], v[102:103], v[128:129]
	v_lshlrev_b32_e32 v128, 16, v179
	v_and_b32_e32 v129, 0xffff0000, v179
	v_lshlrev_b32_e32 v116, 16, v183
	v_and_b32_e32 v117, 0xffff0000, v183
	v_pk_add_f32 v[114:115], v[104:105], v[114:115]
	v_pk_add_f32 v[100:101], v[100:101], v[118:119]
	v_lshlrev_b32_e32 v118, 16, v178
	v_and_b32_e32 v119, 0xffff0000, v178
	v_pk_add_f32 v[128:129], v[98:99], v[128:129]
	v_mul_f32_e32 v98, v109, v109
	v_mul_f32_e32 v99, v111, v111
	v_pk_add_f32 v[116:117], v[106:107], v[116:117]
	v_pk_add_f32 v[118:119], v[96:97], v[118:119]
	v_mul_f32_e32 v97, v115, v115
	v_fmac_f32_e32 v98, v108, v108
	v_fmac_f32_e32 v99, v110, v110
	v_cvt_pk_bf16_f32 v104, v108, v109
	v_mul_f32_e32 v96, v117, v117
	v_fmac_f32_e32 v97, v114, v114
	v_add_f32_e32 v98, v98, v99
	v_mul_f32_e32 v99, v101, v101
	v_mul_f32_e32 v108, v103, v103
	v_fmac_f32_e32 v96, v116, v116
	v_add_f32_e32 v97, v97, v98
	v_mul_f32_e32 v98, v119, v119
	v_fmac_f32_e32 v99, v100, v100
	v_fmac_f32_e32 v108, v102, v102
	v_add_f32_e32 v96, v96, v97
	v_mul_f32_e32 v97, v129, v129
	v_fmac_f32_e32 v98, v118, v118
	v_add_f32_e32 v99, v99, v108
	v_fmac_f32_e32 v97, v128, v128
	v_add_f32_e32 v98, v98, v99
	v_add_f32_e32 v97, v97, v98
	v_add_f32_e32 v99, v96, v97
	v_cvt_pk_bf16_f32 v105, v110, v111
	ds_bpermute_b32 v110, v112, v99
	v_lshl_add_u64 v[96:97], s[42:43], 0, v[236:237]
	v_lshl_add_u64 v[108:109], v[208:209], 1, v[96:97]
	v_cvt_pk_bf16_f32 v106, v114, v115
	v_cvt_pk_bf16_f32 v107, v116, v117
	s_waitcnt lgkmcnt(0)
	v_add_f32_e32 v96, v99, v110
	ds_bpermute_b32 v97, v113, v96
	v_cvt_pk_bf16_f32 v98, v100, v101
	v_cvt_pk_bf16_f32 v99, v102, v103
	v_cvt_pk_bf16_f32 v100, v118, v119
	v_cvt_pk_bf16_f32 v101, v128, v129
	global_store_dwordx4 v[108:109], v[104:107], off
	global_store_dwordx4 v[108:109], v[98:101], off offset:256
	s_and_saveexec_b64 s[0:1], vcc
	s_cbranch_execz .LBB0_408
	v_lshl_add_u64 v[98:99], v[234:235], 2, s[48:49]
	s_waitcnt lgkmcnt(0)
	v_add_f32_e32 v96, v96, v97
	global_atomic_add_f32 v[98:99], v96, off
.LBB0_408:
	s_or_b64 exec, exec, s[0:1]
	v_lshlrev_b32_e32 v96, 16, v172
	s_waitcnt lgkmcnt(0)
	v_and_b32_e32 v97, 0xffff0000, v172
	v_lshlrev_b32_e32 v98, 16, v173
	v_and_b32_e32 v99, 0xffff0000, v173
	v_lshlrev_b32_e32 v102, 16, v169
	v_and_b32_e32 v103, 0xffff0000, v169
	v_pk_add_f32 v[94:95], v[94:95], v[98:99]
	v_pk_add_f32 v[92:93], v[92:93], v[96:97]
	v_lshlrev_b32_e32 v96, 16, v174
	v_and_b32_e32 v97, 0xffff0000, v174
	v_lshlrev_b32_e32 v100, 16, v168
	v_and_b32_e32 v101, 0xffff0000, v168
	v_pk_add_f32 v[86:87], v[86:87], v[102:103]
	v_lshlrev_b32_e32 v102, 16, v171
	v_and_b32_e32 v103, 0xffff0000, v171
	v_lshlrev_b32_e32 v98, 16, v175
	v_and_b32_e32 v99, 0xffff0000, v175
	v_pk_add_f32 v[96:97], v[88:89], v[96:97]
	v_pk_add_f32 v[84:85], v[84:85], v[100:101]
	v_lshlrev_b32_e32 v100, 16, v170
	v_and_b32_e32 v101, 0xffff0000, v170
	v_pk_add_f32 v[102:103], v[82:83], v[102:103]
	v_mul_f32_e32 v82, v93, v93
	v_mul_f32_e32 v83, v95, v95
	v_pk_add_f32 v[98:99], v[90:91], v[98:99]
	v_pk_add_f32 v[100:101], v[80:81], v[100:101]
	v_mul_f32_e32 v81, v97, v97
	v_fmac_f32_e32 v82, v92, v92
	v_fmac_f32_e32 v83, v94, v94
	v_cvt_pk_bf16_f32 v88, v92, v93
	v_mul_f32_e32 v80, v99, v99
	v_fmac_f32_e32 v81, v96, v96
	v_add_f32_e32 v82, v82, v83
	v_mul_f32_e32 v83, v85, v85
	v_mul_f32_e32 v92, v87, v87
	v_fmac_f32_e32 v80, v98, v98
	v_add_f32_e32 v81, v81, v82
	v_mul_f32_e32 v82, v101, v101
	v_fmac_f32_e32 v83, v84, v84
	v_fmac_f32_e32 v92, v86, v86
	v_add_f32_e32 v80, v80, v81
	v_mul_f32_e32 v81, v103, v103
	v_fmac_f32_e32 v82, v100, v100
	v_add_f32_e32 v83, v83, v92
	v_fmac_f32_e32 v81, v102, v102
	v_add_f32_e32 v82, v82, v83
	v_add_f32_e32 v81, v81, v82
	v_add_f32_e32 v83, v80, v81
	v_cvt_pk_bf16_f32 v89, v94, v95
	ds_bpermute_b32 v94, v112, v83
	v_lshl_add_u64 v[80:81], s[42:43], 0, v[232:233]
	v_lshl_add_u64 v[92:93], v[208:209], 1, v[80:81]
	v_cvt_pk_bf16_f32 v90, v96, v97
	v_cvt_pk_bf16_f32 v91, v98, v99
	s_waitcnt lgkmcnt(0)
	v_add_f32_e32 v80, v83, v94
	ds_bpermute_b32 v81, v113, v80
	v_cvt_pk_bf16_f32 v82, v84, v85
	v_cvt_pk_bf16_f32 v83, v86, v87
	v_cvt_pk_bf16_f32 v84, v100, v101
	v_cvt_pk_bf16_f32 v85, v102, v103
	global_store_dwordx4 v[92:93], v[88:91], off
	global_store_dwordx4 v[92:93], v[82:85], off offset:256
	s_and_saveexec_b64 s[0:1], vcc
	s_cbranch_execz .LBB0_410
	v_lshl_add_u64 v[82:83], v[230:231], 2, s[48:49]
	s_waitcnt lgkmcnt(0)
	v_add_f32_e32 v80, v80, v81
	global_atomic_add_f32 v[82:83], v80, off
; __device__ __forceinline__ u32x4 pack8(f32x4 a, f32x4 b) { u32x4 w; w.x = pk2(a[0], a[1]); w.y = pk2(a[2], a[3]); w.z = pk2(b[0], b[1]); w.w = pk2(b[2], b[3]); return w; }
;     __device__ __forceinline__ void operator()(const Acc& acc, const pg8::Unit& u, int wid) const {
;     ...
;         for (int ai = 0; ai < 2; ++ai) {
; #pragma unroll
;             for (int m = 0; m < 4; ++m) {
;                 const int row = row0 + ai * 128 + m * 16; float sq = 0.f;
;                 const float rr = ssq2 ? __builtin_amdgcn_rcpf(r2[ai * 4 + m] * (1.f / 1024.f) + EPS) : 1.f;
; #pragma unroll
;                 for (int bj = 0; bj < 2; ++bj) {
;                     const u32x4 b4 = bv[ai][m][bj];
;                     const f32x4 o0 = (f32x4){bflo(b4.x), bfhi(b4.x), bflo(b4.y), bfhi(b4.y)} + acc[ai][bj][m][0] * rr;
;                     const f32x4 o1 = (f32x4){bflo(b4.z), bfhi(b4.z), bflo(b4.w), bfhi(b4.w)} + acc[ai][bj][m][1] * rr;
;                     *(u32x4*)(hb + (size_t)row * 1024 + col0 + bj * 128) = pack8(o0, o1);
;                     sq += (o0[0] * o0[0] + o0[1] * o0[1]) + (o0[2] * o0[2] + o0[3] * o0[3]) + (o1[0] * o1[0] + o1[1] * o1[1]) + (o1[2] * o1[2] + o1[3] * o1[3]);
;                 }
;                 if (ssq_out) { sq += __shfl_xor(sq, 16); sq += __shfl_xor(sq, 32); if (fq == 0) atomicAdd(ssq_out + row, sq); }
.LBB0_410:
	s_or_b64 exec, exec, s[0:1]
	v_lshlrev_b32_e32 v80, 16, v164
	s_waitcnt lgkmcnt(0)
	v_and_b32_e32 v81, 0xffff0000, v164
	v_lshlrev_b32_e32 v82, 16, v165
	v_and_b32_e32 v83, 0xffff0000, v165
	v_lshlrev_b32_e32 v86, 16, v161
	v_and_b32_e32 v87, 0xffff0000, v161
	v_pk_add_f32 v[78:79], v[78:79], v[82:83]
	v_pk_add_f32 v[76:77], v[76:77], v[80:81]
	v_lshlrev_b32_e32 v80, 16, v166
	v_and_b32_e32 v81, 0xffff0000, v166
	v_lshlrev_b32_e32 v84, 16, v160
	v_and_b32_e32 v85, 0xffff0000, v160
	v_pk_add_f32 v[70:71], v[70:71], v[86:87]
	v_lshlrev_b32_e32 v86, 16, v163
	v_and_b32_e32 v87, 0xffff0000, v163
	v_lshlrev_b32_e32 v82, 16, v167
	v_and_b32_e32 v83, 0xffff0000, v167
	v_pk_add_f32 v[80:81], v[72:73], v[80:81]
	v_pk_add_f32 v[68:69], v[68:69], v[84:85]
	v_lshlrev_b32_e32 v84, 16, v162
	v_and_b32_e32 v85, 0xffff0000, v162
	v_pk_add_f32 v[86:87], v[66:67], v[86:87]
	v_mul_f32_e32 v66, v77, v77
	v_mul_f32_e32 v67, v79, v79
	v_pk_add_f32 v[82:83], v[74:75], v[82:83]
	v_pk_add_f32 v[84:85], v[64:65], v[84:85]
	v_mul_f32_e32 v65, v81, v81
	v_fmac_f32_e32 v66, v76, v76
	v_fmac_f32_e32 v67, v78, v78
	v_cvt_pk_bf16_f32 v72, v76, v77
	v_mul_f32_e32 v64, v83, v83
	v_fmac_f32_e32 v65, v80, v80
	v_add_f32_e32 v66, v66, v67
	v_mul_f32_e32 v67, v69, v69
	v_mul_f32_e32 v76, v71, v71
	v_fmac_f32_e32 v64, v82, v82
	v_add_f32_e32 v65, v65, v66
	v_mul_f32_e32 v66, v85, v85
	v_fmac_f32_e32 v67, v68, v68
	v_fmac_f32_e32 v76, v70, v70
	v_add_f32_e32 v64, v64, v65
	v_mul_f32_e32 v65, v87, v87
	v_fmac_f32_e32 v66, v84, v84
	v_add_f32_e32 v67, v67, v76
	v_fmac_f32_e32 v65, v86, v86
	v_add_f32_e32 v66, v66, v67
	v_add_f32_e32 v65, v65, v66
	v_add_f32_e32 v67, v64, v65
	v_cvt_pk_bf16_f32 v73, v78, v79
	ds_bpermute_b32 v78, v112, v67
	v_lshl_add_u64 v[64:65], s[42:43], 0, v[228:229]
	v_lshl_add_u64 v[76:77], v[208:209], 1, v[64:65]
	v_cvt_pk_bf16_f32 v74, v80, v81
	v_cvt_pk_bf16_f32 v75, v82, v83
	s_waitcnt lgkmcnt(0)
	v_add_f32_e32 v64, v67, v78
	ds_bpermute_b32 v65, v113, v64
	v_cvt_pk_bf16_f32 v66, v68, v69
	v_cvt_pk_bf16_f32 v67, v70, v71
	v_cvt_pk_bf16_f32 v68, v84, v85
	v_cvt_pk_bf16_f32 v69, v86, v87
	global_store_dwordx4 v[76:77], v[72:75], off
	global_store_dwordx4 v[76:77], v[66:69], off offset:256
	s_and_saveexec_b64 s[0:1], vcc
	s_cbranch_execz .LBB0_412
	v_lshl_add_u64 v[66:67], v[226:227], 2, s[48:49]
	s_waitcnt lgkmcnt(0)
	v_add_f32_e32 v64, v64, v65
	global_atomic_add_f32 v[66:67], v64, off
.LBB0_412:
	s_or_b64 exec, exec, s[0:1]
	v_lshlrev_b32_e32 v64, 16, v156
	s_waitcnt lgkmcnt(0)
	v_and_b32_e32 v65, 0xffff0000, v156
	v_lshlrev_b32_e32 v66, 16, v157
	v_and_b32_e32 v67, 0xffff0000, v157
	v_lshlrev_b32_e32 v70, 16, v153
	v_and_b32_e32 v71, 0xffff0000, v153
	v_pk_add_f32 v[62:63], v[62:63], v[66:67]
	v_pk_add_f32 v[60:61], v[60:61], v[64:65]
	v_lshlrev_b32_e32 v64, 16, v158
	v_and_b32_e32 v65, 0xffff0000, v158
	v_lshlrev_b32_e32 v68, 16, v152
	v_and_b32_e32 v69, 0xffff0000, v152
	v_pk_add_f32 v[54:55], v[54:55], v[70:71]
	v_lshlrev_b32_e32 v70, 16, v155
	v_and_b32_e32 v71, 0xffff0000, v155
	v_lshlrev_b32_e32 v66, 16, v159
	v_and_b32_e32 v67, 0xffff0000, v159
	v_pk_add_f32 v[64:65], v[56:57], v[64:65]
	v_pk_add_f32 v[52:53], v[52:53], v[68:69]
	v_lshlrev_b32_e32 v68, 16, v154
	v_and_b32_e32 v69, 0xffff0000, v154
	v_pk_add_f32 v[70:71], v[50:51], v[70:71]
	v_mul_f32_e32 v50, v61, v61
	v_mul_f32_e32 v51, v63, v63
	v_pk_add_f32 v[66:67], v[58:59], v[66:67]
	v_pk_add_f32 v[68:69], v[48:49], v[68:69]
	v_mul_f32_e32 v49, v65, v65
	v_fmac_f32_e32 v50, v60, v60
	v_fmac_f32_e32 v51, v62, v62
	v_cvt_pk_bf16_f32 v56, v60, v61
	v_mul_f32_e32 v48, v67, v67
	v_fmac_f32_e32 v49, v64, v64
	v_add_f32_e32 v50, v50, v51
	v_mul_f32_e32 v51, v53, v53
	v_mul_f32_e32 v60, v55, v55
	v_fmac_f32_e32 v48, v66, v66
	v_add_f32_e32 v49, v49, v50
	v_mul_f32_e32 v50, v69, v69
	v_fmac_f32_e32 v51, v52, v52
	v_fmac_f32_e32 v60, v54, v54
	v_add_f32_e32 v48, v48, v49
	v_mul_f32_e32 v49, v71, v71
	v_fmac_f32_e32 v50, v68, v68
	v_add_f32_e32 v51, v51, v60
	v_fmac_f32_e32 v49, v70, v70
	v_add_f32_e32 v50, v50, v51
	v_add_f32_e32 v49, v49, v50
	v_add_f32_e32 v51, v48, v49
	v_cvt_pk_bf16_f32 v57, v62, v63
	ds_bpermute_b32 v62, v112, v51
	v_lshl_add_u64 v[48:49], s[42:43], 0, v[224:225]
	v_lshl_add_u64 v[60:61], v[208:209], 1, v[48:49]
	v_cvt_pk_bf16_f32 v58, v64, v65
	v_cvt_pk_bf16_f32 v59, v66, v67
	s_waitcnt lgkmcnt(0)
	v_add_f32_e32 v48, v51, v62
	ds_bpermute_b32 v49, v113, v48
	v_cvt_pk_bf16_f32 v50, v52, v53
	v_cvt_pk_bf16_f32 v51, v54, v55
	v_cvt_pk_bf16_f32 v52, v68, v69
	v_cvt_pk_bf16_f32 v53, v70, v71
	global_store_dwordx4 v[60:61], v[56:59], off
	global_store_dwordx4 v[60:61], v[50:53], off offset:256
	s_and_saveexec_b64 s[0:1], vcc
	s_cbranch_execz .LBB0_414
	v_lshl_add_u64 v[50:51], v[220:221], 2, s[48:49]
	s_waitcnt lgkmcnt(0)
	v_add_f32_e32 v48, v48, v49
	global_atomic_add_f32 v[50:51], v48, off
; __device__ __forceinline__ u32x4 pack8(f32x4 a, f32x4 b) { u32x4 w; w.x = pk2(a[0], a[1]); w.y = pk2(a[2], a[3]); w.z = pk2(b[0], b[1]); w.w = pk2(b[2], b[3]); return w; }
;     __device__ __forceinline__ void operator()(const Acc& acc, const pg8::Unit& u, int wid) const {
;     ...
;         for (int ai = 0; ai < 2; ++ai) {
; #pragma unroll
;             for (int m = 0; m < 4; ++m) {
;                 const int row = row0 + ai * 128 + m * 16; float sq = 0.f;
;                 const float rr = ssq2 ? __builtin_amdgcn_rcpf(r2[ai * 4 + m] * (1.f / 1024.f) + EPS) : 1.f;
; #pragma unroll
;                 for (int bj = 0; bj < 2; ++bj) {
;                     const u32x4 b4 = bv[ai][m][bj];
;                     const f32x4 o0 = (f32x4){bflo(b4.x), bfhi(b4.x), bflo(b4.y), bfhi(b4.y)} + acc[ai][bj][m][0] * rr;
;                     const f32x4 o1 = (f32x4){bflo(b4.z), bfhi(b4.z), bflo(b4.w), bfhi(b4.w)} + acc[ai][bj][m][1] * rr;
;                     *(u32x4*)(hb + (size_t)row * 1024 + col0 + bj * 128) = pack8(o0, o1);
;                     sq += (o0[0] * o0[0] + o0[1] * o0[1]) + (o0[2] * o0[2] + o0[3] * o0[3]) + (o1[0] * o1[0] + o1[1] * o1[1]) + (o1[2] * o1[2] + o1[3] * o1[3]);
;                 }
;                 if (ssq_out) { sq += __shfl_xor(sq, 16); sq += __shfl_xor(sq, 32); if (fq == 0) atomicAdd(ssq_out + row, sq); }
.LBB0_414:
	s_or_b64 exec, exec, s[0:1]
	v_lshlrev_b32_e32 v48, 16, v148
	s_waitcnt lgkmcnt(0)
	v_and_b32_e32 v49, 0xffff0000, v148
	v_lshlrev_b32_e32 v50, 16, v149
	v_and_b32_e32 v51, 0xffff0000, v149
	v_lshlrev_b32_e32 v54, 16, v145
	v_and_b32_e32 v55, 0xffff0000, v145
	v_pk_add_f32 v[46:47], v[46:47], v[50:51]
	v_pk_add_f32 v[44:45], v[44:45], v[48:49]
	v_lshlrev_b32_e32 v48, 16, v150
	v_and_b32_e32 v49, 0xffff0000, v150
	v_lshlrev_b32_e32 v52, 16, v144
	v_and_b32_e32 v53, 0xffff0000, v144
	v_pk_add_f32 v[38:39], v[38:39], v[54:55]
	v_lshlrev_b32_e32 v54, 16, v147
	v_and_b32_e32 v55, 0xffff0000, v147
	v_lshlrev_b32_e32 v50, 16, v151
	v_and_b32_e32 v51, 0xffff0000, v151
	v_pk_add_f32 v[48:49], v[40:41], v[48:49]
	v_pk_add_f32 v[36:37], v[36:37], v[52:53]
	v_lshlrev_b32_e32 v52, 16, v146
	v_and_b32_e32 v53, 0xffff0000, v146
	v_pk_add_f32 v[54:55], v[34:35], v[54:55]
	v_mul_f32_e32 v34, v45, v45
	v_mul_f32_e32 v35, v47, v47
	v_pk_add_f32 v[50:51], v[42:43], v[50:51]
	v_pk_add_f32 v[52:53], v[32:33], v[52:53]
	v_mul_f32_e32 v33, v49, v49
	v_fmac_f32_e32 v34, v44, v44
	v_fmac_f32_e32 v35, v46, v46
	v_cvt_pk_bf16_f32 v40, v44, v45
	v_mul_f32_e32 v32, v51, v51
	v_fmac_f32_e32 v33, v48, v48
	v_add_f32_e32 v34, v34, v35
	v_mul_f32_e32 v35, v37, v37
	v_mul_f32_e32 v44, v39, v39
	v_fmac_f32_e32 v32, v50, v50
	v_add_f32_e32 v33, v33, v34
	v_mul_f32_e32 v34, v53, v53
	v_fmac_f32_e32 v35, v36, v36
	v_fmac_f32_e32 v44, v38, v38
	v_add_f32_e32 v32, v32, v33
	v_mul_f32_e32 v33, v55, v55
	v_fmac_f32_e32 v34, v52, v52
	v_add_f32_e32 v35, v35, v44
	v_fmac_f32_e32 v33, v54, v54
	v_add_f32_e32 v34, v34, v35
	v_add_f32_e32 v33, v33, v34
	v_add_f32_e32 v35, v32, v33
	v_cvt_pk_bf16_f32 v41, v46, v47
	ds_bpermute_b32 v46, v112, v35
	v_lshl_add_u64 v[32:33], s[42:43], 0, v[222:223]
	v_lshl_add_u64 v[44:45], v[208:209], 1, v[32:33]
	v_cvt_pk_bf16_f32 v42, v48, v49
	v_cvt_pk_bf16_f32 v43, v50, v51
	s_waitcnt lgkmcnt(0)
	v_add_f32_e32 v32, v35, v46
	ds_bpermute_b32 v33, v113, v32
	v_cvt_pk_bf16_f32 v34, v36, v37
	v_cvt_pk_bf16_f32 v35, v38, v39
	v_cvt_pk_bf16_f32 v36, v52, v53
	v_cvt_pk_bf16_f32 v37, v54, v55
	global_store_dwordx4 v[44:45], v[40:43], off
	global_store_dwordx4 v[44:45], v[34:37], off offset:256
	s_and_saveexec_b64 s[0:1], vcc
	s_cbranch_execz .LBB0_416
	v_lshl_add_u64 v[34:35], v[218:219], 2, s[48:49]
	s_waitcnt lgkmcnt(0)
	v_add_f32_e32 v32, v32, v33
	global_atomic_add_f32 v[34:35], v32, off
; __device__ __forceinline__ u32x4 pack8(f32x4 a, f32x4 b) { u32x4 w; w.x = pk2(a[0], a[1]); w.y = pk2(a[2], a[3]); w.z = pk2(b[0], b[1]); w.w = pk2(b[2], b[3]); return w; }
;     __device__ __forceinline__ void operator()(const Acc& acc, const pg8::Unit& u, int wid) const {
;     ...
;         for (int ai = 0; ai < 2; ++ai) {
; #pragma unroll
;             for (int m = 0; m < 4; ++m) {
;                 const int row = row0 + ai * 128 + m * 16; float sq = 0.f;
;                 const float rr = ssq2 ? __builtin_amdgcn_rcpf(r2[ai * 4 + m] * (1.f / 1024.f) + EPS) : 1.f;
; #pragma unroll
;                 for (int bj = 0; bj < 2; ++bj) {
;                     const u32x4 b4 = bv[ai][m][bj];
;                     const f32x4 o0 = (f32x4){bflo(b4.x), bfhi(b4.x), bflo(b4.y), bfhi(b4.y)} + acc[ai][bj][m][0] * rr;
;                     const f32x4 o1 = (f32x4){bflo(b4.z), bfhi(b4.z), bflo(b4.w), bfhi(b4.w)} + acc[ai][bj][m][1] * rr;
;                     *(u32x4*)(hb + (size_t)row * 1024 + col0 + bj * 128) = pack8(o0, o1);
;                     sq += (o0[0] * o0[0] + o0[1] * o0[1]) + (o0[2] * o0[2] + o0[3] * o0[3]) + (o1[0] * o1[0] + o1[1] * o1[1]) + (o1[2] * o1[2] + o1[3] * o1[3]);
;                 }
;                 if (ssq_out) { sq += __shfl_xor(sq, 16); sq += __shfl_xor(sq, 32); if (fq == 0) atomicAdd(ssq_out + row, sq); }
.LBB0_416:
	s_or_b64 exec, exec, s[0:1]
	v_lshlrev_b32_e32 v32, 16, v136
	s_waitcnt lgkmcnt(0)
	v_and_b32_e32 v33, 0xffff0000, v136
	v_lshlrev_b32_e32 v34, 16, v137
	v_and_b32_e32 v35, 0xffff0000, v137
	v_lshlrev_b32_e32 v38, 16, v125
	v_and_b32_e32 v39, 0xffff0000, v125
	v_pk_add_f32 v[30:31], v[30:31], v[34:35]
	v_pk_add_f32 v[28:29], v[28:29], v[32:33]
	v_lshlrev_b32_e32 v32, 16, v138
	v_and_b32_e32 v33, 0xffff0000, v138
	v_lshlrev_b32_e32 v36, 16, v124
	v_and_b32_e32 v37, 0xffff0000, v124
	v_pk_add_f32 v[22:23], v[22:23], v[38:39]
	v_lshlrev_b32_e32 v38, 16, v127
	v_and_b32_e32 v39, 0xffff0000, v127
	v_lshlrev_b32_e32 v34, 16, v139
	v_and_b32_e32 v35, 0xffff0000, v139
	v_pk_add_f32 v[32:33], v[24:25], v[32:33]
	v_pk_add_f32 v[20:21], v[20:21], v[36:37]
	v_lshlrev_b32_e32 v36, 16, v126
	v_and_b32_e32 v37, 0xffff0000, v126
	v_pk_add_f32 v[38:39], v[18:19], v[38:39]
	v_mul_f32_e32 v18, v29, v29
	v_mul_f32_e32 v19, v31, v31
	v_pk_add_f32 v[34:35], v[26:27], v[34:35]
	v_pk_add_f32 v[36:37], v[16:17], v[36:37]
	v_mul_f32_e32 v17, v33, v33
	v_fmac_f32_e32 v18, v28, v28
	v_fmac_f32_e32 v19, v30, v30
	v_cvt_pk_bf16_f32 v24, v28, v29
	v_mul_f32_e32 v16, v35, v35
	v_fmac_f32_e32 v17, v32, v32
	v_add_f32_e32 v18, v18, v19
	v_mul_f32_e32 v19, v21, v21
	v_mul_f32_e32 v28, v23, v23
	v_fmac_f32_e32 v16, v34, v34
	v_add_f32_e32 v17, v17, v18
	v_mul_f32_e32 v18, v37, v37
	v_fmac_f32_e32 v19, v20, v20
	v_fmac_f32_e32 v28, v22, v22
	v_add_f32_e32 v16, v16, v17
	v_mul_f32_e32 v17, v39, v39
	v_fmac_f32_e32 v18, v36, v36
	v_add_f32_e32 v19, v19, v28
	v_fmac_f32_e32 v17, v38, v38
	v_add_f32_e32 v18, v18, v19
	v_add_f32_e32 v17, v17, v18
	v_add_f32_e32 v19, v16, v17
	v_cvt_pk_bf16_f32 v25, v30, v31
	ds_bpermute_b32 v30, v112, v19
	v_lshl_add_u64 v[16:17], s[42:43], 0, v[216:217]
	v_lshl_add_u64 v[28:29], v[208:209], 1, v[16:17]
	v_cvt_pk_bf16_f32 v26, v32, v33
	v_cvt_pk_bf16_f32 v27, v34, v35
	s_waitcnt lgkmcnt(0)
	v_add_f32_e32 v16, v19, v30
	ds_bpermute_b32 v17, v113, v16
	v_cvt_pk_bf16_f32 v18, v20, v21
	v_cvt_pk_bf16_f32 v19, v22, v23
	v_cvt_pk_bf16_f32 v20, v36, v37
	v_cvt_pk_bf16_f32 v21, v38, v39
	global_store_dwordx4 v[28:29], v[24:27], off
	global_store_dwordx4 v[28:29], v[18:21], off offset:256
	s_and_saveexec_b64 s[0:1], vcc
	s_cbranch_execz .LBB0_418
	v_lshl_add_u64 v[18:19], v[214:215], 2, s[48:49]
	s_waitcnt lgkmcnt(0)
	v_add_f32_e32 v16, v16, v17
	global_atomic_add_f32 v[18:19], v16, off
.LBB0_418:
	s_or_b64 exec, exec, s[0:1]
	v_lshlrev_b32_e32 v16, 16, v132
	s_waitcnt lgkmcnt(0)
	v_and_b32_e32 v17, 0xffff0000, v132
	v_lshlrev_b32_e32 v18, 16, v133
	v_and_b32_e32 v19, 0xffff0000, v133
	v_lshlrev_b32_e32 v22, 16, v121
	v_and_b32_e32 v23, 0xffff0000, v121
	v_pk_add_f32 v[14:15], v[14:15], v[18:19]
	v_pk_add_f32 v[12:13], v[12:13], v[16:17]
	v_lshlrev_b32_e32 v16, 16, v134
	v_and_b32_e32 v17, 0xffff0000, v134
	v_lshlrev_b32_e32 v20, 16, v120
	v_and_b32_e32 v21, 0xffff0000, v120
	v_pk_add_f32 v[6:7], v[6:7], v[22:23]
	v_lshlrev_b32_e32 v22, 16, v123
	v_and_b32_e32 v23, 0xffff0000, v123
	v_lshlrev_b32_e32 v18, 16, v135
	v_and_b32_e32 v19, 0xffff0000, v135
	v_pk_add_f32 v[16:17], v[8:9], v[16:17]
	v_pk_add_f32 v[4:5], v[4:5], v[20:21]
	v_lshlrev_b32_e32 v20, 16, v122
	v_and_b32_e32 v21, 0xffff0000, v122
	v_pk_add_f32 v[22:23], v[2:3], v[22:23]
	v_mul_f32_e32 v2, v13, v13
	v_mul_f32_e32 v3, v15, v15
	v_pk_add_f32 v[18:19], v[10:11], v[18:19]
	v_pk_add_f32 v[20:21], v[0:1], v[20:21]
	v_mul_f32_e32 v1, v17, v17
	v_fmac_f32_e32 v2, v12, v12
	v_fmac_f32_e32 v3, v14, v14
	v_cvt_pk_bf16_f32 v8, v12, v13
	v_mul_f32_e32 v0, v19, v19
	v_fmac_f32_e32 v1, v16, v16
	v_add_f32_e32 v2, v2, v3
	v_mul_f32_e32 v3, v5, v5
	v_mul_f32_e32 v12, v7, v7
	v_fmac_f32_e32 v0, v18, v18
	v_add_f32_e32 v1, v1, v2
	v_mul_f32_e32 v2, v21, v21
	v_fmac_f32_e32 v3, v4, v4
	v_fmac_f32_e32 v12, v6, v6
	v_add_f32_e32 v0, v0, v1
	v_mul_f32_e32 v1, v23, v23
	v_fmac_f32_e32 v2, v20, v20
	v_add_f32_e32 v3, v3, v12
	v_fmac_f32_e32 v1, v22, v22
	v_add_f32_e32 v2, v2, v3
	v_add_f32_e32 v1, v1, v2
	v_add_f32_e32 v3, v0, v1
	v_cvt_pk_bf16_f32 v9, v14, v15
	ds_bpermute_b32 v14, v112, v3
	v_lshl_add_u64 v[0:1], s[42:43], 0, v[212:213]
	v_lshl_add_u64 v[12:13], v[208:209], 1, v[0:1]
	v_cvt_pk_bf16_f32 v10, v16, v17
	v_cvt_pk_bf16_f32 v11, v18, v19
	s_waitcnt lgkmcnt(0)
	v_add_f32_e32 v0, v3, v14
	ds_bpermute_b32 v1, v113, v0
	v_cvt_pk_bf16_f32 v2, v4, v5
	v_cvt_pk_bf16_f32 v3, v6, v7
	v_cvt_pk_bf16_f32 v4, v20, v21
	v_cvt_pk_bf16_f32 v5, v22, v23
	global_store_dwordx4 v[12:13], v[8:11], off
	global_store_dwordx4 v[12:13], v[2:5], off offset:256
	s_and_saveexec_b64 s[0:1], vcc
	s_cbranch_execz .LBB0_420
	v_lshl_add_u64 v[2:3], v[210:211], 2, s[48:49]
	s_waitcnt lgkmcnt(0)
	v_add_f32_e32 v0, v0, v1
	global_atomic_add_f32 v[2:3], v0, off

; __device__ __forceinline__ u32x4 pack8(f32x4 a, f32x4 b) { u32x4 w; w.x = pk2(a[0], a[1]); w.y = pk2(a[2], a[3]); w.z = pk2(b[0], b[1]); w.w = pk2(b[2], b[3]); return w; }
;     __device__ __forceinline__ void operator()(const Acc& acc, const pg8::Unit& u, int wid) const {
;     ...
;         float r2[8];
; #pragma unroll
;         for (int i = 0; i < 8; ++i) r2[i] = ssq2 ? ssq2[row0 + (i >> 2) * 128 + (i & 3) * 16] : 0.f;
;         u32x4 bv[2][4][2];
; #pragma unroll
;         for (int ai = 0; ai < 2; ++ai)
; #pragma unroll
;             for (int m = 0; m < 4; ++m)
; #pragma unroll
;                 for (int bj = 0; bj < 2; ++bj) bv[ai][m][bj] = *(const u32x4*)(base + (size_t)(row0 + ai * 128 + m * 16) * 1024 + col0 + bj * 128);
; #pragma unroll
;         for (int ai = 0; ai < 2; ++ai) {
; #pragma unroll
;             for (int m = 0; m < 4; ++m) {
;                 const int row = row0 + ai * 128 + m * 16; float sq = 0.f;
;                 const float rr = ssq2 ? __builtin_amdgcn_rcpf(r2[ai * 4 + m] * (1.f / 1024.f) + EPS) : 1.f;
; #pragma unroll
;                 for (int bj = 0; bj < 2; ++bj) {
;                     const u32x4 b4 = bv[ai][m][bj];
;                     const f32x4 o0 = (f32x4){bflo(b4.x), bfhi(b4.x), bflo(b4.y), bfhi(b4.y)} + acc[ai][bj][m][0] * rr;
;                     const f32x4 o1 = (f32x4){bflo(b4.z), bfhi(b4.z), bflo(b4.w), bfhi(b4.w)} + acc[ai][bj][m][1] * rr;
;                     *(u32x4*)(hb + (size_t)row * 1024 + col0 + bj * 128) = pack8(o0, o1);
;                     sq += (o0[0] * o0[0] + o0[1] * o0[1]) + (o0[2] * o0[2] + o0[3] * o0[3]) + (o1[0] * o1[0] + o1[1] * o1[1]) + (o1[2] * o1[2] + o1[3] * o1[3]);
;                 }
;                 if (ssq_out) { sq += __shfl_xor(sq, 16); sq += __shfl_xor(sq, 32); if (fq == 0) atomicAdd(ssq_out + row, sq); }
.LBB0_558:
	s_lshl_b32 s1, s26, 8
	s_add_i32 s1, s1, s66
	v_mbcnt_lo_u32_b32 v208, -1, 0
	v_mbcnt_hi_u32_b32 v208, -1, v208
	s_lshl_b32 s0, s0, 8
	v_and_or_b32 v234, v208, 15, s1
	v_ashrrev_i32_e32 v124, 1, v208
	v_ashrrev_i32_e32 v235, 31, v234
	v_and_b32_e32 v126, -8, v124
	v_lshl_add_u64 v[124:125], v[234:235], 2, s[48:49]
	global_load_dword v127, v[124:125], off
	s_or_b32 s0, s0, s69
	v_add_u32_e32 v204, s0, v126
	v_ashrrev_i32_e32 v205, 31, v204
	v_lshlrev_b64 v[236:237], 1, v[204:205]
	v_lshl_add_u64 v[136:137], s[42:43], 0, v[236:237]
	v_lshlrev_b64 v[238:239], 11, v[234:235]
	global_load_dword v253, v[124:125], off offset:64
	global_load_dword v252, v[124:125], off offset:128
	global_load_dword v251, v[124:125], off offset:192
	global_load_dword v250, v[124:125], off offset:512
	global_load_dword v249, v[124:125], off offset:576
	global_load_dword v248, v[124:125], off offset:640
	global_load_dword v247, v[124:125], off offset:704
	v_lshl_add_u64 v[124:125], v[136:137], 0, v[238:239]
	global_load_dwordx4 v[188:191], v[124:125], off
	global_load_dwordx4 v[184:187], v[124:125], off offset:256
	v_or_b32_e32 v230, 16, v234
	v_ashrrev_i32_e32 v231, 31, v230
	v_or_b32_e32 v226, 32, v234
	v_lshlrev_b64 v[232:233], 11, v[230:231]
	v_ashrrev_i32_e32 v227, 31, v226
	v_or_b32_e32 v222, 48, v234
	v_add_u32_e32 v214, 0x80, v234
	v_lshl_add_u64 v[124:125], v[136:137], 0, v[232:233]
	v_lshlrev_b64 v[228:229], 11, v[226:227]
	v_ashrrev_i32_e32 v223, 31, v222
	v_ashrrev_i32_e32 v215, 31, v214
	global_load_dwordx4 v[180:183], v[124:125], off
	global_load_dwordx4 v[176:179], v[124:125], off offset:256
	v_lshl_add_u64 v[124:125], v[136:137], 0, v[228:229]
	v_lshlrev_b64 v[224:225], 11, v[222:223]
	v_add_u32_e32 v216, 0x90, v234
	global_load_dwordx4 v[172:175], v[124:125], off
	global_load_dwordx4 v[168:171], v[124:125], off offset:256
	v_lshl_add_u64 v[124:125], v[136:137], 0, v[224:225]
	v_lshlrev_b64 v[220:221], 11, v[214:215]
	v_ashrrev_i32_e32 v217, 31, v216
	global_load_dwordx4 v[164:167], v[124:125], off
	global_load_dwordx4 v[160:163], v[124:125], off offset:256
	v_lshl_add_u64 v[124:125], v[136:137], 0, v[220:221]
	v_lshlrev_b64 v[218:219], 11, v[216:217]
	v_add_u32_e32 v210, 0xa0, v234
	v_add_u32_e32 v206, 0xb0, v234
	global_load_dwordx4 v[156:159], v[124:125], off
	global_load_dwordx4 v[152:155], v[124:125], off offset:256
	v_lshl_add_u64 v[124:125], v[136:137], 0, v[218:219]
	v_ashrrev_i32_e32 v211, 31, v210
	v_ashrrev_i32_e32 v207, 31, v206
	global_load_dwordx4 v[148:151], v[124:125], off
	global_load_dwordx4 v[144:147], v[124:125], off offset:256
	v_lshlrev_b64 v[124:125], 11, v[210:211]
	v_lshlrev_b64 v[138:139], 11, v[206:207]
	v_lshl_add_u64 v[124:125], v[136:137], 0, v[124:125]
	v_lshl_add_u64 v[136:137], v[136:137], 0, v[138:139]
	v_cmp_gt_u32_e32 vcc, 16, v208
	s_waitcnt vmcnt(0) lgkmcnt(0)
	v_fmamk_f32 v209, v127, 0x3a800000, v245
	global_load_dwordx4 v[132:135], v[124:125], off
	s_nop 0
	global_load_dwordx4 v[124:127], v[124:125], off offset:256
	s_nop 0
	global_load_dwordx4 v[140:143], v[136:137], off
	s_nop 0
	global_load_dwordx4 v[136:139], v[136:137], off offset:256
	v_rcp_f32_e32 v208, v209
	v_lshlrev_b32_e32 v212, 16, v188
	v_and_b32_e32 v213, 0xffff0000, v188
	v_lshlrev_b32_e32 v188, 16, v189
	v_and_b32_e32 v189, 0xffff0000, v189
	v_pk_fma_f32 v[130:131], v[130:131], v[208:209], v[188:189] op_sel_hi:[1,0,1]
	v_lshlrev_b32_e32 v188, 16, v190
	v_and_b32_e32 v189, 0xffff0000, v190
	v_lshlrev_b32_e32 v190, 16, v191
	v_and_b32_e32 v191, 0xffff0000, v191
	v_pk_fma_f32 v[128:129], v[128:129], v[208:209], v[212:213] op_sel_hi:[1,0,1]
	v_pk_fma_f32 v[190:191], v[122:123], v[208:209], v[190:191] op_sel_hi:[1,0,1]
	v_pk_fma_f32 v[188:189], v[120:121], v[208:209], v[188:189] op_sel_hi:[1,0,1]
	v_lshl_add_u64 v[212:213], s[42:43], 0, v[238:239]
	v_cvt_pk_bf16_f32 v120, v128, v129
	v_cvt_pk_bf16_f32 v121, v130, v131
	v_cvt_pk_bf16_f32 v122, v188, v189
	v_cvt_pk_bf16_f32 v123, v190, v191
	v_lshl_add_u64 v[212:213], v[212:213], 0, v[236:237]
	global_store_dwordx4 v[212:213], v[120:123], off
	s_nop 1
	v_lshlrev_b32_e32 v120, 16, v184
	v_and_b32_e32 v121, 0xffff0000, v184
	v_lshlrev_b32_e32 v122, 16, v185
	v_and_b32_e32 v123, 0xffff0000, v185
	v_pk_fma_f32 v[118:119], v[118:119], v[208:209], v[122:123] op_sel_hi:[1,0,1]
	v_pk_fma_f32 v[116:117], v[116:117], v[208:209], v[120:121] op_sel_hi:[1,0,1]
	v_lshlrev_b32_e32 v120, 16, v186
	v_and_b32_e32 v121, 0xffff0000, v186
	v_lshlrev_b32_e32 v122, 16, v187
	v_and_b32_e32 v123, 0xffff0000, v187
	v_pk_fma_f32 v[122:123], v[114:115], v[208:209], v[122:123] op_sel_hi:[1,0,1]
	v_pk_fma_f32 v[120:121], v[112:113], v[208:209], v[120:121] op_sel_hi:[1,0,1]
	v_cvt_pk_bf16_f32 v112, v116, v117
	v_cvt_pk_bf16_f32 v113, v118, v119
	v_cvt_pk_bf16_f32 v114, v120, v121
	v_cvt_pk_bf16_f32 v115, v122, v123
	global_store_dwordx4 v[212:213], v[112:115], off offset:256
	s_nop 1
	v_mul_f32_e32 v114, v129, v129
	v_mul_f32_e32 v115, v131, v131
	v_fmac_f32_e32 v114, v128, v128
	v_fmac_f32_e32 v115, v130, v130
	v_mul_f32_e32 v113, v189, v189
	v_add_f32_e32 v114, v114, v115
	v_mul_f32_e32 v115, v117, v117
	v_mul_f32_e32 v112, v191, v191
	v_fmac_f32_e32 v113, v188, v188
	v_fmac_f32_e32 v115, v116, v116
	v_mul_f32_e32 v116, v119, v119
	v_fmac_f32_e32 v112, v190, v190
	v_add_f32_e32 v113, v113, v114
	v_mul_f32_e32 v114, v121, v121
	v_fmac_f32_e32 v116, v118, v118
	v_add_f32_e32 v112, v112, v113
	v_mul_f32_e32 v113, v123, v123
	v_fmac_f32_e32 v114, v120, v120
	v_add_f32_e32 v115, v115, v116
	v_fmac_f32_e32 v113, v122, v122
	v_add_f32_e32 v114, v114, v115
	v_add_f32_e32 v113, v113, v114
	v_and_b32_e32 v114, 64, v246
	v_add_f32_e32 v113, v112, v113
	v_xor_b32_e32 v112, 16, v246
	v_add_u32_e32 v115, 64, v114
	v_cmp_lt_i32_e64 s[0:1], v112, v115
	s_nop 1
	v_cndmask_b32_e64 v112, v246, v112, s[0:1]
	v_lshlrev_b32_e32 v112, 2, v112
	ds_bpermute_b32 v114, v112, v113
	s_waitcnt lgkmcnt(0)
	v_add_f32_e32 v114, v113, v114
	v_xor_b32_e32 v113, 32, v246
	v_cmp_lt_i32_e64 s[0:1], v113, v115
	s_nop 1
	v_cndmask_b32_e64 v113, v246, v113, s[0:1]
	v_lshlrev_b32_e32 v113, 2, v113
	ds_bpermute_b32 v115, v113, v114
	s_and_saveexec_b64 s[0:1], vcc
	s_cbranch_execz .LBB0_560
	v_lshl_add_u64 v[116:117], v[234:235], 2, s[60:61]
	s_waitcnt lgkmcnt(0)
	v_add_f32_e32 v114, v114, v115
	global_atomic_add_f32 v[116:117], v114, off
; __device__ __forceinline__ u32x4 pack8(f32x4 a, f32x4 b) { u32x4 w; w.x = pk2(a[0], a[1]); w.y = pk2(a[2], a[3]); w.z = pk2(b[0], b[1]); w.w = pk2(b[2], b[3]); return w; }
;     __device__ __forceinline__ void operator()(const Acc& acc, const pg8::Unit& u, int wid) const {
;     ...
;                 const int row = row0 + ai * 128 + m * 16; float sq = 0.f;
;                 const float rr = ssq2 ? __builtin_amdgcn_rcpf(r2[ai * 4 + m] * (1.f / 1024.f) + EPS) : 1.f;
; #pragma unroll
;                 for (int bj = 0; bj < 2; ++bj) {
;                     const u32x4 b4 = bv[ai][m][bj];
;                     const f32x4 o0 = (f32x4){bflo(b4.x), bfhi(b4.x), bflo(b4.y), bfhi(b4.y)} + acc[ai][bj][m][0] * rr;
;                     const f32x4 o1 = (f32x4){bflo(b4.z), bfhi(b4.z), bflo(b4.w), bfhi(b4.w)} + acc[ai][bj][m][1] * rr;
;                     *(u32x4*)(hb + (size_t)row * 1024 + col0 + bj * 128) = pack8(o0, o1);
;                     sq += (o0[0] * o0[0] + o0[1] * o0[1]) + (o0[2] * o0[2] + o0[3] * o0[3]) + (o1[0] * o1[0] + o1[1] * o1[1]) + (o1[2] * o1[2] + o1[3] * o1[3]);
;                 }
;                 if (ssq_out) { sq += __shfl_xor(sq, 16); sq += __shfl_xor(sq, 32); if (fq == 0) atomicAdd(ssq_out + row, sq); }
.LBB0_560:
	s_or_b64 exec, exec, s[0:1]
	v_fmamk_f32 v114, v253, 0x3a800000, v245
	v_rcp_f32_e32 v114, v114
	v_lshlrev_b32_e32 v116, 16, v180
	v_and_b32_e32 v117, 0xffff0000, v180
	v_lshlrev_b32_e32 v118, 16, v181
	v_and_b32_e32 v119, 0xffff0000, v181
	v_lshlrev_b32_e32 v122, 16, v177
	v_and_b32_e32 v123, 0xffff0000, v177
	s_waitcnt lgkmcnt(0)
	v_pk_fma_f32 v[110:111], v[110:111], v[114:115], v[118:119] op_sel_hi:[1,0,1]
	v_pk_fma_f32 v[108:109], v[108:109], v[114:115], v[116:117] op_sel_hi:[1,0,1]
	v_lshlrev_b32_e32 v116, 16, v182
	v_and_b32_e32 v117, 0xffff0000, v182
	v_lshlrev_b32_e32 v120, 16, v176
	v_and_b32_e32 v121, 0xffff0000, v176
	v_pk_fma_f32 v[102:103], v[102:103], v[114:115], v[122:123] op_sel_hi:[1,0,1]
	v_lshlrev_b32_e32 v122, 16, v179
	v_and_b32_e32 v123, 0xffff0000, v179
	v_lshlrev_b32_e32 v118, 16, v183
	v_and_b32_e32 v119, 0xffff0000, v183
	v_pk_fma_f32 v[116:117], v[104:105], v[114:115], v[116:117] op_sel_hi:[1,0,1]
	v_pk_fma_f32 v[100:101], v[100:101], v[114:115], v[120:121] op_sel_hi:[1,0,1]
	v_lshlrev_b32_e32 v120, 16, v178
	v_and_b32_e32 v121, 0xffff0000, v178
	v_pk_fma_f32 v[122:123], v[98:99], v[114:115], v[122:123] op_sel_hi:[1,0,1]
	v_mul_f32_e32 v98, v109, v109
	v_mul_f32_e32 v99, v111, v111
	v_pk_fma_f32 v[118:119], v[106:107], v[114:115], v[118:119] op_sel_hi:[1,0,1]
	v_pk_fma_f32 v[114:115], v[96:97], v[114:115], v[120:121] op_sel_hi:[1,0,1]
	v_mul_f32_e32 v97, v117, v117
	v_fmac_f32_e32 v98, v108, v108
	v_fmac_f32_e32 v99, v110, v110
	v_cvt_pk_bf16_f32 v104, v108, v109
	v_mul_f32_e32 v96, v119, v119
	v_fmac_f32_e32 v97, v116, v116
	v_add_f32_e32 v98, v98, v99
	v_mul_f32_e32 v99, v101, v101
	v_mul_f32_e32 v108, v103, v103
	v_fmac_f32_e32 v96, v118, v118
	v_add_f32_e32 v97, v97, v98
	v_mul_f32_e32 v98, v115, v115
	v_fmac_f32_e32 v99, v100, v100
	v_fmac_f32_e32 v108, v102, v102
	v_add_f32_e32 v96, v96, v97
	v_mul_f32_e32 v97, v123, v123
	v_fmac_f32_e32 v98, v114, v114
	v_add_f32_e32 v99, v99, v108
	v_fmac_f32_e32 v97, v122, v122
	v_add_f32_e32 v98, v98, v99
	v_add_f32_e32 v97, v97, v98
	v_add_f32_e32 v99, v96, v97
	v_cvt_pk_bf16_f32 v105, v110, v111
	ds_bpermute_b32 v110, v112, v99
	v_lshl_add_u64 v[96:97], s[42:43], 0, v[232:233]
	v_lshl_add_u64 v[108:109], v[204:205], 1, v[96:97]
	v_cvt_pk_bf16_f32 v106, v116, v117
	v_cvt_pk_bf16_f32 v107, v118, v119
	s_waitcnt lgkmcnt(0)
	v_add_f32_e32 v96, v99, v110
	ds_bpermute_b32 v97, v113, v96
	v_cvt_pk_bf16_f32 v98, v100, v101
	v_cvt_pk_bf16_f32 v99, v102, v103
	v_cvt_pk_bf16_f32 v100, v114, v115
	v_cvt_pk_bf16_f32 v101, v122, v123
	global_store_dwordx4 v[108:109], v[104:107], off
	global_store_dwordx4 v[108:109], v[98:101], off offset:256
	s_and_saveexec_b64 s[0:1], vcc
	s_cbranch_execz .LBB0_562
	v_lshl_add_u64 v[98:99], v[230:231], 2, s[60:61]
	s_waitcnt lgkmcnt(0)
	v_add_f32_e32 v96, v96, v97
	global_atomic_add_f32 v[98:99], v96, off
.LBB0_562:
	s_or_b64 exec, exec, s[0:1]
	v_fmamk_f32 v96, v252, 0x3a800000, v245
	v_rcp_f32_e32 v96, v96
	v_lshlrev_b32_e32 v98, 16, v172
	v_and_b32_e32 v99, 0xffff0000, v172
	v_lshlrev_b32_e32 v100, 16, v173
	v_and_b32_e32 v101, 0xffff0000, v173
	v_lshlrev_b32_e32 v104, 16, v169
	v_and_b32_e32 v105, 0xffff0000, v169
	s_waitcnt lgkmcnt(0)
	v_pk_fma_f32 v[94:95], v[94:95], v[96:97], v[100:101] op_sel_hi:[1,0,1]
	v_pk_fma_f32 v[92:93], v[92:93], v[96:97], v[98:99] op_sel_hi:[1,0,1]
	v_lshlrev_b32_e32 v98, 16, v174
	v_and_b32_e32 v99, 0xffff0000, v174
	v_lshlrev_b32_e32 v102, 16, v168
	v_and_b32_e32 v103, 0xffff0000, v168
	v_pk_fma_f32 v[86:87], v[86:87], v[96:97], v[104:105] op_sel_hi:[1,0,1]
	v_lshlrev_b32_e32 v104, 16, v171
	v_and_b32_e32 v105, 0xffff0000, v171
	v_lshlrev_b32_e32 v100, 16, v175
	v_and_b32_e32 v101, 0xffff0000, v175
	v_pk_fma_f32 v[98:99], v[88:89], v[96:97], v[98:99] op_sel_hi:[1,0,1]
	v_pk_fma_f32 v[84:85], v[84:85], v[96:97], v[102:103] op_sel_hi:[1,0,1]
	v_lshlrev_b32_e32 v102, 16, v170
	v_and_b32_e32 v103, 0xffff0000, v170
	v_pk_fma_f32 v[104:105], v[82:83], v[96:97], v[104:105] op_sel_hi:[1,0,1]
	v_mul_f32_e32 v82, v93, v93
	v_mul_f32_e32 v83, v95, v95
	v_pk_fma_f32 v[100:101], v[90:91], v[96:97], v[100:101] op_sel_hi:[1,0,1]
	v_pk_fma_f32 v[96:97], v[80:81], v[96:97], v[102:103] op_sel_hi:[1,0,1]
	v_mul_f32_e32 v81, v99, v99
	v_fmac_f32_e32 v82, v92, v92
	v_fmac_f32_e32 v83, v94, v94
	v_cvt_pk_bf16_f32 v88, v92, v93
	v_mul_f32_e32 v80, v101, v101
	v_fmac_f32_e32 v81, v98, v98
	v_add_f32_e32 v82, v82, v83
	v_mul_f32_e32 v83, v85, v85
	v_mul_f32_e32 v92, v87, v87
	v_fmac_f32_e32 v80, v100, v100
	v_add_f32_e32 v81, v81, v82
	v_mul_f32_e32 v82, v97, v97
	v_fmac_f32_e32 v83, v84, v84
	v_fmac_f32_e32 v92, v86, v86
	v_add_f32_e32 v80, v80, v81
	v_mul_f32_e32 v81, v105, v105
	v_fmac_f32_e32 v82, v96, v96
	v_add_f32_e32 v83, v83, v92
	v_fmac_f32_e32 v81, v104, v104
	v_add_f32_e32 v82, v82, v83
	v_add_f32_e32 v81, v81, v82
	v_add_f32_e32 v83, v80, v81
	v_cvt_pk_bf16_f32 v89, v94, v95
	ds_bpermute_b32 v94, v112, v83
	v_lshl_add_u64 v[80:81], s[42:43], 0, v[228:229]
	v_lshl_add_u64 v[92:93], v[204:205], 1, v[80:81]
	v_cvt_pk_bf16_f32 v90, v98, v99
	v_cvt_pk_bf16_f32 v91, v100, v101
	s_waitcnt lgkmcnt(0)
	v_add_f32_e32 v80, v83, v94
	ds_bpermute_b32 v81, v113, v80
	v_cvt_pk_bf16_f32 v82, v84, v85
	v_cvt_pk_bf16_f32 v83, v86, v87
	v_cvt_pk_bf16_f32 v84, v96, v97
	v_cvt_pk_bf16_f32 v85, v104, v105
	global_store_dwordx4 v[92:93], v[88:91], off
	global_store_dwordx4 v[92:93], v[82:85], off offset:256
	s_and_saveexec_b64 s[0:1], vcc
	s_cbranch_execz .LBB0_564
	v_lshl_add_u64 v[82:83], v[226:227], 2, s[60:61]
	s_waitcnt lgkmcnt(0)
	v_add_f32_e32 v80, v80, v81
	global_atomic_add_f32 v[82:83], v80, off
; __device__ __forceinline__ u32x4 pack8(f32x4 a, f32x4 b) { u32x4 w; w.x = pk2(a[0], a[1]); w.y = pk2(a[2], a[3]); w.z = pk2(b[0], b[1]); w.w = pk2(b[2], b[3]); return w; }
;     __device__ __forceinline__ void operator()(const Acc& acc, const pg8::Unit& u, int wid) const {
;     ...
;                 const int row = row0 + ai * 128 + m * 16; float sq = 0.f;
;                 const float rr = ssq2 ? __builtin_amdgcn_rcpf(r2[ai * 4 + m] * (1.f / 1024.f) + EPS) : 1.f;
; #pragma unroll
;                 for (int bj = 0; bj < 2; ++bj) {
;                     const u32x4 b4 = bv[ai][m][bj];
;                     const f32x4 o0 = (f32x4){bflo(b4.x), bfhi(b4.x), bflo(b4.y), bfhi(b4.y)} + acc[ai][bj][m][0] * rr;
;                     const f32x4 o1 = (f32x4){bflo(b4.z), bfhi(b4.z), bflo(b4.w), bfhi(b4.w)} + acc[ai][bj][m][1] * rr;
;                     *(u32x4*)(hb + (size_t)row * 1024 + col0 + bj * 128) = pack8(o0, o1);
;                     sq += (o0[0] * o0[0] + o0[1] * o0[1]) + (o0[2] * o0[2] + o0[3] * o0[3]) + (o1[0] * o1[0] + o1[1] * o1[1]) + (o1[2] * o1[2] + o1[3] * o1[3]);
;                 }
;                 if (ssq_out) { sq += __shfl_xor(sq, 16); sq += __shfl_xor(sq, 32); if (fq == 0) atomicAdd(ssq_out + row, sq); }
.LBB0_564:
	s_or_b64 exec, exec, s[0:1]
	v_fmamk_f32 v80, v251, 0x3a800000, v245
	v_rcp_f32_e32 v80, v80
	v_lshlrev_b32_e32 v82, 16, v164
	v_and_b32_e32 v83, 0xffff0000, v164
	v_lshlrev_b32_e32 v84, 16, v165
	v_and_b32_e32 v85, 0xffff0000, v165
	v_lshlrev_b32_e32 v88, 16, v161
	v_and_b32_e32 v89, 0xffff0000, v161
	s_waitcnt lgkmcnt(0)
	v_pk_fma_f32 v[78:79], v[78:79], v[80:81], v[84:85] op_sel_hi:[1,0,1]
	v_pk_fma_f32 v[76:77], v[76:77], v[80:81], v[82:83] op_sel_hi:[1,0,1]
	v_lshlrev_b32_e32 v82, 16, v166
	v_and_b32_e32 v83, 0xffff0000, v166
	v_lshlrev_b32_e32 v86, 16, v160
	v_and_b32_e32 v87, 0xffff0000, v160
	v_pk_fma_f32 v[70:71], v[70:71], v[80:81], v[88:89] op_sel_hi:[1,0,1]
	v_lshlrev_b32_e32 v88, 16, v163
	v_and_b32_e32 v89, 0xffff0000, v163
	v_lshlrev_b32_e32 v84, 16, v167
	v_and_b32_e32 v85, 0xffff0000, v167
	v_pk_fma_f32 v[82:83], v[72:73], v[80:81], v[82:83] op_sel_hi:[1,0,1]
	v_pk_fma_f32 v[68:69], v[68:69], v[80:81], v[86:87] op_sel_hi:[1,0,1]
	v_lshlrev_b32_e32 v86, 16, v162
	v_and_b32_e32 v87, 0xffff0000, v162
	v_pk_fma_f32 v[88:89], v[66:67], v[80:81], v[88:89] op_sel_hi:[1,0,1]
	v_mul_f32_e32 v66, v77, v77
	v_mul_f32_e32 v67, v79, v79
	v_pk_fma_f32 v[84:85], v[74:75], v[80:81], v[84:85] op_sel_hi:[1,0,1]
	v_pk_fma_f32 v[80:81], v[64:65], v[80:81], v[86:87] op_sel_hi:[1,0,1]
	v_mul_f32_e32 v65, v83, v83
	v_fmac_f32_e32 v66, v76, v76
	v_fmac_f32_e32 v67, v78, v78
	v_cvt_pk_bf16_f32 v72, v76, v77
	v_mul_f32_e32 v64, v85, v85
	v_fmac_f32_e32 v65, v82, v82
	v_add_f32_e32 v66, v66, v67
	v_mul_f32_e32 v67, v69, v69
	v_mul_f32_e32 v76, v71, v71
	v_fmac_f32_e32 v64, v84, v84
	v_add_f32_e32 v65, v65, v66
	v_mul_f32_e32 v66, v81, v81
	v_fmac_f32_e32 v67, v68, v68
	v_fmac_f32_e32 v76, v70, v70
	v_add_f32_e32 v64, v64, v65
	v_mul_f32_e32 v65, v89, v89
	v_fmac_f32_e32 v66, v80, v80
	v_add_f32_e32 v67, v67, v76
	v_fmac_f32_e32 v65, v88, v88
	v_add_f32_e32 v66, v66, v67
	v_add_f32_e32 v65, v65, v66
	v_add_f32_e32 v67, v64, v65
	v_cvt_pk_bf16_f32 v73, v78, v79
	ds_bpermute_b32 v78, v112, v67
	v_lshl_add_u64 v[64:65], s[42:43], 0, v[224:225]
	v_lshl_add_u64 v[76:77], v[204:205], 1, v[64:65]
	v_cvt_pk_bf16_f32 v74, v82, v83
	v_cvt_pk_bf16_f32 v75, v84, v85
	s_waitcnt lgkmcnt(0)
	v_add_f32_e32 v64, v67, v78
	ds_bpermute_b32 v65, v113, v64
	v_cvt_pk_bf16_f32 v66, v68, v69
	v_cvt_pk_bf16_f32 v67, v70, v71
	v_cvt_pk_bf16_f32 v68, v80, v81
	v_cvt_pk_bf16_f32 v69, v88, v89
	global_store_dwordx4 v[76:77], v[72:75], off
	global_store_dwordx4 v[76:77], v[66:69], off offset:256
	s_and_saveexec_b64 s[0:1], vcc
	s_cbranch_execz .LBB0_566
	v_lshl_add_u64 v[66:67], v[222:223], 2, s[60:61]
	s_waitcnt lgkmcnt(0)
	v_add_f32_e32 v64, v64, v65
	global_atomic_add_f32 v[66:67], v64, off
.LBB0_566:
	s_or_b64 exec, exec, s[0:1]
	v_fmamk_f32 v64, v250, 0x3a800000, v245
	v_rcp_f32_e32 v64, v64
	v_lshlrev_b32_e32 v66, 16, v156
	v_and_b32_e32 v67, 0xffff0000, v156
	v_lshlrev_b32_e32 v68, 16, v157
	v_and_b32_e32 v69, 0xffff0000, v157
	v_lshlrev_b32_e32 v72, 16, v153
	v_and_b32_e32 v73, 0xffff0000, v153
	s_waitcnt lgkmcnt(0)
	v_pk_fma_f32 v[62:63], v[62:63], v[64:65], v[68:69] op_sel_hi:[1,0,1]
	v_pk_fma_f32 v[60:61], v[60:61], v[64:65], v[66:67] op_sel_hi:[1,0,1]
	v_lshlrev_b32_e32 v66, 16, v158
	v_and_b32_e32 v67, 0xffff0000, v158
	v_lshlrev_b32_e32 v70, 16, v152
	v_and_b32_e32 v71, 0xffff0000, v152
	v_pk_fma_f32 v[54:55], v[54:55], v[64:65], v[72:73] op_sel_hi:[1,0,1]
	v_lshlrev_b32_e32 v72, 16, v155
	v_and_b32_e32 v73, 0xffff0000, v155
	v_lshlrev_b32_e32 v68, 16, v159
	v_and_b32_e32 v69, 0xffff0000, v159
	v_pk_fma_f32 v[66:67], v[56:57], v[64:65], v[66:67] op_sel_hi:[1,0,1]
	v_pk_fma_f32 v[52:53], v[52:53], v[64:65], v[70:71] op_sel_hi:[1,0,1]
	v_lshlrev_b32_e32 v70, 16, v154
	v_and_b32_e32 v71, 0xffff0000, v154
	v_pk_fma_f32 v[72:73], v[50:51], v[64:65], v[72:73] op_sel_hi:[1,0,1]
	v_mul_f32_e32 v50, v61, v61
	v_mul_f32_e32 v51, v63, v63
	v_pk_fma_f32 v[68:69], v[58:59], v[64:65], v[68:69] op_sel_hi:[1,0,1]
	v_pk_fma_f32 v[64:65], v[48:49], v[64:65], v[70:71] op_sel_hi:[1,0,1]
	v_mul_f32_e32 v49, v67, v67
	v_fmac_f32_e32 v50, v60, v60
	v_fmac_f32_e32 v51, v62, v62
	v_cvt_pk_bf16_f32 v56, v60, v61
	v_mul_f32_e32 v48, v69, v69
	v_fmac_f32_e32 v49, v66, v66
	v_add_f32_e32 v50, v50, v51
	v_mul_f32_e32 v51, v53, v53
	v_mul_f32_e32 v60, v55, v55
	v_fmac_f32_e32 v48, v68, v68
	v_add_f32_e32 v49, v49, v50
	v_mul_f32_e32 v50, v65, v65
	v_fmac_f32_e32 v51, v52, v52
	v_fmac_f32_e32 v60, v54, v54
	v_add_f32_e32 v48, v48, v49
	v_mul_f32_e32 v49, v73, v73
	v_fmac_f32_e32 v50, v64, v64
	v_add_f32_e32 v51, v51, v60
	v_fmac_f32_e32 v49, v72, v72
	v_add_f32_e32 v50, v50, v51
	v_add_f32_e32 v49, v49, v50
	v_add_f32_e32 v51, v48, v49
	v_cvt_pk_bf16_f32 v57, v62, v63
	ds_bpermute_b32 v62, v112, v51
	v_lshl_add_u64 v[48:49], s[42:43], 0, v[220:221]
	v_lshl_add_u64 v[60:61], v[204:205], 1, v[48:49]
	v_cvt_pk_bf16_f32 v58, v66, v67
	v_cvt_pk_bf16_f32 v59, v68, v69
	s_waitcnt lgkmcnt(0)
	v_add_f32_e32 v48, v51, v62
	ds_bpermute_b32 v49, v113, v48
	v_cvt_pk_bf16_f32 v50, v52, v53
	v_cvt_pk_bf16_f32 v51, v54, v55
	v_cvt_pk_bf16_f32 v52, v64, v65
	v_cvt_pk_bf16_f32 v53, v72, v73
	global_store_dwordx4 v[60:61], v[56:59], off
	global_store_dwordx4 v[60:61], v[50:53], off offset:256
	s_and_saveexec_b64 s[0:1], vcc
	s_cbranch_execz .LBB0_568
	v_lshl_add_u64 v[50:51], v[214:215], 2, s[60:61]
	s_waitcnt lgkmcnt(0)
	v_add_f32_e32 v48, v48, v49
	global_atomic_add_f32 v[50:51], v48, off
; __device__ __forceinline__ u32x4 pack8(f32x4 a, f32x4 b) { u32x4 w; w.x = pk2(a[0], a[1]); w.y = pk2(a[2], a[3]); w.z = pk2(b[0], b[1]); w.w = pk2(b[2], b[3]); return w; }
;     __device__ __forceinline__ void operator()(const Acc& acc, const pg8::Unit& u, int wid) const {
;     ...
;                 const int row = row0 + ai * 128 + m * 16; float sq = 0.f;
;                 const float rr = ssq2 ? __builtin_amdgcn_rcpf(r2[ai * 4 + m] * (1.f / 1024.f) + EPS) : 1.f;
; #pragma unroll
;                 for (int bj = 0; bj < 2; ++bj) {
;                     const u32x4 b4 = bv[ai][m][bj];
;                     const f32x4 o0 = (f32x4){bflo(b4.x), bfhi(b4.x), bflo(b4.y), bfhi(b4.y)} + acc[ai][bj][m][0] * rr;
;                     const f32x4 o1 = (f32x4){bflo(b4.z), bfhi(b4.z), bflo(b4.w), bfhi(b4.w)} + acc[ai][bj][m][1] * rr;
;                     *(u32x4*)(hb + (size_t)row * 1024 + col0 + bj * 128) = pack8(o0, o1);
;                     sq += (o0[0] * o0[0] + o0[1] * o0[1]) + (o0[2] * o0[2] + o0[3] * o0[3]) + (o1[0] * o1[0] + o1[1] * o1[1]) + (o1[2] * o1[2] + o1[3] * o1[3]);
;                 }
;                 if (ssq_out) { sq += __shfl_xor(sq, 16); sq += __shfl_xor(sq, 32); if (fq == 0) atomicAdd(ssq_out + row, sq); }
.LBB0_568:
	s_or_b64 exec, exec, s[0:1]
	v_fmamk_f32 v48, v249, 0x3a800000, v245
	v_rcp_f32_e32 v48, v48
	v_lshlrev_b32_e32 v50, 16, v148
	v_and_b32_e32 v51, 0xffff0000, v148
	v_lshlrev_b32_e32 v52, 16, v149
	v_and_b32_e32 v53, 0xffff0000, v149
	v_lshlrev_b32_e32 v56, 16, v145
	v_and_b32_e32 v57, 0xffff0000, v145
	s_waitcnt lgkmcnt(0)
	v_pk_fma_f32 v[46:47], v[46:47], v[48:49], v[52:53] op_sel_hi:[1,0,1]
	v_pk_fma_f32 v[44:45], v[44:45], v[48:49], v[50:51] op_sel_hi:[1,0,1]
	v_lshlrev_b32_e32 v50, 16, v150
	v_and_b32_e32 v51, 0xffff0000, v150
	v_lshlrev_b32_e32 v54, 16, v144
	v_and_b32_e32 v55, 0xffff0000, v144
	v_pk_fma_f32 v[38:39], v[38:39], v[48:49], v[56:57] op_sel_hi:[1,0,1]
	v_lshlrev_b32_e32 v56, 16, v147
	v_and_b32_e32 v57, 0xffff0000, v147
	v_lshlrev_b32_e32 v52, 16, v151
	v_and_b32_e32 v53, 0xffff0000, v151
	v_pk_fma_f32 v[50:51], v[40:41], v[48:49], v[50:51] op_sel_hi:[1,0,1]
	v_pk_fma_f32 v[36:37], v[36:37], v[48:49], v[54:55] op_sel_hi:[1,0,1]
	v_lshlrev_b32_e32 v54, 16, v146
	v_and_b32_e32 v55, 0xffff0000, v146
	v_pk_fma_f32 v[56:57], v[34:35], v[48:49], v[56:57] op_sel_hi:[1,0,1]
	v_mul_f32_e32 v34, v45, v45
	v_mul_f32_e32 v35, v47, v47
	v_pk_fma_f32 v[52:53], v[42:43], v[48:49], v[52:53] op_sel_hi:[1,0,1]
	v_pk_fma_f32 v[48:49], v[32:33], v[48:49], v[54:55] op_sel_hi:[1,0,1]
	v_mul_f32_e32 v33, v51, v51
	v_fmac_f32_e32 v34, v44, v44
	v_fmac_f32_e32 v35, v46, v46
	v_cvt_pk_bf16_f32 v40, v44, v45
	v_mul_f32_e32 v32, v53, v53
	v_fmac_f32_e32 v33, v50, v50
	v_add_f32_e32 v34, v34, v35
	v_mul_f32_e32 v35, v37, v37
	v_mul_f32_e32 v44, v39, v39
	v_fmac_f32_e32 v32, v52, v52
	v_add_f32_e32 v33, v33, v34
	v_mul_f32_e32 v34, v49, v49
	v_fmac_f32_e32 v35, v36, v36
	v_fmac_f32_e32 v44, v38, v38
	v_add_f32_e32 v32, v32, v33
	v_mul_f32_e32 v33, v57, v57
	v_fmac_f32_e32 v34, v48, v48
	v_add_f32_e32 v35, v35, v44
	v_fmac_f32_e32 v33, v56, v56
	v_add_f32_e32 v34, v34, v35
	v_add_f32_e32 v33, v33, v34
	v_add_f32_e32 v35, v32, v33
	v_cvt_pk_bf16_f32 v41, v46, v47
	ds_bpermute_b32 v46, v112, v35
	v_lshl_add_u64 v[32:33], s[42:43], 0, v[218:219]
	v_lshl_add_u64 v[44:45], v[204:205], 1, v[32:33]
	v_cvt_pk_bf16_f32 v42, v50, v51
	v_cvt_pk_bf16_f32 v43, v52, v53
	s_waitcnt lgkmcnt(0)
	v_add_f32_e32 v32, v35, v46
	ds_bpermute_b32 v33, v113, v32
	v_cvt_pk_bf16_f32 v34, v36, v37
	v_cvt_pk_bf16_f32 v35, v38, v39
	v_cvt_pk_bf16_f32 v36, v48, v49
	v_cvt_pk_bf16_f32 v37, v56, v57
	global_store_dwordx4 v[44:45], v[40:43], off
	global_store_dwordx4 v[44:45], v[34:37], off offset:256
	s_and_saveexec_b64 s[0:1], vcc
	s_cbranch_execz .LBB0_570
	v_lshl_add_u64 v[34:35], v[216:217], 2, s[60:61]
	s_waitcnt lgkmcnt(0)
	v_add_f32_e32 v32, v32, v33
	global_atomic_add_f32 v[34:35], v32, off
; __device__ __forceinline__ u32x4 pack8(f32x4 a, f32x4 b) { u32x4 w; w.x = pk2(a[0], a[1]); w.y = pk2(a[2], a[3]); w.z = pk2(b[0], b[1]); w.w = pk2(b[2], b[3]); return w; }
;     __device__ __forceinline__ void operator()(const Acc& acc, const pg8::Unit& u, int wid) const {
;     ...
;                 const int row = row0 + ai * 128 + m * 16; float sq = 0.f;
;                 const float rr = ssq2 ? __builtin_amdgcn_rcpf(r2[ai * 4 + m] * (1.f / 1024.f) + EPS) : 1.f;
; #pragma unroll
;                 for (int bj = 0; bj < 2; ++bj) {
;                     const u32x4 b4 = bv[ai][m][bj];
;                     const f32x4 o0 = (f32x4){bflo(b4.x), bfhi(b4.x), bflo(b4.y), bfhi(b4.y)} + acc[ai][bj][m][0] * rr;
;                     const f32x4 o1 = (f32x4){bflo(b4.z), bfhi(b4.z), bflo(b4.w), bfhi(b4.w)} + acc[ai][bj][m][1] * rr;
;                     *(u32x4*)(hb + (size_t)row * 1024 + col0 + bj * 128) = pack8(o0, o1);
;                     sq += (o0[0] * o0[0] + o0[1] * o0[1]) + (o0[2] * o0[2] + o0[3] * o0[3]) + (o1[0] * o1[0] + o1[1] * o1[1]) + (o1[2] * o1[2] + o1[3] * o1[3]);
;                 }
;                 if (ssq_out) { sq += __shfl_xor(sq, 16); sq += __shfl_xor(sq, 32); if (fq == 0) atomicAdd(ssq_out + row, sq); }
.LBB0_570:
	s_or_b64 exec, exec, s[0:1]
	v_fmamk_f32 v32, v248, 0x3a800000, v245
	v_rcp_f32_e32 v32, v32
	s_waitcnt vmcnt(12)
	v_lshlrev_b32_e32 v34, 16, v132
	v_and_b32_e32 v35, 0xffff0000, v132
	v_lshlrev_b32_e32 v36, 16, v133
	v_and_b32_e32 v37, 0xffff0000, v133
	v_lshlrev_b32_e32 v40, 16, v125
	v_and_b32_e32 v41, 0xffff0000, v125
	s_waitcnt lgkmcnt(0)
	v_pk_fma_f32 v[30:31], v[30:31], v[32:33], v[36:37] op_sel_hi:[1,0,1]
	v_pk_fma_f32 v[28:29], v[28:29], v[32:33], v[34:35] op_sel_hi:[1,0,1]
	v_lshlrev_b32_e32 v34, 16, v134
	v_and_b32_e32 v35, 0xffff0000, v134
	v_lshlrev_b32_e32 v38, 16, v124
	v_and_b32_e32 v39, 0xffff0000, v124
	v_pk_fma_f32 v[22:23], v[22:23], v[32:33], v[40:41] op_sel_hi:[1,0,1]
	v_lshlrev_b32_e32 v40, 16, v127
	v_and_b32_e32 v41, 0xffff0000, v127
	v_lshlrev_b32_e32 v36, 16, v135
	v_and_b32_e32 v37, 0xffff0000, v135
	v_pk_fma_f32 v[34:35], v[24:25], v[32:33], v[34:35] op_sel_hi:[1,0,1]
	v_pk_fma_f32 v[20:21], v[20:21], v[32:33], v[38:39] op_sel_hi:[1,0,1]
	v_lshlrev_b32_e32 v38, 16, v126
	v_and_b32_e32 v39, 0xffff0000, v126
	v_pk_fma_f32 v[40:41], v[18:19], v[32:33], v[40:41] op_sel_hi:[1,0,1]
	v_mul_f32_e32 v18, v29, v29
	v_mul_f32_e32 v19, v31, v31
	v_pk_fma_f32 v[36:37], v[26:27], v[32:33], v[36:37] op_sel_hi:[1,0,1]
	v_pk_fma_f32 v[32:33], v[16:17], v[32:33], v[38:39] op_sel_hi:[1,0,1]
	v_mul_f32_e32 v17, v35, v35
	v_fmac_f32_e32 v18, v28, v28
	v_fmac_f32_e32 v19, v30, v30
	v_cvt_pk_bf16_f32 v24, v28, v29
	v_mul_f32_e32 v16, v37, v37
	v_fmac_f32_e32 v17, v34, v34
	v_add_f32_e32 v18, v18, v19
	v_mul_f32_e32 v19, v21, v21
	v_mul_f32_e32 v28, v23, v23
	v_fmac_f32_e32 v16, v36, v36
	v_add_f32_e32 v17, v17, v18
	v_mul_f32_e32 v18, v33, v33
	v_fmac_f32_e32 v19, v20, v20
	v_fmac_f32_e32 v28, v22, v22
	v_add_f32_e32 v16, v16, v17
	v_mul_f32_e32 v17, v41, v41
	v_fmac_f32_e32 v18, v32, v32
	v_add_f32_e32 v19, v19, v28
	v_fmac_f32_e32 v17, v40, v40
	v_add_f32_e32 v18, v18, v19
	v_add_f32_e32 v17, v17, v18
	v_add_f32_e32 v19, v16, v17
	v_cvt_pk_bf16_f32 v25, v30, v31
	ds_bpermute_b32 v30, v112, v19
	v_lshlrev_b64 v[16:17], 11, v[210:211]
	v_lshl_add_u64 v[16:17], s[42:43], 0, v[16:17]
	v_lshl_add_u64 v[28:29], v[204:205], 1, v[16:17]
	v_cvt_pk_bf16_f32 v26, v34, v35
	s_waitcnt lgkmcnt(0)
	v_add_f32_e32 v16, v19, v30
	ds_bpermute_b32 v17, v113, v16
	v_cvt_pk_bf16_f32 v27, v36, v37
	v_cvt_pk_bf16_f32 v18, v20, v21
	v_cvt_pk_bf16_f32 v19, v22, v23
	v_cvt_pk_bf16_f32 v20, v32, v33
	v_cvt_pk_bf16_f32 v21, v40, v41
	global_store_dwordx4 v[28:29], v[24:27], off
	global_store_dwordx4 v[28:29], v[18:21], off offset:256
	s_and_saveexec_b64 s[0:1], vcc
	s_cbranch_execz .LBB0_572
	v_lshl_add_u64 v[18:19], v[210:211], 2, s[60:61]
	s_waitcnt lgkmcnt(0)
	v_add_f32_e32 v16, v16, v17
	global_atomic_add_f32 v[18:19], v16, off
.LBB0_572:
	s_or_b64 exec, exec, s[0:1]
	v_fmamk_f32 v16, v247, 0x3a800000, v245
	v_rcp_f32_e32 v16, v16
	v_lshlrev_b32_e32 v18, 16, v140
	v_and_b32_e32 v19, 0xffff0000, v140
	v_lshlrev_b32_e32 v20, 16, v141
	v_and_b32_e32 v21, 0xffff0000, v141
	v_lshlrev_b32_e32 v24, 16, v137
	v_and_b32_e32 v25, 0xffff0000, v137
	s_waitcnt lgkmcnt(0)
	v_pk_fma_f32 v[14:15], v[14:15], v[16:17], v[20:21] op_sel_hi:[1,0,1]
	v_pk_fma_f32 v[12:13], v[12:13], v[16:17], v[18:19] op_sel_hi:[1,0,1]
	v_lshlrev_b32_e32 v18, 16, v142
	v_and_b32_e32 v19, 0xffff0000, v142
	v_lshlrev_b32_e32 v22, 16, v136
	v_and_b32_e32 v23, 0xffff0000, v136
	v_pk_fma_f32 v[6:7], v[6:7], v[16:17], v[24:25] op_sel_hi:[1,0,1]
	v_lshlrev_b32_e32 v24, 16, v139
	v_and_b32_e32 v25, 0xffff0000, v139
	v_lshlrev_b32_e32 v20, 16, v143
	v_and_b32_e32 v21, 0xffff0000, v143
	v_pk_fma_f32 v[18:19], v[8:9], v[16:17], v[18:19] op_sel_hi:[1,0,1]
	v_pk_fma_f32 v[4:5], v[4:5], v[16:17], v[22:23] op_sel_hi:[1,0,1]
	v_lshlrev_b32_e32 v22, 16, v138
	v_and_b32_e32 v23, 0xffff0000, v138
	v_pk_fma_f32 v[24:25], v[2:3], v[16:17], v[24:25] op_sel_hi:[1,0,1]
	v_mul_f32_e32 v2, v13, v13
	v_mul_f32_e32 v3, v15, v15
	v_pk_fma_f32 v[20:21], v[10:11], v[16:17], v[20:21] op_sel_hi:[1,0,1]
	v_pk_fma_f32 v[16:17], v[0:1], v[16:17], v[22:23] op_sel_hi:[1,0,1]
	v_mul_f32_e32 v1, v19, v19
	v_fmac_f32_e32 v2, v12, v12
	v_fmac_f32_e32 v3, v14, v14
	v_cvt_pk_bf16_f32 v8, v12, v13
	v_mul_f32_e32 v0, v21, v21
	v_fmac_f32_e32 v1, v18, v18
	v_add_f32_e32 v2, v2, v3
	v_mul_f32_e32 v3, v5, v5
	v_mul_f32_e32 v12, v7, v7
	v_fmac_f32_e32 v0, v20, v20
	v_add_f32_e32 v1, v1, v2
	v_mul_f32_e32 v2, v17, v17
	v_fmac_f32_e32 v3, v4, v4
	v_fmac_f32_e32 v12, v6, v6
	v_add_f32_e32 v0, v0, v1
	v_mul_f32_e32 v1, v25, v25
	v_fmac_f32_e32 v2, v16, v16
	v_add_f32_e32 v3, v3, v12
	v_fmac_f32_e32 v1, v24, v24
	v_add_f32_e32 v2, v2, v3
	v_add_f32_e32 v1, v1, v2
	v_add_f32_e32 v3, v0, v1
	v_cvt_pk_bf16_f32 v9, v14, v15
	ds_bpermute_b32 v14, v112, v3
	v_lshlrev_b64 v[0:1], 11, v[206:207]
	v_lshl_add_u64 v[0:1], s[42:43], 0, v[0:1]
	v_lshl_add_u64 v[12:13], v[204:205], 1, v[0:1]
	v_cvt_pk_bf16_f32 v10, v18, v19
	s_waitcnt lgkmcnt(0)
	v_add_f32_e32 v0, v3, v14
	ds_bpermute_b32 v1, v113, v0
	v_cvt_pk_bf16_f32 v11, v20, v21
	v_cvt_pk_bf16_f32 v2, v4, v5
	v_cvt_pk_bf16_f32 v3, v6, v7
	v_cvt_pk_bf16_f32 v4, v16, v17
	v_cvt_pk_bf16_f32 v5, v24, v25
	global_store_dwordx4 v[12:13], v[8:11], off
	global_store_dwordx4 v[12:13], v[2:5], off offset:256
	s_and_saveexec_b64 s[0:1], vcc
	s_cbranch_execz .LBB0_574
	v_lshl_add_u64 v[2:3], v[206:207], 2, s[60:61]
	s_waitcnt lgkmcnt(0)
	v_add_f32_e32 v0, v0, v1
	global_atomic_add_f32 v[2:3], v0, off

; __device__ __forceinline__ u32x4 pack8(f32x4 a, f32x4 b) { u32x4 w; w.x = pk2(a[0], a[1]); w.y = pk2(a[2], a[3]); w.z = pk2(b[0], b[1]); w.w = pk2(b[2], b[3]); return w; }
;     __device__ __forceinline__ void operator()(const Acc& acc, const pg8::Unit& u, int wid) const {
;     ...
; #pragma unroll
;         for (int ai = 0; ai < 2; ++ai)
; #pragma unroll
;             for (int mp = 0; mp < 2; ++mp) {
;                 u32x4 hv[2][2], pw[2][2]; float scv[2];
; #pragma unroll
;                 for (int mm = 0; mm < 2; ++mm) {
;                     const int row = row0 + ai * 128 + (2 * mp + mm) * 16;
;                     scv[mm] = ssq[row];
; #pragma unroll
;                     for (int bj = 0; bj < 2; ++bj) { const size_t off = (size_t)row * 1024 + col0 + bj * 128; hv[mm][bj] = *(const u32x4*)(hbase + off); pw[mm][bj] = *(const u32x4*)(pp + off); }
;                 }
; #pragma unroll
;                 for (int mm = 0; mm < 2; ++mm) {
;                     const int m = 2 * mp + mm, row = row0 + ai * 128 + m * 16; float sq = 0.f;
;                     const float sc = __builtin_amdgcn_rsqf(scv[mm] * (1.f / 1024.f) + EPS);
; #pragma unroll
;                     for (int bj = 0; bj < 2; ++bj) {
;                         const size_t off = (size_t)row * 1024 + col0 + bj * 128;
;                         const u32x4 pwv = pw[mm][bj], hw = hv[mm][bj];
;                         const f32x4 p0 = (f32x4){bflo(pwv.x), bfhi(pwv.x), bflo(pwv.y), bfhi(pwv.y)}, p1 = (f32x4){bflo(pwv.z), bfhi(pwv.z), bflo(pwv.w), bfhi(pwv.w)};
;                         f32x4 g0 = acc[ai][bj][m][0] * sc, g1 = acc[ai][bj][m][1] * sc;
; #pragma unroll
;                         for (int e = 0; e < 4; ++e) { g0[e] = __builtin_amdgcn_rcpf(1.f + __builtin_amdgcn_exp2f(-1.4426950408889634f * g0[e])); g1[e] = __builtin_amdgcn_rcpf(1.f + __builtin_amdgcn_exp2f(-1.4426950408889634f * g1[e])); }
;                         const f32x4 o0 = (f32x4){bflo(hw.x), bfhi(hw.x), bflo(hw.y), bfhi(hw.y)} + g0 * p0;
;                         const f32x4 o1 = (f32x4){bflo(hw.z), bfhi(hw.z), bflo(hw.w), bfhi(hw.w)} + g1 * p1;
;                         if (fout) { *(f32x4*)(fout + off) = o0; *(f32x4*)(fout + off + 4) = o1; }
;                         if (hb_out) *(u32x4*)(hb_out + off) = pack8(o0, o1);
.LBB0_668:
	s_lshl_b32 s4, s10, 8
	s_add_i32 s4, s4, s67
	v_mbcnt_lo_u32_b32 v188, -1, 0
	v_mbcnt_hi_u32_b32 v188, -1, v188
	v_cndmask_b32_e64 v181, 0, 1, s[40:41]
	v_and_or_b32 v172, v188, 15, s4
	v_ashrrev_i32_e32 v173, 31, v172
	v_lshl_add_u64 v[170:171], v[172:173], 2, s[60:61]
	global_load_dword v180, v[170:171], off
	s_lshl_b32 s4, s8, 8
	v_ashrrev_i32_e32 v128, 1, v188
	s_or_b32 s4, s4, s69
	v_and_b32_e32 v128, -8, v128
	v_add_u32_e32 v168, s4, v128
	v_or_b32_e32 v174, 16, v172
	v_ashrrev_i32_e32 v169, 31, v168
	v_lshlrev_b64 v[128:129], 10, v[172:173]
	v_ashrrev_i32_e32 v175, 31, v174
	v_lshl_add_u64 v[178:179], v[128:129], 0, v[168:169]
	v_lshlrev_b64 v[134:135], 10, v[174:175]
	v_lshlrev_b64 v[128:129], 1, v[178:179]
	v_lshl_add_u64 v[176:177], v[134:135], 0, v[168:169]
	v_lshl_add_u64 v[130:131], s[48:49], 0, v[128:129]
	v_lshl_add_u64 v[128:129], s[42:43], 0, v[128:129]
	v_lshl_add_u64 v[132:133], v[174:175], 2, s[60:61]
	v_lshlrev_b64 v[134:135], 1, v[176:177]
	global_load_dwordx4 v[190:193], v[130:131], off
	global_load_dwordx4 v[194:197], v[128:129], off
	global_load_dwordx4 v[144:147], v[128:129], off offset:256
	global_load_dwordx4 v[148:151], v[130:131], off offset:256
	global_load_dword v189, v[132:133], off
	v_lshl_add_u64 v[128:129], s[42:43], 0, v[134:135]
	v_lshl_add_u64 v[132:133], s[48:49], 0, v[134:135]
	global_load_dwordx4 v[136:139], v[128:129], off
	s_nop 0
	global_load_dwordx4 v[128:131], v[128:129], off offset:256
	s_nop 0
	global_load_dwordx4 v[140:143], v[132:133], off
	s_nop 0
	global_load_dwordx4 v[132:135], v[132:133], off offset:256
	v_cmp_ne_u32_e64 s[8:9], 1, v181
	s_andn2_b64 vcc, exec, s[40:41]
	v_lshl_add_u64 v[178:179], v[178:179], 1, s[52:53]
	s_waitcnt vmcnt(0) lgkmcnt(0)
	v_fmamk_f32 v180, v180, 0x3a800000, v186
	v_rsq_f32_e32 v180, v180
	v_lshlrev_b32_e32 v198, 16, v190
	v_pk_mul_f32 v[126:127], v[126:127], v[180:181] op_sel_hi:[1,0]
	v_pk_mul_f32 v[124:125], v[124:125], v[180:181] op_sel_hi:[1,0]
	v_pk_mul_f32 v[122:123], v[122:123], v[180:181] op_sel_hi:[1,0]
	v_pk_mul_f32 v[120:121], v[120:121], v[180:181] op_sel_hi:[1,0]
	v_mul_f32_e32 v124, 0xbfb8aa3b, v124
	v_mul_f32_e32 v120, 0xbfb8aa3b, v120
	v_mul_f32_e32 v125, 0xbfb8aa3b, v125
	v_mul_f32_e32 v121, 0xbfb8aa3b, v121
	v_mul_f32_e32 v126, 0xbfb8aa3b, v126
	v_mul_f32_e32 v122, 0xbfb8aa3b, v122
	v_mul_f32_e32 v127, 0xbfb8aa3b, v127
	v_mul_f32_e32 v123, 0xbfb8aa3b, v123
	v_exp_f32_e32 v124, v124
	v_exp_f32_e32 v120, v120
	v_exp_f32_e32 v125, v125
	v_exp_f32_e32 v121, v121
	v_exp_f32_e32 v126, v126
	v_exp_f32_e32 v122, v122
	v_exp_f32_e32 v127, v127
	v_exp_f32_e32 v123, v123
	v_add_f32_e32 v124, 1.0, v124
	v_add_f32_e32 v181, 1.0, v120
	v_add_f32_e32 v125, 1.0, v125
	v_add_f32_e32 v208, 1.0, v121
	v_add_f32_e32 v126, 1.0, v126
	v_add_f32_e32 v206, 1.0, v122
	v_add_f32_e32 v127, 1.0, v127
	v_add_f32_e32 v123, 1.0, v123
	v_rcp_f32_e32 v120, v124
	v_rcp_f32_e32 v122, v181
	v_rcp_f32_e32 v121, v125
	v_rcp_f32_e32 v124, v126
	v_rcp_f32_e32 v125, v127
	v_rcp_f32_e32 v206, v206
	v_rcp_f32_e32 v207, v123
	v_rcp_f32_e32 v123, v208
	v_and_b32_e32 v199, 0xffff0000, v190
	v_lshlrev_b32_e32 v190, 16, v191
	v_and_b32_e32 v191, 0xffff0000, v191
	v_lshlrev_b32_e32 v200, 16, v192
	v_and_b32_e32 v201, 0xffff0000, v192
	v_lshlrev_b32_e32 v192, 16, v193
	v_and_b32_e32 v193, 0xffff0000, v193
	v_lshlrev_b32_e32 v202, 16, v194
	v_and_b32_e32 v203, 0xffff0000, v194
	v_lshlrev_b32_e32 v194, 16, v195
	v_and_b32_e32 v195, 0xffff0000, v195
	v_lshlrev_b32_e32 v204, 16, v196
	v_and_b32_e32 v205, 0xffff0000, v196
	v_lshlrev_b32_e32 v196, 16, v197
	v_and_b32_e32 v197, 0xffff0000, v197
	v_pk_fma_f32 v[124:125], v[124:125], v[190:191], v[194:195]
	v_pk_fma_f32 v[126:127], v[120:121], v[198:199], v[202:203]
	v_pk_fma_f32 v[120:121], v[206:207], v[192:193], v[196:197]
	v_pk_fma_f32 v[122:123], v[122:123], v[200:201], v[204:205]
	s_cbranch_vccnz .LBB0_670
	v_cvt_pk_bf16_f32 v190, v126, v127
	v_cvt_pk_bf16_f32 v191, v124, v125
	v_cvt_pk_bf16_f32 v192, v122, v123
	v_cvt_pk_bf16_f32 v193, v120, v121
	global_store_dwordx4 v[178:179], v[190:193], off

;     __device__ __forceinline__ void operator()(const Acc& acc, const pg8::Unit& u, int wid) const {
;     ...
;                         sq += (o0[0] * o0[0] + o0[1] * o0[1]) + (o0[2] * o0[2] + o0[3] * o0[3]) + (o1[0] * o1[0] + o1[1] * o1[1]) + (o1[2] * o1[2] + o1[3] * o1[3]);
;                     }
;                     if (ssq_out) { sq += __shfl_xor(sq, 16); sq += __shfl_xor(sq, 32); if (fq == 0) atomicAdd(ssq_out + row, sq); }
.LBB0_672:
	v_mul_f32_e32 v113, v113, v113
	v_fmac_f32_e32 v113, v112, v112
	v_mul_f32_e32 v112, v115, v115
	v_fmac_f32_e32 v112, v114, v114
	v_mul_f32_e32 v127, v127, v127
	v_mul_f32_e32 v125, v125, v125
	v_add_f32_e32 v112, v113, v112
	v_mul_f32_e32 v113, v117, v117
	v_fmac_f32_e32 v127, v126, v126
	v_fmac_f32_e32 v125, v124, v124
	v_mul_f32_e32 v123, v123, v123
	v_fmac_f32_e32 v113, v116, v116
	v_and_b32_e32 v114, 64, v187
	v_add_f32_e32 v124, v127, v125
	v_fmac_f32_e32 v123, v122, v122
	v_mul_f32_e32 v121, v121, v121
	v_mul_f32_e32 v119, v119, v119
	v_add_f32_e32 v112, v113, v112
	v_xor_b32_e32 v113, 16, v187
	v_add_u32_e32 v114, 64, v114
	v_add_f32_e32 v122, v123, v124
	v_fmac_f32_e32 v121, v120, v120
	v_fmac_f32_e32 v119, v118, v118
	v_cmp_lt_i32_e32 vcc, v113, v114
	v_add_f32_e32 v120, v121, v122
	v_add_f32_e32 v112, v119, v112
	v_cndmask_b32_e32 v113, v187, v113, vcc
	v_add_f32_e32 v112, v120, v112
	v_lshlrev_b32_e32 v144, 2, v113
	ds_bpermute_b32 v113, v144, v112
	v_cmp_gt_u32_e64 s[10:11], 16, v188
	s_waitcnt lgkmcnt(0)
	v_add_f32_e32 v112, v112, v113
	v_xor_b32_e32 v113, 32, v187
	v_cmp_lt_i32_e32 vcc, v113, v114
	s_nop 1
	v_cndmask_b32_e32 v113, v187, v113, vcc
	v_lshlrev_b32_e32 v145, 2, v113
	ds_bpermute_b32 v113, v145, v112
	s_and_saveexec_b64 s[28:29], s[10:11]
	s_cbranch_execz .LBB0_674
	v_lshl_add_u64 v[114:115], v[172:173], 2, s[58:59]
	s_waitcnt lgkmcnt(0)
	v_add_f32_e32 v112, v112, v113
	global_atomic_add_f32 v[114:115], v112, off

;     __device__ __forceinline__ void operator()(const Acc& acc, const pg8::Unit& u, int wid) const {
;     ...
;                 for (int mm = 0; mm < 2; ++mm) {
;                     const int row = row0 + ai * 128 + (2 * mp + mm) * 16;
;                     scv[mm] = ssq[row];
; #pragma unroll
;                     for (int bj = 0; bj < 2; ++bj) { const size_t off = (size_t)row * 1024 + col0 + bj * 128; hv[mm][bj] = *(const u32x4*)(hbase + off); pw[mm][bj] = *(const u32x4*)(pp + off); }
;                 }
; #pragma unroll
;                 for (int mm = 0; mm < 2; ++mm) {
;                     const int m = 2 * mp + mm, row = row0 + ai * 128 + m * 16; float sq = 0.f;
;                     const float sc = __builtin_amdgcn_rsqf(scv[mm] * (1.f / 1024.f) + EPS);
; #pragma unroll
;                     for (int bj = 0; bj < 2; ++bj) {
;                         const size_t off = (size_t)row * 1024 + col0 + bj * 128;
;                         const u32x4 pwv = pw[mm][bj], hw = hv[mm][bj];
;                         const f32x4 p0 = (f32x4){bflo(pwv.x), bfhi(pwv.x), bflo(pwv.y), bfhi(pwv.y)}, p1 = (f32x4){bflo(pwv.z), bfhi(pwv.z), bflo(pwv.w), bfhi(pwv.w)};
;                         f32x4 g0 = acc[ai][bj][m][0] * sc, g1 = acc[ai][bj][m][1] * sc;
; #pragma unroll
;                         for (int e = 0; e < 4; ++e) { g0[e] = __builtin_amdgcn_rcpf(1.f + __builtin_amdgcn_exp2f(-1.4426950408889634f * g0[e])); g1[e] = __builtin_amdgcn_rcpf(1.f + __builtin_amdgcn_exp2f(-1.4426950408889634f * g1[e])); }
;                         const f32x4 o0 = (f32x4){bflo(hw.x), bfhi(hw.x), bflo(hw.y), bfhi(hw.y)} + g0 * p0;
;                         const f32x4 o1 = (f32x4){bflo(hw.z), bfhi(hw.z), bflo(hw.w), bfhi(hw.w)} + g1 * p1;
;                         if (fout) { *(f32x4*)(fout + off) = o0; *(f32x4*)(fout + off + 4) = o1; }
;                         if (hb_out) *(u32x4*)(hb_out + off) = pack8(o0, o1);
;                         sq += (o0[0] * o0[0] + o0[1] * o0[1]) + (o0[2] * o0[2] + o0[3] * o0[3]) + (o1[0] * o1[0] + o1[1] * o1[1]) + (o1[2] * o1[2] + o1[3] * o1[3]);
;                     }
;                     if (ssq_out) { sq += __shfl_xor(sq, 16); sq += __shfl_xor(sq, 32); if (fq == 0) atomicAdd(ssq_out + row, sq); }
.LBB0_678:
	v_mul_f32_e32 v107, v107, v107
	v_mul_f32_e32 v105, v105, v105
	v_mul_f32_e32 v97, v97, v97
	v_fmac_f32_e32 v107, v106, v106
	v_fmac_f32_e32 v105, v104, v104
	v_fmac_f32_e32 v97, v96, v96
	v_mul_f32_e32 v96, v99, v99
	v_add_f32_e32 v104, v107, v105
	v_mul_f32_e32 v105, v111, v111
	v_fmac_f32_e32 v96, v98, v98
	v_fmac_f32_e32 v105, v110, v110
	v_add_f32_e32 v96, v97, v96
	v_mul_f32_e32 v97, v101, v101
	v_add_f32_e32 v104, v105, v104
	v_mul_f32_e32 v105, v109, v109
	v_mul_f32_e32 v103, v103, v103
	v_fmac_f32_e32 v97, v100, v100
	v_fmac_f32_e32 v105, v108, v108
	v_fmac_f32_e32 v103, v102, v102
	v_add_f32_e32 v96, v97, v96
	v_add_f32_e32 v104, v105, v104
	v_add_f32_e32 v96, v103, v96
	v_add_f32_e32 v96, v104, v96
	ds_bpermute_b32 v97, v144, v96
	s_waitcnt lgkmcnt(0)
	v_add_f32_e32 v96, v96, v97
	ds_bpermute_b32 v97, v145, v96
	s_and_saveexec_b64 s[28:29], s[10:11]
	s_cbranch_execz .LBB0_680
	v_lshl_add_u64 v[98:99], v[174:175], 2, s[58:59]
	s_waitcnt lgkmcnt(0)
	v_add_f32_e32 v96, v96, v97
	global_atomic_add_f32 v[98:99], v96, off
.LBB0_680:
	s_or_b64 exec, exec, s[28:29]
	v_or_b32_e32 v124, 32, v172
	v_ashrrev_i32_e32 v125, 31, v124
	s_waitcnt lgkmcnt(0)
	v_lshl_add_u64 v[96:97], v[124:125], 2, s[60:61]
	global_load_dword v128, v[96:97], off
	v_or_b32_e32 v120, 48, v172
	v_ashrrev_i32_e32 v121, 31, v120
	v_lshlrev_b64 v[96:97], 10, v[124:125]
	v_lshlrev_b64 v[102:103], 10, v[120:121]
	v_lshl_add_u64 v[126:127], v[96:97], 0, v[168:169]
	v_lshl_add_u64 v[122:123], v[102:103], 0, v[168:169]
	v_lshlrev_b64 v[96:97], 1, v[126:127]
	v_lshlrev_b64 v[102:103], 1, v[122:123]
	v_lshl_add_u64 v[98:99], s[48:49], 0, v[96:97]
	v_lshl_add_u64 v[96:97], s[42:43], 0, v[96:97]
	v_lshl_add_u64 v[100:101], v[120:121], 2, s[60:61]
	v_lshl_add_u64 v[108:109], s[42:43], 0, v[102:103]
	v_lshl_add_u64 v[102:103], s[48:49], 0, v[102:103]
	global_load_dwordx4 v[132:135], v[98:99], off
	global_load_dwordx4 v[136:139], v[96:97], off
	global_load_dwordx4 v[112:115], v[96:97], off offset:256
	global_load_dwordx4 v[116:119], v[98:99], off offset:256
	global_load_dword v130, v[100:101], off
	global_load_dwordx4 v[104:107], v[108:109], off
	s_nop 0
	global_load_dwordx4 v[96:99], v[108:109], off offset:256
	s_nop 0
	global_load_dwordx4 v[108:111], v[102:103], off
	s_nop 0
	global_load_dwordx4 v[100:103], v[102:103], off offset:256
	s_and_b64 vcc, exec, s[8:9]
	v_lshl_add_u64 v[126:127], v[126:127], 1, s[52:53]
	s_waitcnt vmcnt(0) lgkmcnt(0)
	v_fmamk_f32 v128, v128, 0x3a800000, v186
	v_rsq_f32_e32 v128, v128
	v_lshlrev_b32_e32 v140, 16, v132
	v_pk_mul_f32 v[94:95], v[94:95], v[128:129] op_sel_hi:[1,0]
	v_pk_mul_f32 v[92:93], v[92:93], v[128:129] op_sel_hi:[1,0]
	v_pk_mul_f32 v[90:91], v[90:91], v[128:129] op_sel_hi:[1,0]
	v_pk_mul_f32 v[88:89], v[88:89], v[128:129] op_sel_hi:[1,0]
	v_mul_f32_e32 v92, 0xbfb8aa3b, v92
	v_mul_f32_e32 v88, 0xbfb8aa3b, v88
	v_mul_f32_e32 v93, 0xbfb8aa3b, v93
	v_mul_f32_e32 v89, 0xbfb8aa3b, v89
	v_mul_f32_e32 v94, 0xbfb8aa3b, v94
	v_mul_f32_e32 v90, 0xbfb8aa3b, v90
	v_mul_f32_e32 v95, 0xbfb8aa3b, v95
	v_mul_f32_e32 v91, 0xbfb8aa3b, v91
	v_exp_f32_e32 v92, v92
	v_exp_f32_e32 v88, v88
	v_exp_f32_e32 v93, v93
	v_exp_f32_e32 v89, v89
	v_exp_f32_e32 v94, v94
	v_exp_f32_e32 v90, v90
	v_exp_f32_e32 v95, v95
	v_exp_f32_e32 v91, v91
	v_add_f32_e32 v92, 1.0, v92
	v_add_f32_e32 v129, 1.0, v88
	v_add_f32_e32 v93, 1.0, v93
	v_add_f32_e32 v131, 1.0, v89
	v_add_f32_e32 v94, 1.0, v94
	v_add_f32_e32 v150, 1.0, v90
	v_add_f32_e32 v95, 1.0, v95
	v_add_f32_e32 v91, 1.0, v91
	v_rcp_f32_e32 v88, v92
	v_rcp_f32_e32 v90, v129
	v_rcp_f32_e32 v89, v93
	v_rcp_f32_e32 v92, v94
	v_rcp_f32_e32 v93, v95
	v_rcp_f32_e32 v150, v150
	v_rcp_f32_e32 v151, v91
	v_rcp_f32_e32 v91, v131
	v_and_b32_e32 v141, 0xffff0000, v132
	v_lshlrev_b32_e32 v132, 16, v133
	v_and_b32_e32 v133, 0xffff0000, v133
	v_lshlrev_b32_e32 v142, 16, v134
	v_and_b32_e32 v143, 0xffff0000, v134
	v_lshlrev_b32_e32 v134, 16, v135
	v_and_b32_e32 v135, 0xffff0000, v135
	v_lshlrev_b32_e32 v146, 16, v136
	v_and_b32_e32 v147, 0xffff0000, v136
	v_lshlrev_b32_e32 v136, 16, v137
	v_and_b32_e32 v137, 0xffff0000, v137
	v_lshlrev_b32_e32 v148, 16, v138
	v_and_b32_e32 v149, 0xffff0000, v138
	v_lshlrev_b32_e32 v138, 16, v139
	v_and_b32_e32 v139, 0xffff0000, v139
	v_pk_fma_f32 v[92:93], v[92:93], v[132:133], v[136:137]
	v_pk_fma_f32 v[94:95], v[88:89], v[140:141], v[146:147]
	v_pk_fma_f32 v[88:89], v[150:151], v[134:135], v[138:139]
	v_pk_fma_f32 v[90:91], v[90:91], v[142:143], v[148:149]
	s_cbranch_vccnz .LBB0_682
	v_cvt_pk_bf16_f32 v132, v94, v95
	v_cvt_pk_bf16_f32 v133, v92, v93
	v_cvt_pk_bf16_f32 v134, v90, v91
	v_cvt_pk_bf16_f32 v135, v88, v89
	global_store_dwordx4 v[126:127], v[132:135], off

;     __device__ __forceinline__ void operator()(const Acc& acc, const pg8::Unit& u, int wid) const {
;     ...
;                         sq += (o0[0] * o0[0] + o0[1] * o0[1]) + (o0[2] * o0[2] + o0[3] * o0[3]) + (o1[0] * o1[0] + o1[1] * o1[1]) + (o1[2] * o1[2] + o1[3] * o1[3]);
;                     }
;                     if (ssq_out) { sq += __shfl_xor(sq, 16); sq += __shfl_xor(sq, 32); if (fq == 0) atomicAdd(ssq_out + row, sq); }
.LBB0_684:
	v_mul_f32_e32 v81, v81, v81
	v_fmac_f32_e32 v81, v80, v80
	v_mul_f32_e32 v80, v83, v83
	v_mul_f32_e32 v95, v95, v95
	v_mul_f32_e32 v93, v93, v93
	v_fmac_f32_e32 v80, v82, v82
	v_fmac_f32_e32 v95, v94, v94
	v_fmac_f32_e32 v93, v92, v92
	v_mul_f32_e32 v91, v91, v91
	v_add_f32_e32 v80, v81, v80
	v_mul_f32_e32 v81, v85, v85
	v_add_f32_e32 v92, v95, v93
	v_fmac_f32_e32 v91, v90, v90
	v_mul_f32_e32 v89, v89, v89
	v_mul_f32_e32 v87, v87, v87
	v_fmac_f32_e32 v81, v84, v84
	v_add_f32_e32 v90, v91, v92
	v_fmac_f32_e32 v89, v88, v88
	v_fmac_f32_e32 v87, v86, v86
	v_add_f32_e32 v80, v81, v80
	v_add_f32_e32 v88, v89, v90
	v_add_f32_e32 v80, v87, v80
	v_add_f32_e32 v80, v88, v80
	ds_bpermute_b32 v81, v144, v80
	s_waitcnt lgkmcnt(0)
	v_add_f32_e32 v80, v80, v81
	ds_bpermute_b32 v81, v145, v80
	s_and_saveexec_b64 s[28:29], s[10:11]
	s_cbranch_execz .LBB0_686
	v_lshl_add_u64 v[82:83], v[124:125], 2, s[58:59]
	s_waitcnt lgkmcnt(0)
	v_add_f32_e32 v80, v80, v81
	global_atomic_add_f32 v[82:83], v80, off

;     __device__ __forceinline__ void operator()(const Acc& acc, const pg8::Unit& u, int wid) const {
;     ...
;                 for (int mm = 0; mm < 2; ++mm) {
;                     const int row = row0 + ai * 128 + (2 * mp + mm) * 16;
;                     scv[mm] = ssq[row];
; #pragma unroll
;                     for (int bj = 0; bj < 2; ++bj) { const size_t off = (size_t)row * 1024 + col0 + bj * 128; hv[mm][bj] = *(const u32x4*)(hbase + off); pw[mm][bj] = *(const u32x4*)(pp + off); }
;                 }
; #pragma unroll
;                 for (int mm = 0; mm < 2; ++mm) {
;                     const int m = 2 * mp + mm, row = row0 + ai * 128 + m * 16; float sq = 0.f;
;                     const float sc = __builtin_amdgcn_rsqf(scv[mm] * (1.f / 1024.f) + EPS);
; #pragma unroll
;                     for (int bj = 0; bj < 2; ++bj) {
;                         const size_t off = (size_t)row * 1024 + col0 + bj * 128;
;                         const u32x4 pwv = pw[mm][bj], hw = hv[mm][bj];
;                         const f32x4 p0 = (f32x4){bflo(pwv.x), bfhi(pwv.x), bflo(pwv.y), bfhi(pwv.y)}, p1 = (f32x4){bflo(pwv.z), bfhi(pwv.z), bflo(pwv.w), bfhi(pwv.w)};
;                         f32x4 g0 = acc[ai][bj][m][0] * sc, g1 = acc[ai][bj][m][1] * sc;
; #pragma unroll
;                         for (int e = 0; e < 4; ++e) { g0[e] = __builtin_amdgcn_rcpf(1.f + __builtin_amdgcn_exp2f(-1.4426950408889634f * g0[e])); g1[e] = __builtin_amdgcn_rcpf(1.f + __builtin_amdgcn_exp2f(-1.4426950408889634f * g1[e])); }
;                         const f32x4 o0 = (f32x4){bflo(hw.x), bfhi(hw.x), bflo(hw.y), bfhi(hw.y)} + g0 * p0;
;                         const f32x4 o1 = (f32x4){bflo(hw.z), bfhi(hw.z), bflo(hw.w), bfhi(hw.w)} + g1 * p1;
;                         if (fout) { *(f32x4*)(fout + off) = o0; *(f32x4*)(fout + off + 4) = o1; }
;                         if (hb_out) *(u32x4*)(hb_out + off) = pack8(o0, o1);
;                         sq += (o0[0] * o0[0] + o0[1] * o0[1]) + (o0[2] * o0[2] + o0[3] * o0[3]) + (o1[0] * o1[0] + o1[1] * o1[1]) + (o1[2] * o1[2] + o1[3] * o1[3]);
;                     }
;                     if (ssq_out) { sq += __shfl_xor(sq, 16); sq += __shfl_xor(sq, 32); if (fq == 0) atomicAdd(ssq_out + row, sq); }
.LBB0_690:
	v_mul_f32_e32 v75, v75, v75
	v_mul_f32_e32 v73, v73, v73
	v_mul_f32_e32 v65, v65, v65
	v_fmac_f32_e32 v75, v74, v74
	v_fmac_f32_e32 v73, v72, v72
	v_fmac_f32_e32 v65, v64, v64
	v_mul_f32_e32 v64, v67, v67
	v_add_f32_e32 v72, v75, v73
	v_mul_f32_e32 v73, v79, v79
	v_fmac_f32_e32 v64, v66, v66
	v_fmac_f32_e32 v73, v78, v78
	v_add_f32_e32 v64, v65, v64
	v_mul_f32_e32 v65, v69, v69
	v_add_f32_e32 v72, v73, v72
	v_mul_f32_e32 v73, v77, v77
	v_mul_f32_e32 v71, v71, v71
	v_fmac_f32_e32 v65, v68, v68
	v_fmac_f32_e32 v73, v76, v76
	v_fmac_f32_e32 v71, v70, v70
	v_add_f32_e32 v64, v65, v64
	v_add_f32_e32 v72, v73, v72
	v_add_f32_e32 v64, v71, v64
	v_add_f32_e32 v64, v72, v64
	ds_bpermute_b32 v65, v144, v64
	s_waitcnt lgkmcnt(0)
	v_add_f32_e32 v64, v64, v65
	ds_bpermute_b32 v65, v145, v64
	s_and_saveexec_b64 s[28:29], s[10:11]
	s_cbranch_execz .LBB0_692
	v_lshl_add_u64 v[66:67], v[120:121], 2, s[58:59]
	s_waitcnt lgkmcnt(0)
	v_add_f32_e32 v64, v64, v65
	global_atomic_add_f32 v[66:67], v64, off
.LBB0_692:
	s_or_b64 exec, exec, s[28:29]
	global_load_dword v94, v[170:171], off offset:512
	v_add_u32_e32 v92, 0x80, v172
	v_add_u32_e32 v88, 0x90, v172
	v_ashrrev_i32_e32 v93, 31, v92
	v_ashrrev_i32_e32 v89, 31, v88
	s_waitcnt lgkmcnt(0)
	v_lshlrev_b64 v[64:65], 10, v[92:93]
	v_lshlrev_b64 v[68:69], 10, v[88:89]
	v_lshl_add_u64 v[96:97], v[64:65], 0, v[168:169]
	v_lshl_add_u64 v[90:91], v[68:69], 0, v[168:169]
	v_lshlrev_b64 v[64:65], 1, v[96:97]
	v_lshlrev_b64 v[68:69], 1, v[90:91]
	v_lshl_add_u64 v[66:67], s[48:49], 0, v[64:65]
	v_lshl_add_u64 v[64:65], s[42:43], 0, v[64:65]
	v_lshl_add_u64 v[70:71], s[42:43], 0, v[68:69]
	v_lshl_add_u64 v[68:69], s[48:49], 0, v[68:69]
	global_load_dwordx4 v[100:103], v[66:67], off
	global_load_dwordx4 v[104:107], v[64:65], off
	global_load_dwordx4 v[80:83], v[64:65], off offset:256
	global_load_dword v98, v[170:171], off offset:576
	global_load_dwordx4 v[84:87], v[66:67], off offset:256
	global_load_dwordx4 v[72:75], v[70:71], off
	global_load_dwordx4 v[76:79], v[68:69], off
	s_nop 0
	global_load_dwordx4 v[64:67], v[70:71], off offset:256
	s_nop 0
	global_load_dwordx4 v[68:71], v[68:69], off offset:256
	s_and_b64 vcc, exec, s[8:9]
	v_lshl_add_u64 v[96:97], v[96:97], 1, s[52:53]
	s_waitcnt vmcnt(0)
	v_fmamk_f32 v94, v94, 0x3a800000, v186
	v_rsq_f32_e32 v94, v94
	s_waitcnt lgkmcnt(0)
	v_lshlrev_b32_e32 v108, 16, v100
	v_pk_mul_f32 v[62:63], v[62:63], v[94:95] op_sel_hi:[1,0]
	v_pk_mul_f32 v[60:61], v[60:61], v[94:95] op_sel_hi:[1,0]
	v_pk_mul_f32 v[58:59], v[58:59], v[94:95] op_sel_hi:[1,0]
	v_pk_mul_f32 v[56:57], v[56:57], v[94:95] op_sel_hi:[1,0]
	v_mul_f32_e32 v60, 0xbfb8aa3b, v60
	v_mul_f32_e32 v95, 0xbfb8aa3b, v56
	v_mul_f32_e32 v61, 0xbfb8aa3b, v61
	v_mul_f32_e32 v99, 0xbfb8aa3b, v57
	v_mul_f32_e32 v62, 0xbfb8aa3b, v62
	v_mul_f32_e32 v112, 0xbfb8aa3b, v58
	v_mul_f32_e32 v63, 0xbfb8aa3b, v63
	v_mul_f32_e32 v113, 0xbfb8aa3b, v59
	v_exp_f32_e32 v60, v60
	v_exp_f32_e32 v95, v95
	v_exp_f32_e32 v61, v61
	v_exp_f32_e32 v99, v99
	v_exp_f32_e32 v62, v62
	v_exp_f32_e32 v112, v112
	v_exp_f32_e32 v63, v63
	v_exp_f32_e32 v113, v113
	v_add_f32_e32 v60, 1.0, v60
	v_add_f32_e32 v95, 1.0, v95
	v_add_f32_e32 v61, 1.0, v61
	v_add_f32_e32 v99, 1.0, v99
	v_add_f32_e32 v114, 1.0, v62
	v_add_f32_e32 v115, 1.0, v112
	v_add_f32_e32 v116, 1.0, v63
	v_add_f32_e32 v113, 1.0, v113
	v_rcp_f32_e32 v62, v60
	v_rcp_f32_e32 v112, v95
	v_rcp_f32_e32 v63, v61
	v_rcp_f32_e32 v60, v114
	v_rcp_f32_e32 v61, v116
	v_rcp_f32_e32 v114, v115
	v_rcp_f32_e32 v115, v113
	v_rcp_f32_e32 v113, v99
	v_and_b32_e32 v109, 0xffff0000, v100
	v_lshlrev_b32_e32 v100, 16, v101
	v_and_b32_e32 v101, 0xffff0000, v101
	v_lshlrev_b32_e32 v110, 16, v102
	v_and_b32_e32 v111, 0xffff0000, v102
	v_lshlrev_b32_e32 v102, 16, v103
	v_and_b32_e32 v103, 0xffff0000, v103
	v_lshlrev_b32_e32 v56, 16, v104
	v_and_b32_e32 v57, 0xffff0000, v104
	v_lshlrev_b32_e32 v58, 16, v105
	v_and_b32_e32 v59, 0xffff0000, v105
	v_lshlrev_b32_e32 v104, 16, v106
	v_and_b32_e32 v105, 0xffff0000, v106
	v_lshlrev_b32_e32 v106, 16, v107
	v_and_b32_e32 v107, 0xffff0000, v107
	v_pk_fma_f32 v[60:61], v[60:61], v[100:101], v[58:59]
	v_pk_fma_f32 v[62:63], v[62:63], v[108:109], v[56:57]
	v_pk_fma_f32 v[56:57], v[114:115], v[102:103], v[106:107]
	v_pk_fma_f32 v[58:59], v[112:113], v[110:111], v[104:105]
	s_cbranch_vccnz .LBB0_694
	v_cvt_pk_bf16_f32 v100, v62, v63
	v_cvt_pk_bf16_f32 v101, v60, v61
	v_cvt_pk_bf16_f32 v102, v58, v59
	v_cvt_pk_bf16_f32 v103, v56, v57
	global_store_dwordx4 v[96:97], v[100:103], off

;     __device__ __forceinline__ void operator()(const Acc& acc, const pg8::Unit& u, int wid) const {
;     ...
;                         sq += (o0[0] * o0[0] + o0[1] * o0[1]) + (o0[2] * o0[2] + o0[3] * o0[3]) + (o1[0] * o1[0] + o1[1] * o1[1]) + (o1[2] * o1[2] + o1[3] * o1[3]);
;                     }
;                     if (ssq_out) { sq += __shfl_xor(sq, 16); sq += __shfl_xor(sq, 32); if (fq == 0) atomicAdd(ssq_out + row, sq); }
.LBB0_696:
	v_mul_f32_e32 v49, v49, v49
	v_fmac_f32_e32 v49, v48, v48
	v_mul_f32_e32 v48, v51, v51
	v_mul_f32_e32 v63, v63, v63
	v_mul_f32_e32 v61, v61, v61
	v_fmac_f32_e32 v48, v50, v50
	v_fmac_f32_e32 v63, v62, v62
	v_fmac_f32_e32 v61, v60, v60
	v_mul_f32_e32 v59, v59, v59
	v_add_f32_e32 v48, v49, v48
	v_mul_f32_e32 v49, v53, v53
	v_add_f32_e32 v60, v63, v61
	v_fmac_f32_e32 v59, v58, v58
	v_mul_f32_e32 v57, v57, v57
	v_mul_f32_e32 v55, v55, v55
	v_fmac_f32_e32 v49, v52, v52
	v_add_f32_e32 v58, v59, v60
	v_fmac_f32_e32 v57, v56, v56
	v_fmac_f32_e32 v55, v54, v54
	v_add_f32_e32 v48, v49, v48
	v_add_f32_e32 v56, v57, v58
	v_add_f32_e32 v48, v55, v48
	v_add_f32_e32 v48, v56, v48
	ds_bpermute_b32 v49, v144, v48
	s_waitcnt lgkmcnt(0)
	v_add_f32_e32 v48, v48, v49
	ds_bpermute_b32 v49, v145, v48
	s_and_saveexec_b64 s[28:29], s[10:11]
	s_cbranch_execz .LBB0_698
	v_lshl_add_u64 v[50:51], v[92:93], 2, s[58:59]
	s_waitcnt lgkmcnt(0)
	v_add_f32_e32 v48, v48, v49
	global_atomic_add_f32 v[50:51], v48, off

;     __device__ __forceinline__ void operator()(const Acc& acc, const pg8::Unit& u, int wid) const {
;     ...
;                 for (int mm = 0; mm < 2; ++mm) {
;                     const int row = row0 + ai * 128 + (2 * mp + mm) * 16;
;                     scv[mm] = ssq[row];
; #pragma unroll
;                     for (int bj = 0; bj < 2; ++bj) { const size_t off = (size_t)row * 1024 + col0 + bj * 128; hv[mm][bj] = *(const u32x4*)(hbase + off); pw[mm][bj] = *(const u32x4*)(pp + off); }
;                 }
; #pragma unroll
;                 for (int mm = 0; mm < 2; ++mm) {
;                     const int m = 2 * mp + mm, row = row0 + ai * 128 + m * 16; float sq = 0.f;
;                     const float sc = __builtin_amdgcn_rsqf(scv[mm] * (1.f / 1024.f) + EPS);
; #pragma unroll
;                     for (int bj = 0; bj < 2; ++bj) {
;                         const size_t off = (size_t)row * 1024 + col0 + bj * 128;
;                         const u32x4 pwv = pw[mm][bj], hw = hv[mm][bj];
;                         const f32x4 p0 = (f32x4){bflo(pwv.x), bfhi(pwv.x), bflo(pwv.y), bfhi(pwv.y)}, p1 = (f32x4){bflo(pwv.z), bfhi(pwv.z), bflo(pwv.w), bfhi(pwv.w)};
;                         f32x4 g0 = acc[ai][bj][m][0] * sc, g1 = acc[ai][bj][m][1] * sc;
; #pragma unroll
;                         for (int e = 0; e < 4; ++e) { g0[e] = __builtin_amdgcn_rcpf(1.f + __builtin_amdgcn_exp2f(-1.4426950408889634f * g0[e])); g1[e] = __builtin_amdgcn_rcpf(1.f + __builtin_amdgcn_exp2f(-1.4426950408889634f * g1[e])); }
;                         const f32x4 o0 = (f32x4){bflo(hw.x), bfhi(hw.x), bflo(hw.y), bfhi(hw.y)} + g0 * p0;
;                         const f32x4 o1 = (f32x4){bflo(hw.z), bfhi(hw.z), bflo(hw.w), bfhi(hw.w)} + g1 * p1;
;                         if (fout) { *(f32x4*)(fout + off) = o0; *(f32x4*)(fout + off + 4) = o1; }
;                         if (hb_out) *(u32x4*)(hb_out + off) = pack8(o0, o1);
;                         sq += (o0[0] * o0[0] + o0[1] * o0[1]) + (o0[2] * o0[2] + o0[3] * o0[3]) + (o1[0] * o1[0] + o1[1] * o1[1]) + (o1[2] * o1[2] + o1[3] * o1[3]);
;                     }
;                     if (ssq_out) { sq += __shfl_xor(sq, 16); sq += __shfl_xor(sq, 32); if (fq == 0) atomicAdd(ssq_out + row, sq); }
.LBB0_702:
	v_mul_f32_e32 v43, v43, v43
	v_mul_f32_e32 v41, v41, v41
	v_mul_f32_e32 v33, v33, v33
	v_fmac_f32_e32 v43, v42, v42
	v_fmac_f32_e32 v41, v40, v40
	v_fmac_f32_e32 v33, v32, v32
	v_mul_f32_e32 v32, v35, v35
	v_add_f32_e32 v40, v43, v41
	v_mul_f32_e32 v41, v47, v47
	v_fmac_f32_e32 v32, v34, v34
	v_fmac_f32_e32 v41, v46, v46
	v_add_f32_e32 v32, v33, v32
	v_mul_f32_e32 v33, v37, v37
	v_add_f32_e32 v40, v41, v40
	v_mul_f32_e32 v41, v45, v45
	v_mul_f32_e32 v39, v39, v39
	v_fmac_f32_e32 v33, v36, v36
	v_fmac_f32_e32 v41, v44, v44
	v_fmac_f32_e32 v39, v38, v38
	v_add_f32_e32 v32, v33, v32
	v_add_f32_e32 v40, v41, v40
	v_add_f32_e32 v32, v39, v32
	v_add_f32_e32 v32, v40, v32
	ds_bpermute_b32 v33, v144, v32
	s_waitcnt lgkmcnt(0)
	v_add_f32_e32 v32, v32, v33
	ds_bpermute_b32 v33, v145, v32
	s_and_saveexec_b64 s[28:29], s[10:11]
	s_cbranch_execz .LBB0_704
	v_lshl_add_u64 v[34:35], v[88:89], 2, s[58:59]
	s_waitcnt lgkmcnt(0)
	v_add_f32_e32 v32, v32, v33
	global_atomic_add_f32 v[34:35], v32, off
.LBB0_704:
	s_or_b64 exec, exec, s[28:29]
	global_load_dword v62, v[170:171], off offset:640
	v_add_u32_e32 v60, 0xa0, v172
	v_add_u32_e32 v56, 0xb0, v172
	v_ashrrev_i32_e32 v61, 31, v60
	v_ashrrev_i32_e32 v57, 31, v56
	s_waitcnt lgkmcnt(0)
	v_lshlrev_b64 v[32:33], 10, v[60:61]
	v_lshlrev_b64 v[36:37], 10, v[56:57]
	v_lshl_add_u64 v[64:65], v[32:33], 0, v[168:169]
	v_lshl_add_u64 v[58:59], v[36:37], 0, v[168:169]
	v_lshlrev_b64 v[32:33], 1, v[64:65]
	v_lshlrev_b64 v[36:37], 1, v[58:59]
	v_lshl_add_u64 v[34:35], s[48:49], 0, v[32:33]
	v_lshl_add_u64 v[32:33], s[42:43], 0, v[32:33]
	v_lshl_add_u64 v[38:39], s[42:43], 0, v[36:37]
	v_lshl_add_u64 v[36:37], s[48:49], 0, v[36:37]
	global_load_dwordx4 v[68:71], v[34:35], off
	global_load_dwordx4 v[72:75], v[32:33], off
	global_load_dwordx4 v[48:51], v[32:33], off offset:256
	global_load_dword v66, v[170:171], off offset:704
	global_load_dwordx4 v[52:55], v[34:35], off offset:256
	global_load_dwordx4 v[40:43], v[38:39], off
	global_load_dwordx4 v[44:47], v[36:37], off
	s_nop 0
	global_load_dwordx4 v[32:35], v[38:39], off offset:256
	s_nop 0
	global_load_dwordx4 v[36:39], v[36:37], off offset:256
	s_and_b64 vcc, exec, s[8:9]
	v_lshl_add_u64 v[64:65], v[64:65], 1, s[52:53]
	s_waitcnt vmcnt(0)
	v_fmamk_f32 v62, v62, 0x3a800000, v186
	v_rsq_f32_e32 v62, v62
	s_waitcnt lgkmcnt(0)
	v_lshlrev_b32_e32 v76, 16, v68
	v_pk_mul_f32 v[30:31], v[30:31], v[62:63] op_sel_hi:[1,0]
	v_pk_mul_f32 v[28:29], v[28:29], v[62:63] op_sel_hi:[1,0]
	v_pk_mul_f32 v[26:27], v[26:27], v[62:63] op_sel_hi:[1,0]
	v_pk_mul_f32 v[24:25], v[24:25], v[62:63] op_sel_hi:[1,0]
	v_mul_f32_e32 v28, 0xbfb8aa3b, v28
	v_mul_f32_e32 v63, 0xbfb8aa3b, v24
	v_mul_f32_e32 v29, 0xbfb8aa3b, v29
	v_mul_f32_e32 v67, 0xbfb8aa3b, v25
	v_mul_f32_e32 v30, 0xbfb8aa3b, v30
	v_mul_f32_e32 v80, 0xbfb8aa3b, v26
	v_mul_f32_e32 v31, 0xbfb8aa3b, v31
	v_mul_f32_e32 v81, 0xbfb8aa3b, v27
	v_exp_f32_e32 v28, v28
	v_exp_f32_e32 v63, v63
	v_exp_f32_e32 v29, v29
	v_exp_f32_e32 v67, v67
	v_exp_f32_e32 v30, v30
	v_exp_f32_e32 v80, v80
	v_exp_f32_e32 v31, v31
	v_exp_f32_e32 v81, v81
	v_add_f32_e32 v28, 1.0, v28
	v_add_f32_e32 v63, 1.0, v63
	v_add_f32_e32 v29, 1.0, v29
	v_add_f32_e32 v67, 1.0, v67
	v_add_f32_e32 v82, 1.0, v30
	v_add_f32_e32 v83, 1.0, v80
	v_add_f32_e32 v84, 1.0, v31
	v_add_f32_e32 v81, 1.0, v81
	v_rcp_f32_e32 v30, v28
	v_rcp_f32_e32 v80, v63
	v_rcp_f32_e32 v31, v29
	v_rcp_f32_e32 v28, v82
	v_rcp_f32_e32 v29, v84
	v_rcp_f32_e32 v82, v83
	v_rcp_f32_e32 v83, v81
	v_rcp_f32_e32 v81, v67
	v_and_b32_e32 v77, 0xffff0000, v68
	v_lshlrev_b32_e32 v68, 16, v69
	v_and_b32_e32 v69, 0xffff0000, v69
	v_lshlrev_b32_e32 v78, 16, v70
	v_and_b32_e32 v79, 0xffff0000, v70
	v_lshlrev_b32_e32 v70, 16, v71
	v_and_b32_e32 v71, 0xffff0000, v71
	v_lshlrev_b32_e32 v24, 16, v72
	v_and_b32_e32 v25, 0xffff0000, v72
	v_lshlrev_b32_e32 v26, 16, v73
	v_and_b32_e32 v27, 0xffff0000, v73
	v_lshlrev_b32_e32 v72, 16, v74
	v_and_b32_e32 v73, 0xffff0000, v74
	v_lshlrev_b32_e32 v74, 16, v75
	v_and_b32_e32 v75, 0xffff0000, v75
	v_pk_fma_f32 v[28:29], v[28:29], v[68:69], v[26:27]
	v_pk_fma_f32 v[30:31], v[30:31], v[76:77], v[24:25]
	v_pk_fma_f32 v[24:25], v[82:83], v[70:71], v[74:75]
	v_pk_fma_f32 v[26:27], v[80:81], v[78:79], v[72:73]
	s_cbranch_vccnz .LBB0_706
	v_cvt_pk_bf16_f32 v68, v30, v31
	v_cvt_pk_bf16_f32 v69, v28, v29
	v_cvt_pk_bf16_f32 v70, v26, v27
	v_cvt_pk_bf16_f32 v71, v24, v25
	global_store_dwordx4 v[64:65], v[68:71], off

;     __device__ __forceinline__ void operator()(const Acc& acc, const pg8::Unit& u, int wid) const {
;     ...
;                         sq += (o0[0] * o0[0] + o0[1] * o0[1]) + (o0[2] * o0[2] + o0[3] * o0[3]) + (o1[0] * o1[0] + o1[1] * o1[1]) + (o1[2] * o1[2] + o1[3] * o1[3]);
;                     }
;                     if (ssq_out) { sq += __shfl_xor(sq, 16); sq += __shfl_xor(sq, 32); if (fq == 0) atomicAdd(ssq_out + row, sq); }
.LBB0_708:
	v_mul_f32_e32 v17, v17, v17
	v_fmac_f32_e32 v17, v16, v16
	v_mul_f32_e32 v16, v19, v19
	v_mul_f32_e32 v31, v31, v31
	v_mul_f32_e32 v29, v29, v29
	v_fmac_f32_e32 v16, v18, v18
	v_fmac_f32_e32 v31, v30, v30
	v_fmac_f32_e32 v29, v28, v28
	v_mul_f32_e32 v27, v27, v27
	v_add_f32_e32 v16, v17, v16
	v_mul_f32_e32 v17, v21, v21
	v_add_f32_e32 v28, v31, v29
	v_fmac_f32_e32 v27, v26, v26
	v_mul_f32_e32 v25, v25, v25
	v_mul_f32_e32 v23, v23, v23
	v_fmac_f32_e32 v17, v20, v20
	v_add_f32_e32 v26, v27, v28
	v_fmac_f32_e32 v25, v24, v24
	v_fmac_f32_e32 v23, v22, v22
	v_add_f32_e32 v16, v17, v16
	v_add_f32_e32 v24, v25, v26
	v_add_f32_e32 v16, v23, v16
	v_add_f32_e32 v16, v24, v16
	ds_bpermute_b32 v17, v144, v16
	s_waitcnt lgkmcnt(0)
	v_add_f32_e32 v16, v16, v17
	ds_bpermute_b32 v17, v145, v16
	s_and_saveexec_b64 s[28:29], s[10:11]
	s_cbranch_execz .LBB0_710
	v_lshl_add_u64 v[18:19], v[60:61], 2, s[58:59]
	s_waitcnt lgkmcnt(0)
	v_add_f32_e32 v16, v16, v17
	global_atomic_add_f32 v[18:19], v16, off

;     __device__ __forceinline__ void operator()(const Acc& acc, const pg8::Unit& u, int wid) const {
;     ...
;                         sq += (o0[0] * o0[0] + o0[1] * o0[1]) + (o0[2] * o0[2] + o0[3] * o0[3]) + (o1[0] * o1[0] + o1[1] * o1[1]) + (o1[2] * o1[2] + o1[3] * o1[3]);
;                     }
;                     if (ssq_out) { sq += __shfl_xor(sq, 16); sq += __shfl_xor(sq, 32); if (fq == 0) atomicAdd(ssq_out + row, sq); }
.LBB0_714:
	v_mul_f32_e32 v11, v11, v11
	v_mul_f32_e32 v9, v9, v9
	v_mul_f32_e32 v1, v1, v1
	v_fmac_f32_e32 v11, v10, v10
	v_fmac_f32_e32 v9, v8, v8
	v_fmac_f32_e32 v1, v0, v0
	v_mul_f32_e32 v0, v3, v3
	v_add_f32_e32 v8, v11, v9
	v_mul_f32_e32 v9, v15, v15
	v_fmac_f32_e32 v0, v2, v2
	v_fmac_f32_e32 v9, v14, v14
	v_add_f32_e32 v0, v1, v0
	v_mul_f32_e32 v1, v5, v5
	v_add_f32_e32 v8, v9, v8
	v_mul_f32_e32 v9, v13, v13
	v_mul_f32_e32 v7, v7, v7
	v_fmac_f32_e32 v1, v4, v4
	v_fmac_f32_e32 v9, v12, v12
	v_fmac_f32_e32 v7, v6, v6
	v_add_f32_e32 v0, v1, v0
	v_add_f32_e32 v8, v9, v8
	v_add_f32_e32 v0, v7, v0
	v_add_f32_e32 v0, v8, v0
	ds_bpermute_b32 v1, v144, v0
	s_waitcnt lgkmcnt(0)
	v_add_f32_e32 v0, v0, v1
	ds_bpermute_b32 v1, v145, v0
	s_and_saveexec_b64 s[8:9], s[10:11]
	s_cbranch_execz .LBB0_716
	v_lshl_add_u64 v[2:3], v[56:57], 2, s[58:59]
	s_waitcnt lgkmcnt(0)
	v_add_f32_e32 v0, v0, v1
	global_atomic_add_f32 v[2:3], v0, off

; __device__ __forceinline__ int lane_id_asm() { int l; asm volatile("v_mbcnt_lo_u32_b32 %0, -1, 0\n\tv_mbcnt_hi_u32_b32 %0, -1, %0" : "=v"(l)); return l; }
; __device__ __forceinline__ u32x4 pack8(f32x4 a, f32x4 b) { u32x4 w; w.x = pk2(a[0], a[1]); w.y = pk2(a[2], a[3]); w.z = pk2(b[0], b[1]); w.w = pk2(b[2], b[3]); return w; }
;     __device__ __forceinline__ void operator()(const Acc& acc, const pg8::Unit& u, int wid) const {
;         const int lane_ = lane_id_asm(), wr = wid >> 2, wc = wid & 3, fr = lane_ & 15, fq = lane_ >> 4;
;         const int row0 = u.pm * 256 + wr * 64 + fr, col0 = u.pn * 256 + wc * 32 + 8 * fq;
;         float r2[8];
; #pragma unroll
;         for (int i = 0; i < 8; ++i) r2[i] = ssq2 ? ssq2[row0 + (i >> 2) * 128 + (i & 3) * 16] : 0.f;
;         u32x4 bv[2][4][2];
; #pragma unroll
;         for (int ai = 0; ai < 2; ++ai)
; #pragma unroll
;             for (int m = 0; m < 4; ++m)
; #pragma unroll
;                 for (int bj = 0; bj < 2; ++bj) bv[ai][m][bj] = *(const u32x4*)(base + (size_t)(row0 + ai * 128 + m * 16) * 1024 + col0 + bj * 128);
; #pragma unroll
;         for (int ai = 0; ai < 2; ++ai) {
; #pragma unroll
;             for (int m = 0; m < 4; ++m) {
;                 const int row = row0 + ai * 128 + m * 16; float sq = 0.f;
;                 const float rr = ssq2 ? __builtin_amdgcn_rcpf(r2[ai * 4 + m] * (1.f / 1024.f) + EPS) : 1.f;
; #pragma unroll
;                 for (int bj = 0; bj < 2; ++bj) {
;                     const u32x4 b4 = bv[ai][m][bj];
;                     const f32x4 o0 = (f32x4){bflo(b4.x), bfhi(b4.x), bflo(b4.y), bfhi(b4.y)} + acc[ai][bj][m][0] * rr;
;                     const f32x4 o1 = (f32x4){bflo(b4.z), bfhi(b4.z), bflo(b4.w), bfhi(b4.w)} + acc[ai][bj][m][1] * rr;
;                     *(u32x4*)(hb + (size_t)row * 1024 + col0 + bj * 128) = pack8(o0, o1);
;                     sq += (o0[0] * o0[0] + o0[1] * o0[1]) + (o0[2] * o0[2] + o0[3] * o0[3]) + (o1[0] * o1[0] + o1[1] * o1[1]) + (o1[2] * o1[2] + o1[3] * o1[3]);
;                 }
;                 if (ssq_out) { sq += __shfl_xor(sq, 16); sq += __shfl_xor(sq, 32); if (fq == 0) atomicAdd(ssq_out + row, sq); }
.LBB0_1094:
	v_mbcnt_lo_u32_b32 v250, -1, 0
	v_mbcnt_hi_u32_b32 v250, -1, v250
	s_lshl_b32 s0, s0, 8
	v_ashrrev_i32_e32 v120, 1, v250
	s_lshl_b32 s1, s26, 8
	v_and_b32_e32 v120, -8, v120
	s_or_b32 s0, s0, s69
	s_add_i32 s1, s1, s60
	v_add_u32_e32 v208, s0, v120
	v_and_or_b32 v238, v250, 15, s1
	v_ashrrev_i32_e32 v209, 31, v208
	v_lshlrev_b64 v[240:241], 1, v[208:209]
	v_ashrrev_i32_e32 v239, 31, v238
	v_lshl_add_u64 v[120:121], s[52:53], 0, v[240:241]
	v_lshlrev_b64 v[242:243], 11, v[238:239]
	v_lshl_add_u64 v[122:123], v[120:121], 0, v[242:243]
	global_load_dwordx4 v[188:191], v[122:123], off
	global_load_dwordx4 v[184:187], v[122:123], off offset:256
	v_or_b32_e32 v234, 16, v238
	v_ashrrev_i32_e32 v235, 31, v234
	v_or_b32_e32 v230, 32, v238
	v_lshlrev_b64 v[236:237], 11, v[234:235]
	v_ashrrev_i32_e32 v231, 31, v230
	v_or_b32_e32 v226, 48, v238
	v_add_u32_e32 v220, 0x80, v238
	v_lshl_add_u64 v[122:123], v[120:121], 0, v[236:237]
	v_lshlrev_b64 v[232:233], 11, v[230:231]
	v_ashrrev_i32_e32 v227, 31, v226
	v_ashrrev_i32_e32 v221, 31, v220
	global_load_dwordx4 v[180:183], v[122:123], off
	global_load_dwordx4 v[176:179], v[122:123], off offset:256
	v_lshl_add_u64 v[122:123], v[120:121], 0, v[232:233]
	v_lshlrev_b64 v[228:229], 11, v[226:227]
	v_add_u32_e32 v218, 0x90, v238
	global_load_dwordx4 v[172:175], v[122:123], off
	global_load_dwordx4 v[168:171], v[122:123], off offset:256
	v_lshl_add_u64 v[122:123], v[120:121], 0, v[228:229]
	v_lshlrev_b64 v[224:225], 11, v[220:221]
	v_ashrrev_i32_e32 v219, 31, v218
	v_add_u32_e32 v214, 0xa0, v238
	v_add_u32_e32 v210, 0xb0, v238
	global_load_dwordx4 v[164:167], v[122:123], off
	global_load_dwordx4 v[160:163], v[122:123], off offset:256
	v_lshl_add_u64 v[122:123], v[120:121], 0, v[224:225]
	v_lshlrev_b64 v[222:223], 11, v[218:219]
	v_ashrrev_i32_e32 v215, 31, v214
	v_ashrrev_i32_e32 v211, 31, v210
	global_load_dwordx4 v[156:159], v[122:123], off
	global_load_dwordx4 v[152:155], v[122:123], off offset:256
	v_lshl_add_u64 v[122:123], v[120:121], 0, v[222:223]
	v_lshlrev_b64 v[216:217], 11, v[214:215]
	v_lshlrev_b64 v[212:213], 11, v[210:211]
	global_load_dwordx4 v[148:151], v[122:123], off
	global_load_dwordx4 v[144:147], v[122:123], off offset:256
	v_lshl_add_u64 v[122:123], v[120:121], 0, v[216:217]
	v_lshl_add_u64 v[120:121], v[120:121], 0, v[212:213]
	global_load_dwordx4 v[136:139], v[122:123], off
	global_load_dwordx4 v[124:127], v[122:123], off offset:256
	global_load_dwordx4 v[132:135], v[120:121], off
	s_nop 0
	global_load_dwordx4 v[120:123], v[120:121], off offset:256
	v_cmp_gt_u32_e32 vcc, 16, v250
	v_lshl_add_u64 v[242:243], s[42:43], 0, v[242:243]
	v_lshl_add_u64 v[240:241], v[242:243], 0, v[240:241]
	s_waitcnt vmcnt(0)
	v_lshlrev_b32_e32 v250, 16, v188
	v_and_b32_e32 v251, 0xffff0000, v188
	v_lshlrev_b32_e32 v188, 16, v189
	v_and_b32_e32 v189, 0xffff0000, v189
	v_pk_add_f32 v[142:143], v[142:143], v[188:189]
	v_lshlrev_b32_e32 v188, 16, v190
	v_and_b32_e32 v189, 0xffff0000, v190
	v_lshlrev_b32_e32 v190, 16, v191
	v_and_b32_e32 v191, 0xffff0000, v191
	v_pk_add_f32 v[140:141], v[140:141], v[250:251]
	v_pk_add_f32 v[190:191], v[130:131], v[190:191]
	v_pk_add_f32 v[188:189], v[128:129], v[188:189]
	v_cvt_pk_bf16_f32 v128, v140, v141
	v_cvt_pk_bf16_f32 v129, v142, v143
	v_cvt_pk_bf16_f32 v130, v188, v189
	v_cvt_pk_bf16_f32 v131, v190, v191
	global_store_dwordx4 v[240:241], v[128:131], off
	s_nop 1
	v_lshlrev_b32_e32 v128, 16, v184
	v_and_b32_e32 v129, 0xffff0000, v184
	v_lshlrev_b32_e32 v130, 16, v185
	v_and_b32_e32 v131, 0xffff0000, v185
	v_pk_add_f32 v[118:119], v[118:119], v[130:131]
	v_pk_add_f32 v[116:117], v[116:117], v[128:129]
	v_lshlrev_b32_e32 v128, 16, v186
	v_and_b32_e32 v129, 0xffff0000, v186
	v_lshlrev_b32_e32 v130, 16, v187
	v_and_b32_e32 v131, 0xffff0000, v187
	v_pk_add_f32 v[130:131], v[114:115], v[130:131]
	v_pk_add_f32 v[128:129], v[112:113], v[128:129]
	v_cvt_pk_bf16_f32 v112, v116, v117
	v_cvt_pk_bf16_f32 v113, v118, v119
	v_cvt_pk_bf16_f32 v114, v128, v129
	v_cvt_pk_bf16_f32 v115, v130, v131
	global_store_dwordx4 v[240:241], v[112:115], off offset:256
	s_nop 1
	v_mul_f32_e32 v114, v141, v141
	v_mul_f32_e32 v115, v143, v143
	v_fmac_f32_e32 v114, v140, v140
	v_fmac_f32_e32 v115, v142, v142
	v_mul_f32_e32 v113, v189, v189
	v_add_f32_e32 v114, v114, v115
	v_mul_f32_e32 v115, v117, v117
	v_mul_f32_e32 v112, v191, v191
	v_fmac_f32_e32 v113, v188, v188
	v_fmac_f32_e32 v115, v116, v116
	v_mul_f32_e32 v116, v119, v119
	v_fmac_f32_e32 v112, v190, v190
	v_add_f32_e32 v113, v113, v114
	v_mul_f32_e32 v114, v129, v129
	v_fmac_f32_e32 v116, v118, v118
	v_add_f32_e32 v112, v112, v113
	v_mul_f32_e32 v113, v131, v131
	v_fmac_f32_e32 v114, v128, v128
	v_add_f32_e32 v115, v115, v116
	v_fmac_f32_e32 v113, v130, v130
	v_add_f32_e32 v114, v114, v115
	v_add_f32_e32 v113, v113, v114
	v_and_b32_e32 v114, 64, v249
	v_add_f32_e32 v113, v112, v113
	v_xor_b32_e32 v112, 16, v249
	v_add_u32_e32 v115, 64, v114
	v_cmp_lt_i32_e64 s[0:1], v112, v115
	s_nop 1
	v_cndmask_b32_e64 v112, v249, v112, s[0:1]
	v_lshlrev_b32_e32 v112, 2, v112
	ds_bpermute_b32 v114, v112, v113
	s_waitcnt lgkmcnt(0)
	v_add_f32_e32 v114, v113, v114
	v_xor_b32_e32 v113, 32, v249
	v_cmp_lt_i32_e64 s[0:1], v113, v115
	s_nop 1
	v_cndmask_b32_e64 v113, v249, v113, s[0:1]
	v_lshlrev_b32_e32 v113, 2, v113
	ds_bpermute_b32 v115, v113, v114
	s_and_saveexec_b64 s[0:1], vcc
	s_cbranch_execz .LBB0_1096
	v_lshl_add_u64 v[116:117], v[238:239], 2, s[46:47]
	s_waitcnt lgkmcnt(0)
	v_add_f32_e32 v114, v114, v115
	global_atomic_add_f32 v[116:117], v114, off
; __device__ __forceinline__ u32x4 pack8(f32x4 a, f32x4 b) { u32x4 w; w.x = pk2(a[0], a[1]); w.y = pk2(a[2], a[3]); w.z = pk2(b[0], b[1]); w.w = pk2(b[2], b[3]); return w; }
;     __device__ __forceinline__ void operator()(const Acc& acc, const pg8::Unit& u, int wid) const {
;     ...
;         for (int ai = 0; ai < 2; ++ai) {
; #pragma unroll
;             for (int m = 0; m < 4; ++m) {
;                 const int row = row0 + ai * 128 + m * 16; float sq = 0.f;
;                 const float rr = ssq2 ? __builtin_amdgcn_rcpf(r2[ai * 4 + m] * (1.f / 1024.f) + EPS) : 1.f;
; #pragma unroll
;                 for (int bj = 0; bj < 2; ++bj) {
;                     const u32x4 b4 = bv[ai][m][bj];
;                     const f32x4 o0 = (f32x4){bflo(b4.x), bfhi(b4.x), bflo(b4.y), bfhi(b4.y)} + acc[ai][bj][m][0] * rr;
;                     const f32x4 o1 = (f32x4){bflo(b4.z), bfhi(b4.z), bflo(b4.w), bfhi(b4.w)} + acc[ai][bj][m][1] * rr;
;                     *(u32x4*)(hb + (size_t)row * 1024 + col0 + bj * 128) = pack8(o0, o1);
;                     sq += (o0[0] * o0[0] + o0[1] * o0[1]) + (o0[2] * o0[2] + o0[3] * o0[3]) + (o1[0] * o1[0] + o1[1] * o1[1]) + (o1[2] * o1[2] + o1[3] * o1[3]);
;                 }
;                 if (ssq_out) { sq += __shfl_xor(sq, 16); sq += __shfl_xor(sq, 32); if (fq == 0) atomicAdd(ssq_out + row, sq); }
.LBB0_1096:
	s_or_b64 exec, exec, s[0:1]
	v_lshlrev_b32_e32 v114, 16, v180
	s_waitcnt lgkmcnt(0)
	v_and_b32_e32 v115, 0xffff0000, v180
	v_lshlrev_b32_e32 v116, 16, v181
	v_and_b32_e32 v117, 0xffff0000, v181
	v_lshlrev_b32_e32 v128, 16, v177
	v_and_b32_e32 v129, 0xffff0000, v177
	v_pk_add_f32 v[110:111], v[110:111], v[116:117]
	v_pk_add_f32 v[108:109], v[108:109], v[114:115]
	v_lshlrev_b32_e32 v114, 16, v182
	v_and_b32_e32 v115, 0xffff0000, v182
	v_lshlrev_b32_e32 v118, 16, v176
	v_and_b32_e32 v119, 0xffff0000, v176
	v_pk_add_f32 v[102:103], v[102:103], v[128:129]
	v_lshlrev_b32_e32 v128, 16, v179
	v_and_b32_e32 v129, 0xffff0000, v179
	v_lshlrev_b32_e32 v116, 16, v183
	v_and_b32_e32 v117, 0xffff0000, v183
	v_pk_add_f32 v[114:115], v[104:105], v[114:115]
	v_pk_add_f32 v[100:101], v[100:101], v[118:119]
	v_lshlrev_b32_e32 v118, 16, v178
	v_and_b32_e32 v119, 0xffff0000, v178
	v_pk_add_f32 v[128:129], v[98:99], v[128:129]
	v_mul_f32_e32 v98, v109, v109
	v_mul_f32_e32 v99, v111, v111
	v_pk_add_f32 v[116:117], v[106:107], v[116:117]
	v_pk_add_f32 v[118:119], v[96:97], v[118:119]
	v_mul_f32_e32 v97, v115, v115
	v_fmac_f32_e32 v98, v108, v108
	v_fmac_f32_e32 v99, v110, v110
	v_cvt_pk_bf16_f32 v104, v108, v109
	v_mul_f32_e32 v96, v117, v117
	v_fmac_f32_e32 v97, v114, v114
	v_add_f32_e32 v98, v98, v99
	v_mul_f32_e32 v99, v101, v101
	v_mul_f32_e32 v108, v103, v103
	v_fmac_f32_e32 v96, v116, v116
	v_add_f32_e32 v97, v97, v98
	v_mul_f32_e32 v98, v119, v119
	v_fmac_f32_e32 v99, v100, v100
	v_fmac_f32_e32 v108, v102, v102
	v_add_f32_e32 v96, v96, v97
	v_mul_f32_e32 v97, v129, v129
	v_fmac_f32_e32 v98, v118, v118
	v_add_f32_e32 v99, v99, v108
	v_fmac_f32_e32 v97, v128, v128
	v_add_f32_e32 v98, v98, v99
	v_add_f32_e32 v97, v97, v98
	v_add_f32_e32 v99, v96, v97
	v_cvt_pk_bf16_f32 v105, v110, v111
	ds_bpermute_b32 v110, v112, v99
	v_lshl_add_u64 v[96:97], s[42:43], 0, v[236:237]
	v_lshl_add_u64 v[108:109], v[208:209], 1, v[96:97]
	v_cvt_pk_bf16_f32 v106, v114, v115
	v_cvt_pk_bf16_f32 v107, v116, v117
	s_waitcnt lgkmcnt(0)
	v_add_f32_e32 v96, v99, v110
	ds_bpermute_b32 v97, v113, v96
	v_cvt_pk_bf16_f32 v98, v100, v101
	v_cvt_pk_bf16_f32 v99, v102, v103
	v_cvt_pk_bf16_f32 v100, v118, v119
	v_cvt_pk_bf16_f32 v101, v128, v129
	global_store_dwordx4 v[108:109], v[104:107], off
	global_store_dwordx4 v[108:109], v[98:101], off offset:256
	s_and_saveexec_b64 s[0:1], vcc
	s_cbranch_execz .LBB0_1098
	v_lshl_add_u64 v[98:99], v[234:235], 2, s[46:47]
	s_waitcnt lgkmcnt(0)
	v_add_f32_e32 v96, v96, v97
	global_atomic_add_f32 v[98:99], v96, off
.LBB0_1098:
	s_or_b64 exec, exec, s[0:1]
	v_lshlrev_b32_e32 v96, 16, v172
	s_waitcnt lgkmcnt(0)
	v_and_b32_e32 v97, 0xffff0000, v172
	v_lshlrev_b32_e32 v98, 16, v173
	v_and_b32_e32 v99, 0xffff0000, v173
	v_lshlrev_b32_e32 v102, 16, v169
	v_and_b32_e32 v103, 0xffff0000, v169
	v_pk_add_f32 v[94:95], v[94:95], v[98:99]
	v_pk_add_f32 v[92:93], v[92:93], v[96:97]
	v_lshlrev_b32_e32 v96, 16, v174
	v_and_b32_e32 v97, 0xffff0000, v174
	v_lshlrev_b32_e32 v100, 16, v168
	v_and_b32_e32 v101, 0xffff0000, v168
	v_pk_add_f32 v[86:87], v[86:87], v[102:103]
	v_lshlrev_b32_e32 v102, 16, v171
	v_and_b32_e32 v103, 0xffff0000, v171
	v_lshlrev_b32_e32 v98, 16, v175
	v_and_b32_e32 v99, 0xffff0000, v175
	v_pk_add_f32 v[96:97], v[88:89], v[96:97]
	v_pk_add_f32 v[84:85], v[84:85], v[100:101]
	v_lshlrev_b32_e32 v100, 16, v170
	v_and_b32_e32 v101, 0xffff0000, v170
	v_pk_add_f32 v[102:103], v[82:83], v[102:103]
	v_mul_f32_e32 v82, v93, v93
	v_mul_f32_e32 v83, v95, v95
	v_pk_add_f32 v[98:99], v[90:91], v[98:99]
	v_pk_add_f32 v[100:101], v[80:81], v[100:101]
	v_mul_f32_e32 v81, v97, v97
	v_fmac_f32_e32 v82, v92, v92
	v_fmac_f32_e32 v83, v94, v94
	v_cvt_pk_bf16_f32 v88, v92, v93
	v_mul_f32_e32 v80, v99, v99
	v_fmac_f32_e32 v81, v96, v96
	v_add_f32_e32 v82, v82, v83
	v_mul_f32_e32 v83, v85, v85
	v_mul_f32_e32 v92, v87, v87
	v_fmac_f32_e32 v80, v98, v98
	v_add_f32_e32 v81, v81, v82
	v_mul_f32_e32 v82, v101, v101
	v_fmac_f32_e32 v83, v84, v84
	v_fmac_f32_e32 v92, v86, v86
	v_add_f32_e32 v80, v80, v81
	v_mul_f32_e32 v81, v103, v103
	v_fmac_f32_e32 v82, v100, v100
	v_add_f32_e32 v83, v83, v92
	v_fmac_f32_e32 v81, v102, v102
	v_add_f32_e32 v82, v82, v83
	v_add_f32_e32 v81, v81, v82
	v_add_f32_e32 v83, v80, v81
	v_cvt_pk_bf16_f32 v89, v94, v95
	ds_bpermute_b32 v94, v112, v83
	v_lshl_add_u64 v[80:81], s[42:43], 0, v[232:233]
	v_lshl_add_u64 v[92:93], v[208:209], 1, v[80:81]
	v_cvt_pk_bf16_f32 v90, v96, v97
	v_cvt_pk_bf16_f32 v91, v98, v99
	s_waitcnt lgkmcnt(0)
	v_add_f32_e32 v80, v83, v94
	ds_bpermute_b32 v81, v113, v80
	v_cvt_pk_bf16_f32 v82, v84, v85
	v_cvt_pk_bf16_f32 v83, v86, v87
	v_cvt_pk_bf16_f32 v84, v100, v101
	v_cvt_pk_bf16_f32 v85, v102, v103
	global_store_dwordx4 v[92:93], v[88:91], off
	global_store_dwordx4 v[92:93], v[82:85], off offset:256
	s_and_saveexec_b64 s[0:1], vcc
	s_cbranch_execz .LBB0_1100
	v_lshl_add_u64 v[82:83], v[230:231], 2, s[46:47]
	s_waitcnt lgkmcnt(0)
	v_add_f32_e32 v80, v80, v81
	global_atomic_add_f32 v[82:83], v80, off
; __device__ __forceinline__ u32x4 pack8(f32x4 a, f32x4 b) { u32x4 w; w.x = pk2(a[0], a[1]); w.y = pk2(a[2], a[3]); w.z = pk2(b[0], b[1]); w.w = pk2(b[2], b[3]); return w; }
;     __device__ __forceinline__ void operator()(const Acc& acc, const pg8::Unit& u, int wid) const {
;     ...
;         for (int ai = 0; ai < 2; ++ai) {
; #pragma unroll
;             for (int m = 0; m < 4; ++m) {
;                 const int row = row0 + ai * 128 + m * 16; float sq = 0.f;
;                 const float rr = ssq2 ? __builtin_amdgcn_rcpf(r2[ai * 4 + m] * (1.f / 1024.f) + EPS) : 1.f;
; #pragma unroll
;                 for (int bj = 0; bj < 2; ++bj) {
;                     const u32x4 b4 = bv[ai][m][bj];
;                     const f32x4 o0 = (f32x4){bflo(b4.x), bfhi(b4.x), bflo(b4.y), bfhi(b4.y)} + acc[ai][bj][m][0] * rr;
;                     const f32x4 o1 = (f32x4){bflo(b4.z), bfhi(b4.z), bflo(b4.w), bfhi(b4.w)} + acc[ai][bj][m][1] * rr;
;                     *(u32x4*)(hb + (size_t)row * 1024 + col0 + bj * 128) = pack8(o0, o1);
;                     sq += (o0[0] * o0[0] + o0[1] * o0[1]) + (o0[2] * o0[2] + o0[3] * o0[3]) + (o1[0] * o1[0] + o1[1] * o1[1]) + (o1[2] * o1[2] + o1[3] * o1[3]);
;                 }
;                 if (ssq_out) { sq += __shfl_xor(sq, 16); sq += __shfl_xor(sq, 32); if (fq == 0) atomicAdd(ssq_out + row, sq); }
.LBB0_1100:
	s_or_b64 exec, exec, s[0:1]
	v_lshlrev_b32_e32 v80, 16, v164
	s_waitcnt lgkmcnt(0)
	v_and_b32_e32 v81, 0xffff0000, v164
	v_lshlrev_b32_e32 v82, 16, v165
	v_and_b32_e32 v83, 0xffff0000, v165
	v_lshlrev_b32_e32 v86, 16, v161
	v_and_b32_e32 v87, 0xffff0000, v161
	v_pk_add_f32 v[78:79], v[78:79], v[82:83]
	v_pk_add_f32 v[76:77], v[76:77], v[80:81]
	v_lshlrev_b32_e32 v80, 16, v166
	v_and_b32_e32 v81, 0xffff0000, v166
	v_lshlrev_b32_e32 v84, 16, v160
	v_and_b32_e32 v85, 0xffff0000, v160
	v_pk_add_f32 v[70:71], v[70:71], v[86:87]
	v_lshlrev_b32_e32 v86, 16, v163
	v_and_b32_e32 v87, 0xffff0000, v163
	v_lshlrev_b32_e32 v82, 16, v167
	v_and_b32_e32 v83, 0xffff0000, v167
	v_pk_add_f32 v[80:81], v[72:73], v[80:81]
	v_pk_add_f32 v[68:69], v[68:69], v[84:85]
	v_lshlrev_b32_e32 v84, 16, v162
	v_and_b32_e32 v85, 0xffff0000, v162
	v_pk_add_f32 v[86:87], v[66:67], v[86:87]
	v_mul_f32_e32 v66, v77, v77
	v_mul_f32_e32 v67, v79, v79
	v_pk_add_f32 v[82:83], v[74:75], v[82:83]
	v_pk_add_f32 v[84:85], v[64:65], v[84:85]
	v_mul_f32_e32 v65, v81, v81
	v_fmac_f32_e32 v66, v76, v76
	v_fmac_f32_e32 v67, v78, v78
	v_cvt_pk_bf16_f32 v72, v76, v77
	v_mul_f32_e32 v64, v83, v83
	v_fmac_f32_e32 v65, v80, v80
	v_add_f32_e32 v66, v66, v67
	v_mul_f32_e32 v67, v69, v69
	v_mul_f32_e32 v76, v71, v71
	v_fmac_f32_e32 v64, v82, v82
	v_add_f32_e32 v65, v65, v66
	v_mul_f32_e32 v66, v85, v85
	v_fmac_f32_e32 v67, v68, v68
	v_fmac_f32_e32 v76, v70, v70
	v_add_f32_e32 v64, v64, v65
	v_mul_f32_e32 v65, v87, v87
	v_fmac_f32_e32 v66, v84, v84
	v_add_f32_e32 v67, v67, v76
	v_fmac_f32_e32 v65, v86, v86
	v_add_f32_e32 v66, v66, v67
	v_add_f32_e32 v65, v65, v66
	v_add_f32_e32 v67, v64, v65
	v_cvt_pk_bf16_f32 v73, v78, v79
	ds_bpermute_b32 v78, v112, v67
	v_lshl_add_u64 v[64:65], s[42:43], 0, v[228:229]
	v_lshl_add_u64 v[76:77], v[208:209], 1, v[64:65]
	v_cvt_pk_bf16_f32 v74, v80, v81
	v_cvt_pk_bf16_f32 v75, v82, v83
	s_waitcnt lgkmcnt(0)
	v_add_f32_e32 v64, v67, v78
	ds_bpermute_b32 v65, v113, v64
	v_cvt_pk_bf16_f32 v66, v68, v69
	v_cvt_pk_bf16_f32 v67, v70, v71
	v_cvt_pk_bf16_f32 v68, v84, v85
	v_cvt_pk_bf16_f32 v69, v86, v87
	global_store_dwordx4 v[76:77], v[72:75], off
	global_store_dwordx4 v[76:77], v[66:69], off offset:256
	s_and_saveexec_b64 s[0:1], vcc
	s_cbranch_execz .LBB0_1102
	v_lshl_add_u64 v[66:67], v[226:227], 2, s[46:47]
	s_waitcnt lgkmcnt(0)
	v_add_f32_e32 v64, v64, v65
	global_atomic_add_f32 v[66:67], v64, off
.LBB0_1102:
	s_or_b64 exec, exec, s[0:1]
	v_lshlrev_b32_e32 v64, 16, v156
	s_waitcnt lgkmcnt(0)
	v_and_b32_e32 v65, 0xffff0000, v156
	v_lshlrev_b32_e32 v66, 16, v157
	v_and_b32_e32 v67, 0xffff0000, v157
	v_lshlrev_b32_e32 v70, 16, v153
	v_and_b32_e32 v71, 0xffff0000, v153
	v_pk_add_f32 v[62:63], v[62:63], v[66:67]
	v_pk_add_f32 v[60:61], v[60:61], v[64:65]
	v_lshlrev_b32_e32 v64, 16, v158
	v_and_b32_e32 v65, 0xffff0000, v158
	v_lshlrev_b32_e32 v68, 16, v152
	v_and_b32_e32 v69, 0xffff0000, v152
	v_pk_add_f32 v[54:55], v[54:55], v[70:71]
	v_lshlrev_b32_e32 v70, 16, v155
	v_and_b32_e32 v71, 0xffff0000, v155
	v_lshlrev_b32_e32 v66, 16, v159
	v_and_b32_e32 v67, 0xffff0000, v159
	v_pk_add_f32 v[64:65], v[56:57], v[64:65]
	v_pk_add_f32 v[52:53], v[52:53], v[68:69]
	v_lshlrev_b32_e32 v68, 16, v154
	v_and_b32_e32 v69, 0xffff0000, v154
	v_pk_add_f32 v[70:71], v[50:51], v[70:71]
	v_mul_f32_e32 v50, v61, v61
	v_mul_f32_e32 v51, v63, v63
	v_pk_add_f32 v[66:67], v[58:59], v[66:67]
	v_pk_add_f32 v[68:69], v[48:49], v[68:69]
	v_mul_f32_e32 v49, v65, v65
	v_fmac_f32_e32 v50, v60, v60
	v_fmac_f32_e32 v51, v62, v62
	v_cvt_pk_bf16_f32 v56, v60, v61
	v_mul_f32_e32 v48, v67, v67
	v_fmac_f32_e32 v49, v64, v64
	v_add_f32_e32 v50, v50, v51
	v_mul_f32_e32 v51, v53, v53
	v_mul_f32_e32 v60, v55, v55
	v_fmac_f32_e32 v48, v66, v66
	v_add_f32_e32 v49, v49, v50
	v_mul_f32_e32 v50, v69, v69
	v_fmac_f32_e32 v51, v52, v52
	v_fmac_f32_e32 v60, v54, v54
	v_add_f32_e32 v48, v48, v49
	v_mul_f32_e32 v49, v71, v71
	v_fmac_f32_e32 v50, v68, v68
	v_add_f32_e32 v51, v51, v60
	v_fmac_f32_e32 v49, v70, v70
	v_add_f32_e32 v50, v50, v51
	v_add_f32_e32 v49, v49, v50
	v_add_f32_e32 v51, v48, v49
	v_cvt_pk_bf16_f32 v57, v62, v63
	ds_bpermute_b32 v62, v112, v51
	v_lshl_add_u64 v[48:49], s[42:43], 0, v[224:225]
	v_lshl_add_u64 v[60:61], v[208:209], 1, v[48:49]
	v_cvt_pk_bf16_f32 v58, v64, v65
	v_cvt_pk_bf16_f32 v59, v66, v67
	s_waitcnt lgkmcnt(0)
	v_add_f32_e32 v48, v51, v62
	ds_bpermute_b32 v49, v113, v48
	v_cvt_pk_bf16_f32 v50, v52, v53
	v_cvt_pk_bf16_f32 v51, v54, v55
	v_cvt_pk_bf16_f32 v52, v68, v69
	v_cvt_pk_bf16_f32 v53, v70, v71
	global_store_dwordx4 v[60:61], v[56:59], off
	global_store_dwordx4 v[60:61], v[50:53], off offset:256
	s_and_saveexec_b64 s[0:1], vcc
	s_cbranch_execz .LBB0_1104
	v_lshl_add_u64 v[50:51], v[220:221], 2, s[46:47]
	s_waitcnt lgkmcnt(0)
	v_add_f32_e32 v48, v48, v49
	global_atomic_add_f32 v[50:51], v48, off
; __device__ __forceinline__ u32x4 pack8(f32x4 a, f32x4 b) { u32x4 w; w.x = pk2(a[0], a[1]); w.y = pk2(a[2], a[3]); w.z = pk2(b[0], b[1]); w.w = pk2(b[2], b[3]); return w; }
;     __device__ __forceinline__ void operator()(const Acc& acc, const pg8::Unit& u, int wid) const {
;     ...
;         for (int ai = 0; ai < 2; ++ai) {
; #pragma unroll
;             for (int m = 0; m < 4; ++m) {
;                 const int row = row0 + ai * 128 + m * 16; float sq = 0.f;
;                 const float rr = ssq2 ? __builtin_amdgcn_rcpf(r2[ai * 4 + m] * (1.f / 1024.f) + EPS) : 1.f;
; #pragma unroll
;                 for (int bj = 0; bj < 2; ++bj) {
;                     const u32x4 b4 = bv[ai][m][bj];
;                     const f32x4 o0 = (f32x4){bflo(b4.x), bfhi(b4.x), bflo(b4.y), bfhi(b4.y)} + acc[ai][bj][m][0] * rr;
;                     const f32x4 o1 = (f32x4){bflo(b4.z), bfhi(b4.z), bflo(b4.w), bfhi(b4.w)} + acc[ai][bj][m][1] * rr;
;                     *(u32x4*)(hb + (size_t)row * 1024 + col0 + bj * 128) = pack8(o0, o1);
;                     sq += (o0[0] * o0[0] + o0[1] * o0[1]) + (o0[2] * o0[2] + o0[3] * o0[3]) + (o1[0] * o1[0] + o1[1] * o1[1]) + (o1[2] * o1[2] + o1[3] * o1[3]);
;                 }
;                 if (ssq_out) { sq += __shfl_xor(sq, 16); sq += __shfl_xor(sq, 32); if (fq == 0) atomicAdd(ssq_out + row, sq); }
.LBB0_1104:
	s_or_b64 exec, exec, s[0:1]
	v_lshlrev_b32_e32 v48, 16, v148
	s_waitcnt lgkmcnt(0)
	v_and_b32_e32 v49, 0xffff0000, v148
	v_lshlrev_b32_e32 v50, 16, v149
	v_and_b32_e32 v51, 0xffff0000, v149
	v_lshlrev_b32_e32 v54, 16, v145
	v_and_b32_e32 v55, 0xffff0000, v145
	v_pk_add_f32 v[46:47], v[46:47], v[50:51]
	v_pk_add_f32 v[44:45], v[44:45], v[48:49]
	v_lshlrev_b32_e32 v48, 16, v150
	v_and_b32_e32 v49, 0xffff0000, v150
	v_lshlrev_b32_e32 v52, 16, v144
	v_and_b32_e32 v53, 0xffff0000, v144
	v_pk_add_f32 v[38:39], v[38:39], v[54:55]
	v_lshlrev_b32_e32 v54, 16, v147
	v_and_b32_e32 v55, 0xffff0000, v147
	v_lshlrev_b32_e32 v50, 16, v151
	v_and_b32_e32 v51, 0xffff0000, v151
	v_pk_add_f32 v[48:49], v[40:41], v[48:49]
	v_pk_add_f32 v[36:37], v[36:37], v[52:53]
	v_lshlrev_b32_e32 v52, 16, v146
	v_and_b32_e32 v53, 0xffff0000, v146
	v_pk_add_f32 v[54:55], v[34:35], v[54:55]
	v_mul_f32_e32 v34, v45, v45
	v_mul_f32_e32 v35, v47, v47
	v_pk_add_f32 v[50:51], v[42:43], v[50:51]
	v_pk_add_f32 v[52:53], v[32:33], v[52:53]
	v_mul_f32_e32 v33, v49, v49
	v_fmac_f32_e32 v34, v44, v44
	v_fmac_f32_e32 v35, v46, v46
	v_cvt_pk_bf16_f32 v40, v44, v45
	v_mul_f32_e32 v32, v51, v51
	v_fmac_f32_e32 v33, v48, v48
	v_add_f32_e32 v34, v34, v35
	v_mul_f32_e32 v35, v37, v37
	v_mul_f32_e32 v44, v39, v39
	v_fmac_f32_e32 v32, v50, v50
	v_add_f32_e32 v33, v33, v34
	v_mul_f32_e32 v34, v53, v53
	v_fmac_f32_e32 v35, v36, v36
	v_fmac_f32_e32 v44, v38, v38
	v_add_f32_e32 v32, v32, v33
	v_mul_f32_e32 v33, v55, v55
	v_fmac_f32_e32 v34, v52, v52
	v_add_f32_e32 v35, v35, v44
	v_fmac_f32_e32 v33, v54, v54
	v_add_f32_e32 v34, v34, v35
	v_add_f32_e32 v33, v33, v34
	v_add_f32_e32 v35, v32, v33
	v_cvt_pk_bf16_f32 v41, v46, v47
	ds_bpermute_b32 v46, v112, v35
	v_lshl_add_u64 v[32:33], s[42:43], 0, v[222:223]
	v_lshl_add_u64 v[44:45], v[208:209], 1, v[32:33]
	v_cvt_pk_bf16_f32 v42, v48, v49
	v_cvt_pk_bf16_f32 v43, v50, v51
	s_waitcnt lgkmcnt(0)
	v_add_f32_e32 v32, v35, v46
	ds_bpermute_b32 v33, v113, v32
	v_cvt_pk_bf16_f32 v34, v36, v37
	v_cvt_pk_bf16_f32 v35, v38, v39
	v_cvt_pk_bf16_f32 v36, v52, v53
	v_cvt_pk_bf16_f32 v37, v54, v55
	global_store_dwordx4 v[44:45], v[40:43], off
	global_store_dwordx4 v[44:45], v[34:37], off offset:256
	s_and_saveexec_b64 s[0:1], vcc
	s_cbranch_execz .LBB0_1106
	v_lshl_add_u64 v[34:35], v[218:219], 2, s[46:47]
	s_waitcnt lgkmcnt(0)
	v_add_f32_e32 v32, v32, v33
	global_atomic_add_f32 v[34:35], v32, off
; __device__ __forceinline__ u32x4 pack8(f32x4 a, f32x4 b) { u32x4 w; w.x = pk2(a[0], a[1]); w.y = pk2(a[2], a[3]); w.z = pk2(b[0], b[1]); w.w = pk2(b[2], b[3]); return w; }
;     __device__ __forceinline__ void operator()(const Acc& acc, const pg8::Unit& u, int wid) const {
;     ...
;         for (int ai = 0; ai < 2; ++ai) {
; #pragma unroll
;             for (int m = 0; m < 4; ++m) {
;                 const int row = row0 + ai * 128 + m * 16; float sq = 0.f;
;                 const float rr = ssq2 ? __builtin_amdgcn_rcpf(r2[ai * 4 + m] * (1.f / 1024.f) + EPS) : 1.f;
; #pragma unroll
;                 for (int bj = 0; bj < 2; ++bj) {
;                     const u32x4 b4 = bv[ai][m][bj];
;                     const f32x4 o0 = (f32x4){bflo(b4.x), bfhi(b4.x), bflo(b4.y), bfhi(b4.y)} + acc[ai][bj][m][0] * rr;
;                     const f32x4 o1 = (f32x4){bflo(b4.z), bfhi(b4.z), bflo(b4.w), bfhi(b4.w)} + acc[ai][bj][m][1] * rr;
;                     *(u32x4*)(hb + (size_t)row * 1024 + col0 + bj * 128) = pack8(o0, o1);
;                     sq += (o0[0] * o0[0] + o0[1] * o0[1]) + (o0[2] * o0[2] + o0[3] * o0[3]) + (o1[0] * o1[0] + o1[1] * o1[1]) + (o1[2] * o1[2] + o1[3] * o1[3]);
;                 }
;                 if (ssq_out) { sq += __shfl_xor(sq, 16); sq += __shfl_xor(sq, 32); if (fq == 0) atomicAdd(ssq_out + row, sq); }
.LBB0_1106:
	s_or_b64 exec, exec, s[0:1]
	v_lshlrev_b32_e32 v32, 16, v136
	s_waitcnt lgkmcnt(0)
	v_and_b32_e32 v33, 0xffff0000, v136
	v_lshlrev_b32_e32 v34, 16, v137
	v_and_b32_e32 v35, 0xffff0000, v137
	v_lshlrev_b32_e32 v38, 16, v125
	v_and_b32_e32 v39, 0xffff0000, v125
	v_pk_add_f32 v[30:31], v[30:31], v[34:35]
	v_pk_add_f32 v[28:29], v[28:29], v[32:33]
	v_lshlrev_b32_e32 v32, 16, v138
	v_and_b32_e32 v33, 0xffff0000, v138
	v_lshlrev_b32_e32 v36, 16, v124
	v_and_b32_e32 v37, 0xffff0000, v124
	v_pk_add_f32 v[22:23], v[22:23], v[38:39]
	v_lshlrev_b32_e32 v38, 16, v127
	v_and_b32_e32 v39, 0xffff0000, v127
	v_lshlrev_b32_e32 v34, 16, v139
	v_and_b32_e32 v35, 0xffff0000, v139
	v_pk_add_f32 v[32:33], v[24:25], v[32:33]
	v_pk_add_f32 v[20:21], v[20:21], v[36:37]
	v_lshlrev_b32_e32 v36, 16, v126
	v_and_b32_e32 v37, 0xffff0000, v126
	v_pk_add_f32 v[38:39], v[18:19], v[38:39]
	v_mul_f32_e32 v18, v29, v29
	v_mul_f32_e32 v19, v31, v31
	v_pk_add_f32 v[34:35], v[26:27], v[34:35]
	v_pk_add_f32 v[36:37], v[16:17], v[36:37]
	v_mul_f32_e32 v17, v33, v33
	v_fmac_f32_e32 v18, v28, v28
	v_fmac_f32_e32 v19, v30, v30
	v_cvt_pk_bf16_f32 v24, v28, v29
	v_mul_f32_e32 v16, v35, v35
	v_fmac_f32_e32 v17, v32, v32
	v_add_f32_e32 v18, v18, v19
	v_mul_f32_e32 v19, v21, v21
	v_mul_f32_e32 v28, v23, v23
	v_fmac_f32_e32 v16, v34, v34
	v_add_f32_e32 v17, v17, v18
	v_mul_f32_e32 v18, v37, v37
	v_fmac_f32_e32 v19, v20, v20
	v_fmac_f32_e32 v28, v22, v22
	v_add_f32_e32 v16, v16, v17
	v_mul_f32_e32 v17, v39, v39
	v_fmac_f32_e32 v18, v36, v36
	v_add_f32_e32 v19, v19, v28
	v_fmac_f32_e32 v17, v38, v38
	v_add_f32_e32 v18, v18, v19
	v_add_f32_e32 v17, v17, v18
	v_add_f32_e32 v19, v16, v17
	v_cvt_pk_bf16_f32 v25, v30, v31
	ds_bpermute_b32 v30, v112, v19
	v_lshl_add_u64 v[16:17], s[42:43], 0, v[216:217]
	v_lshl_add_u64 v[28:29], v[208:209], 1, v[16:17]
	v_cvt_pk_bf16_f32 v26, v32, v33
	v_cvt_pk_bf16_f32 v27, v34, v35
	s_waitcnt lgkmcnt(0)
	v_add_f32_e32 v16, v19, v30
	ds_bpermute_b32 v17, v113, v16
	v_cvt_pk_bf16_f32 v18, v20, v21
	v_cvt_pk_bf16_f32 v19, v22, v23
	v_cvt_pk_bf16_f32 v20, v36, v37
	v_cvt_pk_bf16_f32 v21, v38, v39
	global_store_dwordx4 v[28:29], v[24:27], off
	global_store_dwordx4 v[28:29], v[18:21], off offset:256
	s_and_saveexec_b64 s[0:1], vcc
	s_cbranch_execz .LBB0_1108
	v_lshl_add_u64 v[18:19], v[214:215], 2, s[46:47]
	s_waitcnt lgkmcnt(0)
	v_add_f32_e32 v16, v16, v17
	global_atomic_add_f32 v[18:19], v16, off
.LBB0_1108:
	s_or_b64 exec, exec, s[0:1]
	v_lshlrev_b32_e32 v16, 16, v132
	s_waitcnt lgkmcnt(0)
	v_and_b32_e32 v17, 0xffff0000, v132
	v_lshlrev_b32_e32 v18, 16, v133
	v_and_b32_e32 v19, 0xffff0000, v133
	v_lshlrev_b32_e32 v22, 16, v121
	v_and_b32_e32 v23, 0xffff0000, v121
	v_pk_add_f32 v[14:15], v[14:15], v[18:19]
	v_pk_add_f32 v[12:13], v[12:13], v[16:17]
	v_lshlrev_b32_e32 v16, 16, v134
	v_and_b32_e32 v17, 0xffff0000, v134
	v_lshlrev_b32_e32 v20, 16, v120
	v_and_b32_e32 v21, 0xffff0000, v120
	v_pk_add_f32 v[6:7], v[6:7], v[22:23]
	v_lshlrev_b32_e32 v22, 16, v123
	v_and_b32_e32 v23, 0xffff0000, v123
	v_lshlrev_b32_e32 v18, 16, v135
	v_and_b32_e32 v19, 0xffff0000, v135
	v_pk_add_f32 v[16:17], v[8:9], v[16:17]
	v_pk_add_f32 v[4:5], v[4:5], v[20:21]
	v_lshlrev_b32_e32 v20, 16, v122
	v_and_b32_e32 v21, 0xffff0000, v122
	v_pk_add_f32 v[22:23], v[2:3], v[22:23]
	v_mul_f32_e32 v2, v13, v13
	v_mul_f32_e32 v3, v15, v15
	v_pk_add_f32 v[18:19], v[10:11], v[18:19]
	v_pk_add_f32 v[20:21], v[0:1], v[20:21]
	v_mul_f32_e32 v1, v17, v17
	v_fmac_f32_e32 v2, v12, v12
	v_fmac_f32_e32 v3, v14, v14
	v_cvt_pk_bf16_f32 v8, v12, v13
	v_mul_f32_e32 v0, v19, v19
	v_fmac_f32_e32 v1, v16, v16
	v_add_f32_e32 v2, v2, v3
	v_mul_f32_e32 v3, v5, v5
	v_mul_f32_e32 v12, v7, v7
	v_fmac_f32_e32 v0, v18, v18
	v_add_f32_e32 v1, v1, v2
	v_mul_f32_e32 v2, v21, v21
	v_fmac_f32_e32 v3, v4, v4
	v_fmac_f32_e32 v12, v6, v6
	v_add_f32_e32 v0, v0, v1
	v_mul_f32_e32 v1, v23, v23
	v_fmac_f32_e32 v2, v20, v20
	v_add_f32_e32 v3, v3, v12
	v_fmac_f32_e32 v1, v22, v22
	v_add_f32_e32 v2, v2, v3
	v_add_f32_e32 v1, v1, v2
	v_add_f32_e32 v3, v0, v1
	v_cvt_pk_bf16_f32 v9, v14, v15
	ds_bpermute_b32 v14, v112, v3
	v_lshl_add_u64 v[0:1], s[42:43], 0, v[212:213]
	v_lshl_add_u64 v[12:13], v[208:209], 1, v[0:1]
	v_cvt_pk_bf16_f32 v10, v16, v17
	v_cvt_pk_bf16_f32 v11, v18, v19
	s_waitcnt lgkmcnt(0)
	v_add_f32_e32 v0, v3, v14
	ds_bpermute_b32 v1, v113, v0
	v_cvt_pk_bf16_f32 v2, v4, v5
	v_cvt_pk_bf16_f32 v3, v6, v7
	v_cvt_pk_bf16_f32 v4, v20, v21
	v_cvt_pk_bf16_f32 v5, v22, v23
	global_store_dwordx4 v[12:13], v[8:11], off
	global_store_dwordx4 v[12:13], v[2:5], off offset:256
	s_and_saveexec_b64 s[0:1], vcc
	s_cbranch_execz .LBB0_1110
	v_lshl_add_u64 v[2:3], v[210:211], 2, s[46:47]
	s_waitcnt lgkmcnt(0)
	v_add_f32_e32 v0, v0, v1
	global_atomic_add_f32 v[2:3], v0, off

; __device__ __forceinline__ u32x4 pack8(f32x4 a, f32x4 b) { u32x4 w; w.x = pk2(a[0], a[1]); w.y = pk2(a[2], a[3]); w.z = pk2(b[0], b[1]); w.w = pk2(b[2], b[3]); return w; }
;     __device__ __forceinline__ void operator()(const Acc& acc, const pg8::Unit& u, int wid) const {
;     ...
;         const int row0 = u.pm * 256 + wr * 64 + fr, col0 = u.pn * 256 + wc * 32 + 8 * fq;
;         float r2[8];
; #pragma unroll
;         for (int i = 0; i < 8; ++i) r2[i] = ssq2 ? ssq2[row0 + (i >> 2) * 128 + (i & 3) * 16] : 0.f;
;         u32x4 bv[2][4][2];
; #pragma unroll
;         for (int ai = 0; ai < 2; ++ai)
; #pragma unroll
;             for (int m = 0; m < 4; ++m)
; #pragma unroll
;                 for (int bj = 0; bj < 2; ++bj) bv[ai][m][bj] = *(const u32x4*)(base + (size_t)(row0 + ai * 128 + m * 16) * 1024 + col0 + bj * 128);
; #pragma unroll
;         for (int ai = 0; ai < 2; ++ai) {
; #pragma unroll
;             for (int m = 0; m < 4; ++m) {
;                 const int row = row0 + ai * 128 + m * 16; float sq = 0.f;
;                 const float rr = ssq2 ? __builtin_amdgcn_rcpf(r2[ai * 4 + m] * (1.f / 1024.f) + EPS) : 1.f;
; #pragma unroll
;                 for (int bj = 0; bj < 2; ++bj) {
;                     const u32x4 b4 = bv[ai][m][bj];
;                     const f32x4 o0 = (f32x4){bflo(b4.x), bfhi(b4.x), bflo(b4.y), bfhi(b4.y)} + acc[ai][bj][m][0] * rr;
;                     const f32x4 o1 = (f32x4){bflo(b4.z), bfhi(b4.z), bflo(b4.w), bfhi(b4.w)} + acc[ai][bj][m][1] * rr;
;                     *(u32x4*)(hb + (size_t)row * 1024 + col0 + bj * 128) = pack8(o0, o1);
;                     sq += (o0[0] * o0[0] + o0[1] * o0[1]) + (o0[2] * o0[2] + o0[3] * o0[3]) + (o1[0] * o1[0] + o1[1] * o1[1]) + (o1[2] * o1[2] + o1[3] * o1[3]);
;                 }
;                 if (ssq_out) { sq += __shfl_xor(sq, 16); sq += __shfl_xor(sq, 32); if (fq == 0) atomicAdd(ssq_out + row, sq); }
.LBB0_1248:
	s_lshl_b32 s1, s24, 8
	s_add_i32 s1, s1, s60
	v_mbcnt_lo_u32_b32 v208, -1, 0
	v_mbcnt_hi_u32_b32 v208, -1, v208
	s_lshl_b32 s0, s0, 8
	v_and_or_b32 v234, v208, 15, s1
	v_ashrrev_i32_e32 v124, 1, v208
	v_ashrrev_i32_e32 v235, 31, v234
	v_and_b32_e32 v126, -8, v124
	v_lshl_add_u64 v[124:125], v[234:235], 2, s[46:47]
	global_load_dword v127, v[124:125], off
	s_or_b32 s0, s0, s69
	v_add_u32_e32 v204, s0, v126
	v_ashrrev_i32_e32 v205, 31, v204
	v_lshlrev_b64 v[236:237], 1, v[204:205]
	v_lshl_add_u64 v[136:137], s[42:43], 0, v[236:237]
	v_lshlrev_b64 v[238:239], 11, v[234:235]
	global_load_dword v252, v[124:125], off offset:64
	global_load_dword v251, v[124:125], off offset:128
	global_load_dword v250, v[124:125], off offset:192
	global_load_dword v249, v[124:125], off offset:512
	global_load_dword v248, v[124:125], off offset:576
	global_load_dword v247, v[124:125], off offset:640
	global_load_dword v246, v[124:125], off offset:704
	v_lshl_add_u64 v[124:125], v[136:137], 0, v[238:239]
	global_load_dwordx4 v[188:191], v[124:125], off
	global_load_dwordx4 v[184:187], v[124:125], off offset:256
	v_or_b32_e32 v230, 16, v234
	v_ashrrev_i32_e32 v231, 31, v230
	v_or_b32_e32 v226, 32, v234
	v_lshlrev_b64 v[232:233], 11, v[230:231]
	v_ashrrev_i32_e32 v227, 31, v226
	v_or_b32_e32 v222, 48, v234
	v_add_u32_e32 v214, 0x80, v234
	v_lshl_add_u64 v[124:125], v[136:137], 0, v[232:233]
	v_lshlrev_b64 v[228:229], 11, v[226:227]
	v_ashrrev_i32_e32 v223, 31, v222
	v_ashrrev_i32_e32 v215, 31, v214
	global_load_dwordx4 v[180:183], v[124:125], off
	global_load_dwordx4 v[176:179], v[124:125], off offset:256
	v_lshl_add_u64 v[124:125], v[136:137], 0, v[228:229]
	v_lshlrev_b64 v[224:225], 11, v[222:223]
	v_add_u32_e32 v216, 0x90, v234
	global_load_dwordx4 v[172:175], v[124:125], off
	global_load_dwordx4 v[168:171], v[124:125], off offset:256
	v_lshl_add_u64 v[124:125], v[136:137], 0, v[224:225]
	v_lshlrev_b64 v[220:221], 11, v[214:215]
	v_ashrrev_i32_e32 v217, 31, v216
	global_load_dwordx4 v[164:167], v[124:125], off
	global_load_dwordx4 v[160:163], v[124:125], off offset:256
	v_lshl_add_u64 v[124:125], v[136:137], 0, v[220:221]
	v_lshlrev_b64 v[218:219], 11, v[216:217]
	v_add_u32_e32 v210, 0xa0, v234
	v_add_u32_e32 v206, 0xb0, v234
	global_load_dwordx4 v[156:159], v[124:125], off
	global_load_dwordx4 v[152:155], v[124:125], off offset:256
	v_lshl_add_u64 v[124:125], v[136:137], 0, v[218:219]
	v_ashrrev_i32_e32 v211, 31, v210
	v_ashrrev_i32_e32 v207, 31, v206
	global_load_dwordx4 v[148:151], v[124:125], off
	global_load_dwordx4 v[144:147], v[124:125], off offset:256
	v_lshlrev_b64 v[124:125], 11, v[210:211]
	v_lshlrev_b64 v[138:139], 11, v[206:207]
	v_lshl_add_u64 v[124:125], v[136:137], 0, v[124:125]
	v_lshl_add_u64 v[136:137], v[136:137], 0, v[138:139]
	v_cmp_gt_u32_e32 vcc, 16, v208
	s_waitcnt vmcnt(0) lgkmcnt(0)
	v_fmamk_f32 v209, v127, 0x3a800000, v245
	global_load_dwordx4 v[132:135], v[124:125], off
	s_nop 0
	global_load_dwordx4 v[124:127], v[124:125], off offset:256
	s_nop 0
	global_load_dwordx4 v[140:143], v[136:137], off
	s_nop 0
	global_load_dwordx4 v[136:139], v[136:137], off offset:256
	v_rcp_f32_e32 v208, v209
	v_lshlrev_b32_e32 v212, 16, v188
	v_and_b32_e32 v213, 0xffff0000, v188
	v_lshlrev_b32_e32 v188, 16, v189
	v_and_b32_e32 v189, 0xffff0000, v189
	v_pk_fma_f32 v[130:131], v[130:131], v[208:209], v[188:189] op_sel_hi:[1,0,1]
	v_lshlrev_b32_e32 v188, 16, v190
	v_and_b32_e32 v189, 0xffff0000, v190
	v_lshlrev_b32_e32 v190, 16, v191
	v_and_b32_e32 v191, 0xffff0000, v191
	v_pk_fma_f32 v[128:129], v[128:129], v[208:209], v[212:213] op_sel_hi:[1,0,1]
	v_pk_fma_f32 v[190:191], v[122:123], v[208:209], v[190:191] op_sel_hi:[1,0,1]
	v_pk_fma_f32 v[188:189], v[120:121], v[208:209], v[188:189] op_sel_hi:[1,0,1]
	v_lshl_add_u64 v[212:213], s[42:43], 0, v[238:239]
	v_cvt_pk_bf16_f32 v120, v128, v129
	v_cvt_pk_bf16_f32 v121, v130, v131
	v_cvt_pk_bf16_f32 v122, v188, v189
	v_cvt_pk_bf16_f32 v123, v190, v191
	v_lshl_add_u64 v[212:213], v[212:213], 0, v[236:237]
	global_store_dwordx4 v[212:213], v[120:123], off
	s_nop 1
	v_lshlrev_b32_e32 v120, 16, v184
	v_and_b32_e32 v121, 0xffff0000, v184
	v_lshlrev_b32_e32 v122, 16, v185
	v_and_b32_e32 v123, 0xffff0000, v185
	v_pk_fma_f32 v[118:119], v[118:119], v[208:209], v[122:123] op_sel_hi:[1,0,1]
	v_pk_fma_f32 v[116:117], v[116:117], v[208:209], v[120:121] op_sel_hi:[1,0,1]
	v_lshlrev_b32_e32 v120, 16, v186
	v_and_b32_e32 v121, 0xffff0000, v186
	v_lshlrev_b32_e32 v122, 16, v187
	v_and_b32_e32 v123, 0xffff0000, v187
	v_pk_fma_f32 v[122:123], v[114:115], v[208:209], v[122:123] op_sel_hi:[1,0,1]
	v_pk_fma_f32 v[120:121], v[112:113], v[208:209], v[120:121] op_sel_hi:[1,0,1]
	v_cvt_pk_bf16_f32 v112, v116, v117
	v_cvt_pk_bf16_f32 v113, v118, v119
	v_cvt_pk_bf16_f32 v114, v120, v121
	v_cvt_pk_bf16_f32 v115, v122, v123
	global_store_dwordx4 v[212:213], v[112:115], off offset:256
	s_nop 1
	v_mul_f32_e32 v114, v129, v129
	v_mul_f32_e32 v115, v131, v131
	v_fmac_f32_e32 v114, v128, v128
	v_fmac_f32_e32 v115, v130, v130
	v_mul_f32_e32 v113, v189, v189
	v_add_f32_e32 v114, v114, v115
	v_mul_f32_e32 v115, v117, v117
	v_mul_f32_e32 v112, v191, v191
	v_fmac_f32_e32 v113, v188, v188
	v_fmac_f32_e32 v115, v116, v116
	v_mul_f32_e32 v116, v119, v119
	v_fmac_f32_e32 v112, v190, v190
	v_add_f32_e32 v113, v113, v114
	v_mul_f32_e32 v114, v121, v121
	v_fmac_f32_e32 v116, v118, v118
	v_add_f32_e32 v112, v112, v113
	v_mul_f32_e32 v113, v123, v123
	v_fmac_f32_e32 v114, v120, v120
	v_add_f32_e32 v115, v115, v116
	v_fmac_f32_e32 v113, v122, v122
	v_add_f32_e32 v114, v114, v115
	v_add_f32_e32 v113, v113, v114
	v_and_b32_e32 v114, 64, v244
	v_add_f32_e32 v113, v112, v113
	v_xor_b32_e32 v112, 16, v244
	v_add_u32_e32 v115, 64, v114
	v_cmp_lt_i32_e64 s[0:1], v112, v115
	s_nop 1
	v_cndmask_b32_e64 v112, v244, v112, s[0:1]
	v_lshlrev_b32_e32 v112, 2, v112
	ds_bpermute_b32 v114, v112, v113
	s_waitcnt lgkmcnt(0)
	v_add_f32_e32 v114, v113, v114
	v_xor_b32_e32 v113, 32, v244
	v_cmp_lt_i32_e64 s[0:1], v113, v115
	s_nop 1
	v_cndmask_b32_e64 v113, v244, v113, s[0:1]
	v_lshlrev_b32_e32 v113, 2, v113
	ds_bpermute_b32 v115, v113, v114
	s_and_saveexec_b64 s[0:1], vcc
	s_cbranch_execz .LBB0_1250
	v_lshl_add_u64 v[116:117], v[234:235], 2, s[36:37]
	s_waitcnt lgkmcnt(0)
	v_add_f32_e32 v114, v114, v115
	global_atomic_add_f32 v[116:117], v114, off
; __device__ __forceinline__ u32x4 pack8(f32x4 a, f32x4 b) { u32x4 w; w.x = pk2(a[0], a[1]); w.y = pk2(a[2], a[3]); w.z = pk2(b[0], b[1]); w.w = pk2(b[2], b[3]); return w; }
;     __device__ __forceinline__ void operator()(const Acc& acc, const pg8::Unit& u, int wid) const {
;     ...
;             for (int m = 0; m < 4; ++m) {
;                 const int row = row0 + ai * 128 + m * 16; float sq = 0.f;
;                 const float rr = ssq2 ? __builtin_amdgcn_rcpf(r2[ai * 4 + m] * (1.f / 1024.f) + EPS) : 1.f;
; #pragma unroll
;                 for (int bj = 0; bj < 2; ++bj) {
;                     const u32x4 b4 = bv[ai][m][bj];
;                     const f32x4 o0 = (f32x4){bflo(b4.x), bfhi(b4.x), bflo(b4.y), bfhi(b4.y)} + acc[ai][bj][m][0] * rr;
;                     const f32x4 o1 = (f32x4){bflo(b4.z), bfhi(b4.z), bflo(b4.w), bfhi(b4.w)} + acc[ai][bj][m][1] * rr;
;                     *(u32x4*)(hb + (size_t)row * 1024 + col0 + bj * 128) = pack8(o0, o1);
;                     sq += (o0[0] * o0[0] + o0[1] * o0[1]) + (o0[2] * o0[2] + o0[3] * o0[3]) + (o1[0] * o1[0] + o1[1] * o1[1]) + (o1[2] * o1[2] + o1[3] * o1[3]);
;                 }
;                 if (ssq_out) { sq += __shfl_xor(sq, 16); sq += __shfl_xor(sq, 32); if (fq == 0) atomicAdd(ssq_out + row, sq); }
.LBB0_1250:
	s_or_b64 exec, exec, s[0:1]
	v_fmamk_f32 v114, v252, 0x3a800000, v245
	v_rcp_f32_e32 v114, v114
	v_lshlrev_b32_e32 v116, 16, v180
	v_and_b32_e32 v117, 0xffff0000, v180
	v_lshlrev_b32_e32 v118, 16, v181
	v_and_b32_e32 v119, 0xffff0000, v181
	v_lshlrev_b32_e32 v122, 16, v177
	v_and_b32_e32 v123, 0xffff0000, v177
	s_waitcnt lgkmcnt(0)
	v_pk_fma_f32 v[110:111], v[110:111], v[114:115], v[118:119] op_sel_hi:[1,0,1]
	v_pk_fma_f32 v[108:109], v[108:109], v[114:115], v[116:117] op_sel_hi:[1,0,1]
	v_lshlrev_b32_e32 v116, 16, v182
	v_and_b32_e32 v117, 0xffff0000, v182
	v_lshlrev_b32_e32 v120, 16, v176
	v_and_b32_e32 v121, 0xffff0000, v176
	v_pk_fma_f32 v[102:103], v[102:103], v[114:115], v[122:123] op_sel_hi:[1,0,1]
	v_lshlrev_b32_e32 v122, 16, v179
	v_and_b32_e32 v123, 0xffff0000, v179
	v_lshlrev_b32_e32 v118, 16, v183
	v_and_b32_e32 v119, 0xffff0000, v183
	v_pk_fma_f32 v[116:117], v[104:105], v[114:115], v[116:117] op_sel_hi:[1,0,1]
	v_pk_fma_f32 v[100:101], v[100:101], v[114:115], v[120:121] op_sel_hi:[1,0,1]
	v_lshlrev_b32_e32 v120, 16, v178
	v_and_b32_e32 v121, 0xffff0000, v178
	v_pk_fma_f32 v[122:123], v[98:99], v[114:115], v[122:123] op_sel_hi:[1,0,1]
	v_mul_f32_e32 v98, v109, v109
	v_mul_f32_e32 v99, v111, v111
	v_pk_fma_f32 v[118:119], v[106:107], v[114:115], v[118:119] op_sel_hi:[1,0,1]
	v_pk_fma_f32 v[114:115], v[96:97], v[114:115], v[120:121] op_sel_hi:[1,0,1]
	v_mul_f32_e32 v97, v117, v117
	v_fmac_f32_e32 v98, v108, v108
	v_fmac_f32_e32 v99, v110, v110
	v_cvt_pk_bf16_f32 v104, v108, v109
	v_mul_f32_e32 v96, v119, v119
	v_fmac_f32_e32 v97, v116, v116
	v_add_f32_e32 v98, v98, v99
	v_mul_f32_e32 v99, v101, v101
	v_mul_f32_e32 v108, v103, v103
	v_fmac_f32_e32 v96, v118, v118
	v_add_f32_e32 v97, v97, v98
	v_mul_f32_e32 v98, v115, v115
	v_fmac_f32_e32 v99, v100, v100
	v_fmac_f32_e32 v108, v102, v102
	v_add_f32_e32 v96, v96, v97
	v_mul_f32_e32 v97, v123, v123
	v_fmac_f32_e32 v98, v114, v114
	v_add_f32_e32 v99, v99, v108
	v_fmac_f32_e32 v97, v122, v122
	v_add_f32_e32 v98, v98, v99
	v_add_f32_e32 v97, v97, v98
	v_add_f32_e32 v99, v96, v97
	v_cvt_pk_bf16_f32 v105, v110, v111
	ds_bpermute_b32 v110, v112, v99
	v_lshl_add_u64 v[96:97], s[42:43], 0, v[232:233]
	v_lshl_add_u64 v[108:109], v[204:205], 1, v[96:97]
	v_cvt_pk_bf16_f32 v106, v116, v117
	v_cvt_pk_bf16_f32 v107, v118, v119
	s_waitcnt lgkmcnt(0)
	v_add_f32_e32 v96, v99, v110
	ds_bpermute_b32 v97, v113, v96
	v_cvt_pk_bf16_f32 v98, v100, v101
	v_cvt_pk_bf16_f32 v99, v102, v103
	v_cvt_pk_bf16_f32 v100, v114, v115
	v_cvt_pk_bf16_f32 v101, v122, v123
	global_store_dwordx4 v[108:109], v[104:107], off
	global_store_dwordx4 v[108:109], v[98:101], off offset:256
	s_and_saveexec_b64 s[0:1], vcc
	s_cbranch_execz .LBB0_1252
	v_lshl_add_u64 v[98:99], v[230:231], 2, s[36:37]
	s_waitcnt lgkmcnt(0)
	v_add_f32_e32 v96, v96, v97
	global_atomic_add_f32 v[98:99], v96, off
.LBB0_1252:
	s_or_b64 exec, exec, s[0:1]
	v_fmamk_f32 v96, v251, 0x3a800000, v245
	v_rcp_f32_e32 v96, v96
	v_lshlrev_b32_e32 v98, 16, v172
	v_and_b32_e32 v99, 0xffff0000, v172
	v_lshlrev_b32_e32 v100, 16, v173
	v_and_b32_e32 v101, 0xffff0000, v173
	v_lshlrev_b32_e32 v104, 16, v169
	v_and_b32_e32 v105, 0xffff0000, v169
	s_waitcnt lgkmcnt(0)
	v_pk_fma_f32 v[94:95], v[94:95], v[96:97], v[100:101] op_sel_hi:[1,0,1]
	v_pk_fma_f32 v[92:93], v[92:93], v[96:97], v[98:99] op_sel_hi:[1,0,1]
	v_lshlrev_b32_e32 v98, 16, v174
	v_and_b32_e32 v99, 0xffff0000, v174
	v_lshlrev_b32_e32 v102, 16, v168
	v_and_b32_e32 v103, 0xffff0000, v168
	v_pk_fma_f32 v[86:87], v[86:87], v[96:97], v[104:105] op_sel_hi:[1,0,1]
	v_lshlrev_b32_e32 v104, 16, v171
	v_and_b32_e32 v105, 0xffff0000, v171
	v_lshlrev_b32_e32 v100, 16, v175
	v_and_b32_e32 v101, 0xffff0000, v175
	v_pk_fma_f32 v[98:99], v[88:89], v[96:97], v[98:99] op_sel_hi:[1,0,1]
	v_pk_fma_f32 v[84:85], v[84:85], v[96:97], v[102:103] op_sel_hi:[1,0,1]
	v_lshlrev_b32_e32 v102, 16, v170
	v_and_b32_e32 v103, 0xffff0000, v170
	v_pk_fma_f32 v[104:105], v[82:83], v[96:97], v[104:105] op_sel_hi:[1,0,1]
	v_mul_f32_e32 v82, v93, v93
	v_mul_f32_e32 v83, v95, v95
	v_pk_fma_f32 v[100:101], v[90:91], v[96:97], v[100:101] op_sel_hi:[1,0,1]
	v_pk_fma_f32 v[96:97], v[80:81], v[96:97], v[102:103] op_sel_hi:[1,0,1]
	v_mul_f32_e32 v81, v99, v99
	v_fmac_f32_e32 v82, v92, v92
	v_fmac_f32_e32 v83, v94, v94
	v_cvt_pk_bf16_f32 v88, v92, v93
	v_mul_f32_e32 v80, v101, v101
	v_fmac_f32_e32 v81, v98, v98
	v_add_f32_e32 v82, v82, v83
	v_mul_f32_e32 v83, v85, v85
	v_mul_f32_e32 v92, v87, v87
	v_fmac_f32_e32 v80, v100, v100
	v_add_f32_e32 v81, v81, v82
	v_mul_f32_e32 v82, v97, v97
	v_fmac_f32_e32 v83, v84, v84
	v_fmac_f32_e32 v92, v86, v86
	v_add_f32_e32 v80, v80, v81
	v_mul_f32_e32 v81, v105, v105
	v_fmac_f32_e32 v82, v96, v96
	v_add_f32_e32 v83, v83, v92
	v_fmac_f32_e32 v81, v104, v104
	v_add_f32_e32 v82, v82, v83
	v_add_f32_e32 v81, v81, v82
	v_add_f32_e32 v83, v80, v81
	v_cvt_pk_bf16_f32 v89, v94, v95
	ds_bpermute_b32 v94, v112, v83
	v_lshl_add_u64 v[80:81], s[42:43], 0, v[228:229]
	v_lshl_add_u64 v[92:93], v[204:205], 1, v[80:81]
	v_cvt_pk_bf16_f32 v90, v98, v99
	v_cvt_pk_bf16_f32 v91, v100, v101
	s_waitcnt lgkmcnt(0)
	v_add_f32_e32 v80, v83, v94
	ds_bpermute_b32 v81, v113, v80
	v_cvt_pk_bf16_f32 v82, v84, v85
	v_cvt_pk_bf16_f32 v83, v86, v87
	v_cvt_pk_bf16_f32 v84, v96, v97
	v_cvt_pk_bf16_f32 v85, v104, v105
	global_store_dwordx4 v[92:93], v[88:91], off
	global_store_dwordx4 v[92:93], v[82:85], off offset:256
	s_and_saveexec_b64 s[0:1], vcc
	s_cbranch_execz .LBB0_1254
	v_lshl_add_u64 v[82:83], v[226:227], 2, s[36:37]
	s_waitcnt lgkmcnt(0)
	v_add_f32_e32 v80, v80, v81
	global_atomic_add_f32 v[82:83], v80, off
; __device__ __forceinline__ u32x4 pack8(f32x4 a, f32x4 b) { u32x4 w; w.x = pk2(a[0], a[1]); w.y = pk2(a[2], a[3]); w.z = pk2(b[0], b[1]); w.w = pk2(b[2], b[3]); return w; }
;     __device__ __forceinline__ void operator()(const Acc& acc, const pg8::Unit& u, int wid) const {
;     ...
;             for (int m = 0; m < 4; ++m) {
;                 const int row = row0 + ai * 128 + m * 16; float sq = 0.f;
;                 const float rr = ssq2 ? __builtin_amdgcn_rcpf(r2[ai * 4 + m] * (1.f / 1024.f) + EPS) : 1.f;
; #pragma unroll
;                 for (int bj = 0; bj < 2; ++bj) {
;                     const u32x4 b4 = bv[ai][m][bj];
;                     const f32x4 o0 = (f32x4){bflo(b4.x), bfhi(b4.x), bflo(b4.y), bfhi(b4.y)} + acc[ai][bj][m][0] * rr;
;                     const f32x4 o1 = (f32x4){bflo(b4.z), bfhi(b4.z), bflo(b4.w), bfhi(b4.w)} + acc[ai][bj][m][1] * rr;
;                     *(u32x4*)(hb + (size_t)row * 1024 + col0 + bj * 128) = pack8(o0, o1);
;                     sq += (o0[0] * o0[0] + o0[1] * o0[1]) + (o0[2] * o0[2] + o0[3] * o0[3]) + (o1[0] * o1[0] + o1[1] * o1[1]) + (o1[2] * o1[2] + o1[3] * o1[3]);
;                 }
;                 if (ssq_out) { sq += __shfl_xor(sq, 16); sq += __shfl_xor(sq, 32); if (fq == 0) atomicAdd(ssq_out + row, sq); }
.LBB0_1254:
	s_or_b64 exec, exec, s[0:1]
	v_fmamk_f32 v80, v250, 0x3a800000, v245
	v_rcp_f32_e32 v80, v80
	v_lshlrev_b32_e32 v82, 16, v164
	v_and_b32_e32 v83, 0xffff0000, v164
	v_lshlrev_b32_e32 v84, 16, v165
	v_and_b32_e32 v85, 0xffff0000, v165
	v_lshlrev_b32_e32 v88, 16, v161
	v_and_b32_e32 v89, 0xffff0000, v161
	s_waitcnt lgkmcnt(0)
	v_pk_fma_f32 v[78:79], v[78:79], v[80:81], v[84:85] op_sel_hi:[1,0,1]
	v_pk_fma_f32 v[76:77], v[76:77], v[80:81], v[82:83] op_sel_hi:[1,0,1]
	v_lshlrev_b32_e32 v82, 16, v166
	v_and_b32_e32 v83, 0xffff0000, v166
	v_lshlrev_b32_e32 v86, 16, v160
	v_and_b32_e32 v87, 0xffff0000, v160
	v_pk_fma_f32 v[70:71], v[70:71], v[80:81], v[88:89] op_sel_hi:[1,0,1]
	v_lshlrev_b32_e32 v88, 16, v163
	v_and_b32_e32 v89, 0xffff0000, v163
	v_lshlrev_b32_e32 v84, 16, v167
	v_and_b32_e32 v85, 0xffff0000, v167
	v_pk_fma_f32 v[82:83], v[72:73], v[80:81], v[82:83] op_sel_hi:[1,0,1]
	v_pk_fma_f32 v[68:69], v[68:69], v[80:81], v[86:87] op_sel_hi:[1,0,1]
	v_lshlrev_b32_e32 v86, 16, v162
	v_and_b32_e32 v87, 0xffff0000, v162
	v_pk_fma_f32 v[88:89], v[66:67], v[80:81], v[88:89] op_sel_hi:[1,0,1]
	v_mul_f32_e32 v66, v77, v77
	v_mul_f32_e32 v67, v79, v79
	v_pk_fma_f32 v[84:85], v[74:75], v[80:81], v[84:85] op_sel_hi:[1,0,1]
	v_pk_fma_f32 v[80:81], v[64:65], v[80:81], v[86:87] op_sel_hi:[1,0,1]
	v_mul_f32_e32 v65, v83, v83
	v_fmac_f32_e32 v66, v76, v76
	v_fmac_f32_e32 v67, v78, v78
	v_cvt_pk_bf16_f32 v72, v76, v77
	v_mul_f32_e32 v64, v85, v85
	v_fmac_f32_e32 v65, v82, v82
	v_add_f32_e32 v66, v66, v67
	v_mul_f32_e32 v67, v69, v69
	v_mul_f32_e32 v76, v71, v71
	v_fmac_f32_e32 v64, v84, v84
	v_add_f32_e32 v65, v65, v66
	v_mul_f32_e32 v66, v81, v81
	v_fmac_f32_e32 v67, v68, v68
	v_fmac_f32_e32 v76, v70, v70
	v_add_f32_e32 v64, v64, v65
	v_mul_f32_e32 v65, v89, v89
	v_fmac_f32_e32 v66, v80, v80
	v_add_f32_e32 v67, v67, v76
	v_fmac_f32_e32 v65, v88, v88
	v_add_f32_e32 v66, v66, v67
	v_add_f32_e32 v65, v65, v66
	v_add_f32_e32 v67, v64, v65
	v_cvt_pk_bf16_f32 v73, v78, v79
	ds_bpermute_b32 v78, v112, v67
	v_lshl_add_u64 v[64:65], s[42:43], 0, v[224:225]
	v_lshl_add_u64 v[76:77], v[204:205], 1, v[64:65]
	v_cvt_pk_bf16_f32 v74, v82, v83
	v_cvt_pk_bf16_f32 v75, v84, v85
	s_waitcnt lgkmcnt(0)
	v_add_f32_e32 v64, v67, v78
	ds_bpermute_b32 v65, v113, v64
	v_cvt_pk_bf16_f32 v66, v68, v69
	v_cvt_pk_bf16_f32 v67, v70, v71
	v_cvt_pk_bf16_f32 v68, v80, v81
	v_cvt_pk_bf16_f32 v69, v88, v89
	global_store_dwordx4 v[76:77], v[72:75], off
	global_store_dwordx4 v[76:77], v[66:69], off offset:256
	s_and_saveexec_b64 s[0:1], vcc
	s_cbranch_execz .LBB0_1256
	v_lshl_add_u64 v[66:67], v[222:223], 2, s[36:37]
	s_waitcnt lgkmcnt(0)
	v_add_f32_e32 v64, v64, v65
	global_atomic_add_f32 v[66:67], v64, off
.LBB0_1256:
	s_or_b64 exec, exec, s[0:1]
	v_fmamk_f32 v64, v249, 0x3a800000, v245
	v_rcp_f32_e32 v64, v64
	v_lshlrev_b32_e32 v66, 16, v156
	v_and_b32_e32 v67, 0xffff0000, v156
	v_lshlrev_b32_e32 v68, 16, v157
	v_and_b32_e32 v69, 0xffff0000, v157
	v_lshlrev_b32_e32 v72, 16, v153
	v_and_b32_e32 v73, 0xffff0000, v153
	s_waitcnt lgkmcnt(0)
	v_pk_fma_f32 v[62:63], v[62:63], v[64:65], v[68:69] op_sel_hi:[1,0,1]
	v_pk_fma_f32 v[60:61], v[60:61], v[64:65], v[66:67] op_sel_hi:[1,0,1]
	v_lshlrev_b32_e32 v66, 16, v158
	v_and_b32_e32 v67, 0xffff0000, v158
	v_lshlrev_b32_e32 v70, 16, v152
	v_and_b32_e32 v71, 0xffff0000, v152
	v_pk_fma_f32 v[54:55], v[54:55], v[64:65], v[72:73] op_sel_hi:[1,0,1]
	v_lshlrev_b32_e32 v72, 16, v155
	v_and_b32_e32 v73, 0xffff0000, v155
	v_lshlrev_b32_e32 v68, 16, v159
	v_and_b32_e32 v69, 0xffff0000, v159
	v_pk_fma_f32 v[66:67], v[56:57], v[64:65], v[66:67] op_sel_hi:[1,0,1]
	v_pk_fma_f32 v[52:53], v[52:53], v[64:65], v[70:71] op_sel_hi:[1,0,1]
	v_lshlrev_b32_e32 v70, 16, v154
	v_and_b32_e32 v71, 0xffff0000, v154
	v_pk_fma_f32 v[72:73], v[50:51], v[64:65], v[72:73] op_sel_hi:[1,0,1]
	v_mul_f32_e32 v50, v61, v61
	v_mul_f32_e32 v51, v63, v63
	v_pk_fma_f32 v[68:69], v[58:59], v[64:65], v[68:69] op_sel_hi:[1,0,1]
	v_pk_fma_f32 v[64:65], v[48:49], v[64:65], v[70:71] op_sel_hi:[1,0,1]
	v_mul_f32_e32 v49, v67, v67
	v_fmac_f32_e32 v50, v60, v60
	v_fmac_f32_e32 v51, v62, v62
	v_cvt_pk_bf16_f32 v56, v60, v61
	v_mul_f32_e32 v48, v69, v69
	v_fmac_f32_e32 v49, v66, v66
	v_add_f32_e32 v50, v50, v51
	v_mul_f32_e32 v51, v53, v53
	v_mul_f32_e32 v60, v55, v55
	v_fmac_f32_e32 v48, v68, v68
	v_add_f32_e32 v49, v49, v50
	v_mul_f32_e32 v50, v65, v65
	v_fmac_f32_e32 v51, v52, v52
	v_fmac_f32_e32 v60, v54, v54
	v_add_f32_e32 v48, v48, v49
	v_mul_f32_e32 v49, v73, v73
	v_fmac_f32_e32 v50, v64, v64
	v_add_f32_e32 v51, v51, v60
	v_fmac_f32_e32 v49, v72, v72
	v_add_f32_e32 v50, v50, v51
	v_add_f32_e32 v49, v49, v50
	v_add_f32_e32 v51, v48, v49
	v_cvt_pk_bf16_f32 v57, v62, v63
	ds_bpermute_b32 v62, v112, v51
	v_lshl_add_u64 v[48:49], s[42:43], 0, v[220:221]
	v_lshl_add_u64 v[60:61], v[204:205], 1, v[48:49]
	v_cvt_pk_bf16_f32 v58, v66, v67
	v_cvt_pk_bf16_f32 v59, v68, v69
	s_waitcnt lgkmcnt(0)
	v_add_f32_e32 v48, v51, v62
	ds_bpermute_b32 v49, v113, v48
	v_cvt_pk_bf16_f32 v50, v52, v53
	v_cvt_pk_bf16_f32 v51, v54, v55
	v_cvt_pk_bf16_f32 v52, v64, v65
	v_cvt_pk_bf16_f32 v53, v72, v73
	global_store_dwordx4 v[60:61], v[56:59], off
	global_store_dwordx4 v[60:61], v[50:53], off offset:256
	s_and_saveexec_b64 s[0:1], vcc
	s_cbranch_execz .LBB0_1258
	v_lshl_add_u64 v[50:51], v[214:215], 2, s[36:37]
	s_waitcnt lgkmcnt(0)
	v_add_f32_e32 v48, v48, v49
	global_atomic_add_f32 v[50:51], v48, off
; __device__ __forceinline__ u32x4 pack8(f32x4 a, f32x4 b) { u32x4 w; w.x = pk2(a[0], a[1]); w.y = pk2(a[2], a[3]); w.z = pk2(b[0], b[1]); w.w = pk2(b[2], b[3]); return w; }
;     __device__ __forceinline__ void operator()(const Acc& acc, const pg8::Unit& u, int wid) const {
;     ...
;             for (int m = 0; m < 4; ++m) {
;                 const int row = row0 + ai * 128 + m * 16; float sq = 0.f;
;                 const float rr = ssq2 ? __builtin_amdgcn_rcpf(r2[ai * 4 + m] * (1.f / 1024.f) + EPS) : 1.f;
; #pragma unroll
;                 for (int bj = 0; bj < 2; ++bj) {
;                     const u32x4 b4 = bv[ai][m][bj];
;                     const f32x4 o0 = (f32x4){bflo(b4.x), bfhi(b4.x), bflo(b4.y), bfhi(b4.y)} + acc[ai][bj][m][0] * rr;
;                     const f32x4 o1 = (f32x4){bflo(b4.z), bfhi(b4.z), bflo(b4.w), bfhi(b4.w)} + acc[ai][bj][m][1] * rr;
;                     *(u32x4*)(hb + (size_t)row * 1024 + col0 + bj * 128) = pack8(o0, o1);
;                     sq += (o0[0] * o0[0] + o0[1] * o0[1]) + (o0[2] * o0[2] + o0[3] * o0[3]) + (o1[0] * o1[0] + o1[1] * o1[1]) + (o1[2] * o1[2] + o1[3] * o1[3]);
;                 }
;                 if (ssq_out) { sq += __shfl_xor(sq, 16); sq += __shfl_xor(sq, 32); if (fq == 0) atomicAdd(ssq_out + row, sq); }
.LBB0_1258:
	s_or_b64 exec, exec, s[0:1]
	v_fmamk_f32 v48, v248, 0x3a800000, v245
	v_rcp_f32_e32 v48, v48
	v_lshlrev_b32_e32 v50, 16, v148
	v_and_b32_e32 v51, 0xffff0000, v148
	v_lshlrev_b32_e32 v52, 16, v149
	v_and_b32_e32 v53, 0xffff0000, v149
	v_lshlrev_b32_e32 v56, 16, v145
	v_and_b32_e32 v57, 0xffff0000, v145
	s_waitcnt lgkmcnt(0)
	v_pk_fma_f32 v[46:47], v[46:47], v[48:49], v[52:53] op_sel_hi:[1,0,1]
	v_pk_fma_f32 v[44:45], v[44:45], v[48:49], v[50:51] op_sel_hi:[1,0,1]
	v_lshlrev_b32_e32 v50, 16, v150
	v_and_b32_e32 v51, 0xffff0000, v150
	v_lshlrev_b32_e32 v54, 16, v144
	v_and_b32_e32 v55, 0xffff0000, v144
	v_pk_fma_f32 v[38:39], v[38:39], v[48:49], v[56:57] op_sel_hi:[1,0,1]
	v_lshlrev_b32_e32 v56, 16, v147
	v_and_b32_e32 v57, 0xffff0000, v147
	v_lshlrev_b32_e32 v52, 16, v151
	v_and_b32_e32 v53, 0xffff0000, v151
	v_pk_fma_f32 v[50:51], v[40:41], v[48:49], v[50:51] op_sel_hi:[1,0,1]
	v_pk_fma_f32 v[36:37], v[36:37], v[48:49], v[54:55] op_sel_hi:[1,0,1]
	v_lshlrev_b32_e32 v54, 16, v146
	v_and_b32_e32 v55, 0xffff0000, v146
	v_pk_fma_f32 v[56:57], v[34:35], v[48:49], v[56:57] op_sel_hi:[1,0,1]
	v_mul_f32_e32 v34, v45, v45
	v_mul_f32_e32 v35, v47, v47
	v_pk_fma_f32 v[52:53], v[42:43], v[48:49], v[52:53] op_sel_hi:[1,0,1]
	v_pk_fma_f32 v[48:49], v[32:33], v[48:49], v[54:55] op_sel_hi:[1,0,1]
	v_mul_f32_e32 v33, v51, v51
	v_fmac_f32_e32 v34, v44, v44
	v_fmac_f32_e32 v35, v46, v46
	v_cvt_pk_bf16_f32 v40, v44, v45
	v_mul_f32_e32 v32, v53, v53
	v_fmac_f32_e32 v33, v50, v50
	v_add_f32_e32 v34, v34, v35
	v_mul_f32_e32 v35, v37, v37
	v_mul_f32_e32 v44, v39, v39
	v_fmac_f32_e32 v32, v52, v52
	v_add_f32_e32 v33, v33, v34
	v_mul_f32_e32 v34, v49, v49
	v_fmac_f32_e32 v35, v36, v36
	v_fmac_f32_e32 v44, v38, v38
	v_add_f32_e32 v32, v32, v33
	v_mul_f32_e32 v33, v57, v57
	v_fmac_f32_e32 v34, v48, v48
	v_add_f32_e32 v35, v35, v44
	v_fmac_f32_e32 v33, v56, v56
	v_add_f32_e32 v34, v34, v35
	v_add_f32_e32 v33, v33, v34
	v_add_f32_e32 v35, v32, v33
	v_cvt_pk_bf16_f32 v41, v46, v47
	ds_bpermute_b32 v46, v112, v35
	v_lshl_add_u64 v[32:33], s[42:43], 0, v[218:219]
	v_lshl_add_u64 v[44:45], v[204:205], 1, v[32:33]
	v_cvt_pk_bf16_f32 v42, v50, v51
	v_cvt_pk_bf16_f32 v43, v52, v53
	s_waitcnt lgkmcnt(0)
	v_add_f32_e32 v32, v35, v46
	ds_bpermute_b32 v33, v113, v32
	v_cvt_pk_bf16_f32 v34, v36, v37
	v_cvt_pk_bf16_f32 v35, v38, v39
	v_cvt_pk_bf16_f32 v36, v48, v49
	v_cvt_pk_bf16_f32 v37, v56, v57
	global_store_dwordx4 v[44:45], v[40:43], off
	global_store_dwordx4 v[44:45], v[34:37], off offset:256
	s_and_saveexec_b64 s[0:1], vcc
	s_cbranch_execz .LBB0_1260
	v_lshl_add_u64 v[34:35], v[216:217], 2, s[36:37]
	s_waitcnt lgkmcnt(0)
	v_add_f32_e32 v32, v32, v33
	global_atomic_add_f32 v[34:35], v32, off
; __device__ __forceinline__ u32x4 pack8(f32x4 a, f32x4 b) { u32x4 w; w.x = pk2(a[0], a[1]); w.y = pk2(a[2], a[3]); w.z = pk2(b[0], b[1]); w.w = pk2(b[2], b[3]); return w; }
;     __device__ __forceinline__ void operator()(const Acc& acc, const pg8::Unit& u, int wid) const {
;     ...
;             for (int m = 0; m < 4; ++m) {
;                 const int row = row0 + ai * 128 + m * 16; float sq = 0.f;
;                 const float rr = ssq2 ? __builtin_amdgcn_rcpf(r2[ai * 4 + m] * (1.f / 1024.f) + EPS) : 1.f;
; #pragma unroll
;                 for (int bj = 0; bj < 2; ++bj) {
;                     const u32x4 b4 = bv[ai][m][bj];
;                     const f32x4 o0 = (f32x4){bflo(b4.x), bfhi(b4.x), bflo(b4.y), bfhi(b4.y)} + acc[ai][bj][m][0] * rr;
;                     const f32x4 o1 = (f32x4){bflo(b4.z), bfhi(b4.z), bflo(b4.w), bfhi(b4.w)} + acc[ai][bj][m][1] * rr;
;                     *(u32x4*)(hb + (size_t)row * 1024 + col0 + bj * 128) = pack8(o0, o1);
;                     sq += (o0[0] * o0[0] + o0[1] * o0[1]) + (o0[2] * o0[2] + o0[3] * o0[3]) + (o1[0] * o1[0] + o1[1] * o1[1]) + (o1[2] * o1[2] + o1[3] * o1[3]);
;                 }
;                 if (ssq_out) { sq += __shfl_xor(sq, 16); sq += __shfl_xor(sq, 32); if (fq == 0) atomicAdd(ssq_out + row, sq); }
.LBB0_1260:
	s_or_b64 exec, exec, s[0:1]
	v_fmamk_f32 v32, v247, 0x3a800000, v245
	v_rcp_f32_e32 v32, v32
	s_waitcnt vmcnt(12)
	v_lshlrev_b32_e32 v34, 16, v132
	v_and_b32_e32 v35, 0xffff0000, v132
	v_lshlrev_b32_e32 v36, 16, v133
	v_and_b32_e32 v37, 0xffff0000, v133
	v_lshlrev_b32_e32 v40, 16, v125
	v_and_b32_e32 v41, 0xffff0000, v125
	s_waitcnt lgkmcnt(0)
	v_pk_fma_f32 v[30:31], v[30:31], v[32:33], v[36:37] op_sel_hi:[1,0,1]
	v_pk_fma_f32 v[28:29], v[28:29], v[32:33], v[34:35] op_sel_hi:[1,0,1]
	v_lshlrev_b32_e32 v34, 16, v134
	v_and_b32_e32 v35, 0xffff0000, v134
	v_lshlrev_b32_e32 v38, 16, v124
	v_and_b32_e32 v39, 0xffff0000, v124
	v_pk_fma_f32 v[22:23], v[22:23], v[32:33], v[40:41] op_sel_hi:[1,0,1]
	v_lshlrev_b32_e32 v40, 16, v127
	v_and_b32_e32 v41, 0xffff0000, v127
	v_lshlrev_b32_e32 v36, 16, v135
	v_and_b32_e32 v37, 0xffff0000, v135
	v_pk_fma_f32 v[34:35], v[24:25], v[32:33], v[34:35] op_sel_hi:[1,0,1]
	v_pk_fma_f32 v[20:21], v[20:21], v[32:33], v[38:39] op_sel_hi:[1,0,1]
	v_lshlrev_b32_e32 v38, 16, v126
	v_and_b32_e32 v39, 0xffff0000, v126
	v_pk_fma_f32 v[40:41], v[18:19], v[32:33], v[40:41] op_sel_hi:[1,0,1]
	v_mul_f32_e32 v18, v29, v29
	v_mul_f32_e32 v19, v31, v31
	v_pk_fma_f32 v[36:37], v[26:27], v[32:33], v[36:37] op_sel_hi:[1,0,1]
	v_pk_fma_f32 v[32:33], v[16:17], v[32:33], v[38:39] op_sel_hi:[1,0,1]
	v_mul_f32_e32 v17, v35, v35
	v_fmac_f32_e32 v18, v28, v28
	v_fmac_f32_e32 v19, v30, v30
	v_cvt_pk_bf16_f32 v24, v28, v29
	v_mul_f32_e32 v16, v37, v37
	v_fmac_f32_e32 v17, v34, v34
	v_add_f32_e32 v18, v18, v19
	v_mul_f32_e32 v19, v21, v21
	v_mul_f32_e32 v28, v23, v23
	v_fmac_f32_e32 v16, v36, v36
	v_add_f32_e32 v17, v17, v18
	v_mul_f32_e32 v18, v33, v33
	v_fmac_f32_e32 v19, v20, v20
	v_fmac_f32_e32 v28, v22, v22
	v_add_f32_e32 v16, v16, v17
	v_mul_f32_e32 v17, v41, v41
	v_fmac_f32_e32 v18, v32, v32
	v_add_f32_e32 v19, v19, v28
	v_fmac_f32_e32 v17, v40, v40
	v_add_f32_e32 v18, v18, v19
	v_add_f32_e32 v17, v17, v18
	v_add_f32_e32 v19, v16, v17
	v_cvt_pk_bf16_f32 v25, v30, v31
	ds_bpermute_b32 v30, v112, v19
	v_lshlrev_b64 v[16:17], 11, v[210:211]
	v_lshl_add_u64 v[16:17], s[42:43], 0, v[16:17]
	v_lshl_add_u64 v[28:29], v[204:205], 1, v[16:17]
	v_cvt_pk_bf16_f32 v26, v34, v35
	s_waitcnt lgkmcnt(0)
	v_add_f32_e32 v16, v19, v30
	ds_bpermute_b32 v17, v113, v16
	v_cvt_pk_bf16_f32 v27, v36, v37
	v_cvt_pk_bf16_f32 v18, v20, v21
	v_cvt_pk_bf16_f32 v19, v22, v23
	v_cvt_pk_bf16_f32 v20, v32, v33
	v_cvt_pk_bf16_f32 v21, v40, v41
	global_store_dwordx4 v[28:29], v[24:27], off
	global_store_dwordx4 v[28:29], v[18:21], off offset:256
	s_and_saveexec_b64 s[0:1], vcc
	s_cbranch_execz .LBB0_1262
	v_lshl_add_u64 v[18:19], v[210:211], 2, s[36:37]
	s_waitcnt lgkmcnt(0)
	v_add_f32_e32 v16, v16, v17
	global_atomic_add_f32 v[18:19], v16, off
.LBB0_1262:
	s_or_b64 exec, exec, s[0:1]
	v_fmamk_f32 v16, v246, 0x3a800000, v245
	v_rcp_f32_e32 v16, v16
	v_lshlrev_b32_e32 v18, 16, v140
	v_and_b32_e32 v19, 0xffff0000, v140
	v_lshlrev_b32_e32 v20, 16, v141
	v_and_b32_e32 v21, 0xffff0000, v141
	v_lshlrev_b32_e32 v24, 16, v137
	v_and_b32_e32 v25, 0xffff0000, v137
	s_waitcnt lgkmcnt(0)
	v_pk_fma_f32 v[14:15], v[14:15], v[16:17], v[20:21] op_sel_hi:[1,0,1]
	v_pk_fma_f32 v[12:13], v[12:13], v[16:17], v[18:19] op_sel_hi:[1,0,1]
	v_lshlrev_b32_e32 v18, 16, v142
	v_and_b32_e32 v19, 0xffff0000, v142
	v_lshlrev_b32_e32 v22, 16, v136
	v_and_b32_e32 v23, 0xffff0000, v136
	v_pk_fma_f32 v[6:7], v[6:7], v[16:17], v[24:25] op_sel_hi:[1,0,1]
	v_lshlrev_b32_e32 v24, 16, v139
	v_and_b32_e32 v25, 0xffff0000, v139
	v_lshlrev_b32_e32 v20, 16, v143
	v_and_b32_e32 v21, 0xffff0000, v143
	v_pk_fma_f32 v[18:19], v[8:9], v[16:17], v[18:19] op_sel_hi:[1,0,1]
	v_pk_fma_f32 v[4:5], v[4:5], v[16:17], v[22:23] op_sel_hi:[1,0,1]
	v_lshlrev_b32_e32 v22, 16, v138
	v_and_b32_e32 v23, 0xffff0000, v138
	v_pk_fma_f32 v[24:25], v[2:3], v[16:17], v[24:25] op_sel_hi:[1,0,1]
	v_mul_f32_e32 v2, v13, v13
	v_mul_f32_e32 v3, v15, v15
	v_pk_fma_f32 v[20:21], v[10:11], v[16:17], v[20:21] op_sel_hi:[1,0,1]
	v_pk_fma_f32 v[16:17], v[0:1], v[16:17], v[22:23] op_sel_hi:[1,0,1]
	v_mul_f32_e32 v1, v19, v19
	v_fmac_f32_e32 v2, v12, v12
	v_fmac_f32_e32 v3, v14, v14
	v_cvt_pk_bf16_f32 v8, v12, v13
	v_mul_f32_e32 v0, v21, v21
	v_fmac_f32_e32 v1, v18, v18
	v_add_f32_e32 v2, v2, v3
	v_mul_f32_e32 v3, v5, v5
	v_mul_f32_e32 v12, v7, v7
	v_fmac_f32_e32 v0, v20, v20
	v_add_f32_e32 v1, v1, v2
	v_mul_f32_e32 v2, v17, v17
	v_fmac_f32_e32 v3, v4, v4
	v_fmac_f32_e32 v12, v6, v6
	v_add_f32_e32 v0, v0, v1
	v_mul_f32_e32 v1, v25, v25
	v_fmac_f32_e32 v2, v16, v16
	v_add_f32_e32 v3, v3, v12
	v_fmac_f32_e32 v1, v24, v24
	v_add_f32_e32 v2, v2, v3
	v_add_f32_e32 v1, v1, v2
	v_add_f32_e32 v3, v0, v1
	v_cvt_pk_bf16_f32 v9, v14, v15
	ds_bpermute_b32 v14, v112, v3
	v_lshlrev_b64 v[0:1], 11, v[206:207]
	v_lshl_add_u64 v[0:1], s[42:43], 0, v[0:1]
	v_lshl_add_u64 v[12:13], v[204:205], 1, v[0:1]
	v_cvt_pk_bf16_f32 v10, v18, v19
	s_waitcnt lgkmcnt(0)
	v_add_f32_e32 v0, v3, v14
	ds_bpermute_b32 v1, v113, v0
	v_cvt_pk_bf16_f32 v11, v20, v21
	v_cvt_pk_bf16_f32 v2, v4, v5
	v_cvt_pk_bf16_f32 v3, v6, v7
	v_cvt_pk_bf16_f32 v4, v16, v17
	v_cvt_pk_bf16_f32 v5, v24, v25
	global_store_dwordx4 v[12:13], v[8:11], off
	global_store_dwordx4 v[12:13], v[2:5], off offset:256
	s_and_saveexec_b64 s[0:1], vcc
	s_cbranch_execz .LBB0_1264
	v_lshl_add_u64 v[2:3], v[206:207], 2, s[36:37]
	s_waitcnt lgkmcnt(0)
	v_add_f32_e32 v0, v0, v1
	global_atomic_add_f32 v[2:3], v0, off

;     __device__ __forceinline__ void operator()(const Acc& acc, const pg8::Unit& u, int wid) const {
;     ...
;         for (int ai = 0; ai < 2; ++ai)
; #pragma unroll
;             for (int mp = 0; mp < 2; ++mp) {
;                 u32x4 hv[2][2], pw[2][2]; float scv[2];
; #pragma unroll
;                 for (int mm = 0; mm < 2; ++mm) {
;                     const int row = row0 + ai * 128 + (2 * mp + mm) * 16;
;                     scv[mm] = ssq[row];
; #pragma unroll
;                     for (int bj = 0; bj < 2; ++bj) { const size_t off = (size_t)row * 1024 + col0 + bj * 128; hv[mm][bj] = *(const u32x4*)(hbase + off); pw[mm][bj] = *(const u32x4*)(pp + off); }
;                 }
; #pragma unroll
;                 for (int mm = 0; mm < 2; ++mm) {
;                     const int m = 2 * mp + mm, row = row0 + ai * 128 + m * 16; float sq = 0.f;
;                     const float sc = __builtin_amdgcn_rsqf(scv[mm] * (1.f / 1024.f) + EPS);
; #pragma unroll
;                     for (int bj = 0; bj < 2; ++bj) {
;                         const size_t off = (size_t)row * 1024 + col0 + bj * 128;
;                         const u32x4 pwv = pw[mm][bj], hw = hv[mm][bj];
;                         const f32x4 p0 = (f32x4){bflo(pwv.x), bfhi(pwv.x), bflo(pwv.y), bfhi(pwv.y)}, p1 = (f32x4){bflo(pwv.z), bfhi(pwv.z), bflo(pwv.w), bfhi(pwv.w)};
;                         f32x4 g0 = acc[ai][bj][m][0] * sc, g1 = acc[ai][bj][m][1] * sc;
; #pragma unroll
;                         for (int e = 0; e < 4; ++e) { g0[e] = __builtin_amdgcn_rcpf(1.f + __builtin_amdgcn_exp2f(-1.4426950408889634f * g0[e])); g1[e] = __builtin_amdgcn_rcpf(1.f + __builtin_amdgcn_exp2f(-1.4426950408889634f * g1[e])); }
;                         const f32x4 o0 = (f32x4){bflo(hw.x), bfhi(hw.x), bflo(hw.y), bfhi(hw.y)} + g0 * p0;
;                         const f32x4 o1 = (f32x4){bflo(hw.z), bfhi(hw.z), bflo(hw.w), bfhi(hw.w)} + g1 * p1;
;                         if (fout) { *(f32x4*)(fout + off) = o0; *(f32x4*)(fout + off + 4) = o1; }
.LBB0_1356:
	s_andn2_b64 vcc, exec, s[40:41]
	v_mbcnt_lo_u32_b32 v128, -1, 0
	v_mbcnt_hi_u32_b32 v128, -1, v128
	s_cbranch_vccnz .LBB0_1358
	s_lshl_b32 s21, s60, 8
	v_ashrrev_i32_e32 v129, 1, v128
	s_or_b32 s21, s21, s69
	v_and_b32_e32 v129, -8, v129
	v_add_u32_e32 v164, s21, v129
	s_lshl_b32 s21, s28, 8
	s_add_i32 s21, s21, s3
	v_and_or_b32 v166, v128, 15, s21
	v_ashrrev_i32_e32 v167, 31, v166
	v_lshl_add_u64 v[160:161], v[166:167], 2, s[36:37]
	global_load_dword v173, v[160:161], off
	v_ashrrev_i32_e32 v165, 31, v164
	v_lshlrev_b64 v[128:129], 10, v[166:167]
	v_lshl_add_u64 v[162:163], v[128:129], 0, v[164:165]
	v_lshlrev_b64 v[128:129], 1, v[162:163]
	v_lshl_add_u64 v[130:131], s[48:49], 0, v[128:129]
	global_load_dwordx4 v[174:177], v[130:131], off
	v_lshl_add_u64 v[130:131], s[42:43], 0, v[128:129]
	global_load_dwordx4 v[178:181], v[130:131], off
	v_or_b32_e32 v130, 16, v166
	v_ashrrev_i32_e32 v131, 31, v130
	v_lshlrev_b64 v[132:133], 10, v[130:131]
	v_lshl_add_u64 v[190:191], v[132:133], 0, v[164:165]
	v_lshlrev_b64 v[132:133], 1, v[190:191]
	v_lshl_add_u64 v[128:129], v[128:129], 0, s[10:11]
	v_lshl_add_u64 v[130:131], v[130:131], 2, s[36:37]
	v_lshl_add_u64 v[134:135], v[132:133], 0, s[10:11]
	v_lshl_add_u64 v[140:141], s[48:49], 0, v[132:133]
	v_lshl_add_u64 v[132:133], s[42:43], 0, v[132:133]
	v_lshl_add_u64 v[142:143], s[48:49], 0, v[128:129]
	v_lshl_add_u64 v[128:129], s[42:43], 0, v[128:129]
	v_lshl_add_u64 v[194:195], s[48:49], 0, v[134:135]
	v_lshl_add_u64 v[196:197], s[42:43], 0, v[134:135]
	global_load_dwordx4 v[136:139], v[132:133], off
	global_load_dword v167, v[130:131], off
	global_load_dwordx4 v[182:185], v[142:143], off
	global_load_dwordx4 v[186:189], v[128:129], off
	s_nop 0
	global_load_dwordx4 v[132:135], v[194:195], off
	global_load_dwordx4 v[128:131], v[196:197], off
	s_nop 0
	global_load_dwordx4 v[140:143], v[140:141], off
	v_lshl_add_u64 v[192:193], v[162:163], 2, s[52:53]
	s_waitcnt vmcnt(0) lgkmcnt(0)
	v_fmamk_f32 v173, v173, 0x3a800000, v172
	v_rsq_f32_e32 v194, v173
	v_lshlrev_b32_e32 v196, 16, v176
	v_pk_mul_f32 v[120:121], v[120:121], v[194:195] op_sel_hi:[1,0]
	v_pk_mul_f32 v[126:127], v[126:127], v[194:195] op_sel_hi:[1,0]
	v_pk_mul_f32 v[124:125], v[124:125], v[194:195] op_sel_hi:[1,0]
	v_pk_mul_f32 v[122:123], v[122:123], v[194:195] op_sel_hi:[1,0]
	v_mul_f32_e32 v120, 0xbfb8aa3b, v120
	v_mul_f32_e32 v121, 0xbfb8aa3b, v121
	v_mul_f32_e32 v124, 0xbfb8aa3b, v124
	v_mul_f32_e32 v125, 0xbfb8aa3b, v125
	v_mul_f32_e32 v126, 0xbfb8aa3b, v126
	v_mul_f32_e32 v127, 0xbfb8aa3b, v127
	v_mul_f32_e32 v122, 0xbfb8aa3b, v122
	v_mul_f32_e32 v123, 0xbfb8aa3b, v123
	v_exp_f32_e32 v120, v120
	v_exp_f32_e32 v121, v121
	v_exp_f32_e32 v124, v124
	v_exp_f32_e32 v125, v125
	v_exp_f32_e32 v126, v126
	v_exp_f32_e32 v127, v127
	v_exp_f32_e32 v122, v122
	v_exp_f32_e32 v123, v123
	v_add_f32_e32 v120, 1.0, v120
	v_add_f32_e32 v121, 1.0, v121
	v_add_f32_e32 v124, 1.0, v124
	v_add_f32_e32 v125, 1.0, v125
	v_add_f32_e32 v126, 1.0, v126
	v_add_f32_e32 v127, 1.0, v127
	v_add_f32_e32 v122, 1.0, v122
	v_add_f32_e32 v123, 1.0, v123
	v_rcp_f32_e32 v120, v120
	v_rcp_f32_e32 v121, v121
	v_rcp_f32_e32 v124, v124
	v_rcp_f32_e32 v126, v126
	v_rcp_f32_e32 v127, v127
	v_rcp_f32_e32 v125, v125
	v_rcp_f32_e32 v122, v122
	v_rcp_f32_e32 v123, v123
	v_and_b32_e32 v197, 0xffff0000, v176
	v_lshlrev_b32_e32 v198, 16, v180
	v_and_b32_e32 v199, 0xffff0000, v180
	v_lshlrev_b32_e32 v200, 16, v174
	v_and_b32_e32 v201, 0xffff0000, v174
	v_lshlrev_b32_e32 v174, 16, v175
	v_and_b32_e32 v175, 0xffff0000, v175
	v_lshlrev_b32_e32 v202, 16, v178
	v_and_b32_e32 v203, 0xffff0000, v178
	v_lshlrev_b32_e32 v178, 16, v179
	v_and_b32_e32 v179, 0xffff0000, v179
	v_pk_mul_f32 v[116:117], v[116:117], v[194:195] op_sel_hi:[1,0]
	v_lshlrev_b32_e32 v176, 16, v177
	v_and_b32_e32 v177, 0xffff0000, v177
	v_lshlrev_b32_e32 v180, 16, v181
	v_and_b32_e32 v181, 0xffff0000, v181
	v_mul_f32_e32 v116, 0xbfb8aa3b, v116
	v_pk_fma_f32 v[120:121], v[120:121], v[196:197], v[198:199]
	v_pk_fma_f32 v[126:127], v[126:127], v[174:175], v[178:179]
	v_pk_fma_f32 v[124:125], v[124:125], v[200:201], v[202:203]
	v_pk_fma_f32 v[122:123], v[122:123], v[176:177], v[180:181]
	global_store_dwordx4 v[192:193], v[124:127], off
	global_store_dwordx4 v[192:193], v[120:123], off offset:16
	v_pk_mul_f32 v[112:113], v[112:113], v[194:195] op_sel_hi:[1,0]
	v_lshlrev_b32_e32 v124, 16, v188
	v_exp_f32_e32 v120, v116
	v_mul_f32_e32 v116, 0xbfb8aa3b, v117
	v_exp_f32_e32 v121, v116
	v_pk_mul_f32 v[116:117], v[118:119], v[194:195] op_sel_hi:[1,0]
	v_add_f32_e32 v118, 1.0, v120
	v_mul_f32_e32 v116, 0xbfb8aa3b, v116
	v_mul_f32_e32 v117, 0xbfb8aa3b, v117
	v_exp_f32_e32 v116, v116
	v_exp_f32_e32 v117, v117
	v_rcp_f32_e32 v120, v118
	v_add_f32_e32 v118, 1.0, v121
	v_add_f32_e32 v116, 1.0, v116
	v_add_f32_e32 v117, 1.0, v117
	v_rcp_f32_e32 v121, v118
	v_rcp_f32_e32 v116, v116
	v_rcp_f32_e32 v117, v117
	v_lshlrev_b32_e32 v122, 16, v184
	v_and_b32_e32 v123, 0xffff0000, v184
	v_lshlrev_b32_e32 v118, 16, v185
	v_and_b32_e32 v119, 0xffff0000, v185
	v_and_b32_e32 v125, 0xffff0000, v188
	v_lshlrev_b32_e32 v126, 16, v189
	v_and_b32_e32 v127, 0xffff0000, v189
	v_mul_f32_e32 v112, 0xbfb8aa3b, v112
	v_pk_fma_f32 v[118:119], v[116:117], v[118:119], v[126:127]
	v_pk_fma_f32 v[116:117], v[120:121], v[122:123], v[124:125]
	v_exp_f32_e32 v120, v112
	v_mul_f32_e32 v112, 0xbfb8aa3b, v113
	v_exp_f32_e32 v121, v112
	v_pk_mul_f32 v[112:113], v[114:115], v[194:195] op_sel_hi:[1,0]
	v_add_f32_e32 v114, 1.0, v120
	v_mul_f32_e32 v112, 0xbfb8aa3b, v112
	v_mul_f32_e32 v113, 0xbfb8aa3b, v113
	v_exp_f32_e32 v112, v112
	v_exp_f32_e32 v113, v113
; __device__ __forceinline__ u32x4 pack8(f32x4 a, f32x4 b) { u32x4 w; w.x = pk2(a[0], a[1]); w.y = pk2(a[2], a[3]); w.z = pk2(b[0], b[1]); w.w = pk2(b[2], b[3]); return w; }
;     __device__ __forceinline__ void operator()(const Acc& acc, const pg8::Unit& u, int wid) const {
;     ...
;                 for (int mm = 0; mm < 2; ++mm) {
;                     const int m = 2 * mp + mm, row = row0 + ai * 128 + m * 16; float sq = 0.f;
;                     const float sc = __builtin_amdgcn_rsqf(scv[mm] * (1.f / 1024.f) + EPS);
; #pragma unroll
;                     for (int bj = 0; bj < 2; ++bj) {
;                         const size_t off = (size_t)row * 1024 + col0 + bj * 128;
;                         const u32x4 pwv = pw[mm][bj], hw = hv[mm][bj];
;                         const f32x4 p0 = (f32x4){bflo(pwv.x), bfhi(pwv.x), bflo(pwv.y), bfhi(pwv.y)}, p1 = (f32x4){bflo(pwv.z), bfhi(pwv.z), bflo(pwv.w), bfhi(pwv.w)};
;                         f32x4 g0 = acc[ai][bj][m][0] * sc, g1 = acc[ai][bj][m][1] * sc;
; #pragma unroll
;                         for (int e = 0; e < 4; ++e) { g0[e] = __builtin_amdgcn_rcpf(1.f + __builtin_amdgcn_exp2f(-1.4426950408889634f * g0[e])); g1[e] = __builtin_amdgcn_rcpf(1.f + __builtin_amdgcn_exp2f(-1.4426950408889634f * g1[e])); }
;                         const f32x4 o0 = (f32x4){bflo(hw.x), bfhi(hw.x), bflo(hw.y), bfhi(hw.y)} + g0 * p0;
;                         const f32x4 o1 = (f32x4){bflo(hw.z), bfhi(hw.z), bflo(hw.w), bfhi(hw.w)} + g1 * p1;
;                         if (fout) { *(f32x4*)(fout + off) = o0; *(f32x4*)(fout + off + 4) = o1; }
;                         if (hb_out) *(u32x4*)(hb_out + off) = pack8(o0, o1);
;                         sq += (o0[0] * o0[0] + o0[1] * o0[1]) + (o0[2] * o0[2] + o0[3] * o0[3]) + (o1[0] * o1[0] + o1[1] * o1[1]) + (o1[2] * o1[2] + o1[3] * o1[3]);
;                     }
;                     if (ssq_out) { sq += __shfl_xor(sq, 16); sq += __shfl_xor(sq, 32); if (fq == 0) atomicAdd(ssq_out + row, sq); }
	v_rcp_f32_e32 v120, v114
	v_add_f32_e32 v114, 1.0, v121
	v_add_f32_e32 v112, 1.0, v112
	v_add_f32_e32 v113, 1.0, v113
	v_rcp_f32_e32 v121, v114
	v_rcp_f32_e32 v112, v112
	v_rcp_f32_e32 v113, v113
	v_lshlrev_b32_e32 v122, 16, v182
	v_and_b32_e32 v123, 0xffff0000, v182
	v_lshlrev_b32_e32 v114, 16, v183
	v_and_b32_e32 v115, 0xffff0000, v183
	v_lshlrev_b32_e32 v124, 16, v186
	v_and_b32_e32 v125, 0xffff0000, v186
	v_lshlrev_b32_e32 v126, 16, v187
	v_and_b32_e32 v127, 0xffff0000, v187
	v_pk_fma_f32 v[114:115], v[112:113], v[114:115], v[126:127]
	v_pk_fma_f32 v[112:113], v[120:121], v[122:123], v[124:125]
	v_fmamk_f32 v120, v167, 0x3a800000, v172
	v_rsq_f32_e32 v120, v120
	global_store_dwordx4 v[192:193], v[112:115], off offset:512
	global_store_dwordx4 v[192:193], v[116:119], off offset:528
	v_lshlrev_b32_e32 v122, 16, v139
	v_and_b32_e32 v123, 0xffff0000, v139
	v_pk_mul_f32 v[108:109], v[108:109], v[120:121] op_sel_hi:[1,0]
	v_pk_mul_f32 v[104:105], v[104:105], v[120:121] op_sel_hi:[1,0]
	v_mul_f32_e32 v108, 0xbfb8aa3b, v108
	v_exp_f32_e32 v114, v108
	v_mul_f32_e32 v108, 0xbfb8aa3b, v109
	v_exp_f32_e32 v115, v108
	v_pk_mul_f32 v[108:109], v[110:111], v[120:121] op_sel_hi:[1,0]
	v_add_f32_e32 v110, 1.0, v114
	v_mul_f32_e32 v108, 0xbfb8aa3b, v108
	v_mul_f32_e32 v109, 0xbfb8aa3b, v109
	v_exp_f32_e32 v108, v108
	v_exp_f32_e32 v109, v109
	v_rcp_f32_e32 v114, v110
	v_add_f32_e32 v110, 1.0, v115
	v_add_f32_e32 v108, 1.0, v108
	v_add_f32_e32 v109, 1.0, v109
	v_rcp_f32_e32 v115, v110
	v_rcp_f32_e32 v108, v108
	v_rcp_f32_e32 v109, v109
	v_lshlrev_b32_e32 v116, 16, v142
	v_and_b32_e32 v117, 0xffff0000, v142
	v_lshlrev_b32_e32 v110, 16, v143
	v_and_b32_e32 v111, 0xffff0000, v143
	v_lshlrev_b32_e32 v118, 16, v138
	v_and_b32_e32 v119, 0xffff0000, v138
	v_mul_f32_e32 v104, 0xbfb8aa3b, v104
	v_pk_fma_f32 v[110:111], v[108:109], v[110:111], v[122:123]
	v_pk_fma_f32 v[108:109], v[114:115], v[116:117], v[118:119]
	v_exp_f32_e32 v114, v104
	v_mul_f32_e32 v104, 0xbfb8aa3b, v105
	v_exp_f32_e32 v115, v104
	v_pk_mul_f32 v[104:105], v[106:107], v[120:121] op_sel_hi:[1,0]
	v_add_f32_e32 v106, 1.0, v114
	v_mul_f32_e32 v104, 0xbfb8aa3b, v104
	v_mul_f32_e32 v105, 0xbfb8aa3b, v105
	v_exp_f32_e32 v104, v104
	v_exp_f32_e32 v105, v105
	v_rcp_f32_e32 v114, v106
	v_add_f32_e32 v106, 1.0, v115
	v_add_f32_e32 v104, 1.0, v104
	v_add_f32_e32 v105, 1.0, v105
	v_rcp_f32_e32 v115, v106
	v_rcp_f32_e32 v104, v104
	v_rcp_f32_e32 v105, v105
	v_lshlrev_b32_e32 v116, 16, v140
	v_and_b32_e32 v117, 0xffff0000, v140
	v_lshlrev_b32_e32 v106, 16, v141
	v_and_b32_e32 v107, 0xffff0000, v141
	v_lshlrev_b32_e32 v118, 16, v136
	v_and_b32_e32 v119, 0xffff0000, v136
	v_lshlrev_b32_e32 v122, 16, v137
	v_and_b32_e32 v123, 0xffff0000, v137
	v_pk_mul_f32 v[100:101], v[100:101], v[120:121] op_sel_hi:[1,0]
	v_lshl_add_u64 v[112:113], v[190:191], 2, s[52:53]
	v_pk_fma_f32 v[106:107], v[104:105], v[106:107], v[122:123]
	v_pk_fma_f32 v[104:105], v[114:115], v[116:117], v[118:119]
	v_mul_f32_e32 v100, 0xbfb8aa3b, v100
	global_store_dwordx4 v[112:113], v[104:107], off
	global_store_dwordx4 v[112:113], v[108:111], off offset:16
	v_pk_mul_f32 v[96:97], v[96:97], v[120:121] op_sel_hi:[1,0]
	v_exp_f32_e32 v104, v100
	v_mul_f32_e32 v100, 0xbfb8aa3b, v101
	v_exp_f32_e32 v105, v100
	v_pk_mul_f32 v[100:101], v[102:103], v[120:121] op_sel_hi:[1,0]
	v_add_f32_e32 v102, 1.0, v104
	v_mul_f32_e32 v100, 0xbfb8aa3b, v100
	v_mul_f32_e32 v101, 0xbfb8aa3b, v101
	v_exp_f32_e32 v100, v100
	v_exp_f32_e32 v101, v101
	v_rcp_f32_e32 v104, v102
	v_add_f32_e32 v102, 1.0, v105
	v_add_f32_e32 v100, 1.0, v100
	v_add_f32_e32 v101, 1.0, v101
	v_rcp_f32_e32 v105, v102
	v_rcp_f32_e32 v100, v100
	v_rcp_f32_e32 v101, v101
	v_lshlrev_b32_e32 v106, 16, v134
	v_and_b32_e32 v107, 0xffff0000, v134
	v_lshlrev_b32_e32 v102, 16, v135
	v_and_b32_e32 v103, 0xffff0000, v135
	v_lshlrev_b32_e32 v108, 16, v130
	v_and_b32_e32 v109, 0xffff0000, v130
	v_lshlrev_b32_e32 v110, 16, v131
	v_and_b32_e32 v111, 0xffff0000, v131
	v_mul_f32_e32 v96, 0xbfb8aa3b, v96
	v_pk_fma_f32 v[102:103], v[100:101], v[102:103], v[110:111]
	v_pk_fma_f32 v[100:101], v[104:105], v[106:107], v[108:109]
	v_exp_f32_e32 v104, v96
	v_mul_f32_e32 v96, 0xbfb8aa3b, v97
	v_exp_f32_e32 v105, v96
	v_pk_mul_f32 v[96:97], v[98:99], v[120:121] op_sel_hi:[1,0]
	v_add_f32_e32 v98, 1.0, v104
	v_mul_f32_e32 v96, 0xbfb8aa3b, v96
	v_mul_f32_e32 v97, 0xbfb8aa3b, v97
	v_exp_f32_e32 v96, v96
	v_exp_f32_e32 v97, v97
	v_rcp_f32_e32 v104, v98
	v_add_f32_e32 v98, 1.0, v105
	v_add_f32_e32 v96, 1.0, v96
	v_add_f32_e32 v97, 1.0, v97
	v_rcp_f32_e32 v105, v98
	v_rcp_f32_e32 v96, v96
	v_rcp_f32_e32 v97, v97
	v_lshlrev_b32_e32 v106, 16, v132
	v_and_b32_e32 v107, 0xffff0000, v132
	v_lshlrev_b32_e32 v98, 16, v133
	v_and_b32_e32 v99, 0xffff0000, v133
	v_lshlrev_b32_e32 v108, 16, v128
	v_and_b32_e32 v109, 0xffff0000, v128
	v_lshlrev_b32_e32 v110, 16, v129
	v_and_b32_e32 v111, 0xffff0000, v129
	v_pk_fma_f32 v[98:99], v[96:97], v[98:99], v[110:111]
	v_pk_fma_f32 v[96:97], v[104:105], v[106:107], v[108:109]
	global_store_dwordx4 v[112:113], v[96:99], off offset:512
	global_store_dwordx4 v[112:113], v[100:103], off offset:528
	v_or_b32_e32 v104, 48, v166
	v_or_b32_e32 v96, 32, v166
	v_ashrrev_i32_e32 v97, 31, v96
	v_lshl_add_u64 v[98:99], v[96:97], 2, s[36:37]
	global_load_dword v102, v[98:99], off
	v_lshlrev_b64 v[96:97], 10, v[96:97]
	v_lshl_add_u64 v[128:129], v[96:97], 0, v[164:165]
	v_lshlrev_b64 v[120:121], 1, v[128:129]
	v_lshl_add_u64 v[96:97], s[48:49], 0, v[120:121]
	global_load_dwordx4 v[112:115], v[96:97], off
	v_lshl_add_u64 v[96:97], s[42:43], 0, v[120:121]
	v_ashrrev_i32_e32 v105, 31, v104
	global_load_dwordx4 v[116:119], v[96:97], off
	v_lshlrev_b64 v[96:97], 10, v[104:105]
	v_lshl_add_u64 v[130:131], v[96:97], 0, v[164:165]
	v_lshlrev_b64 v[106:107], 1, v[130:131]
	v_lshl_add_u64 v[100:101], v[106:107], 0, s[10:11]
	v_lshl_add_u64 v[96:97], s[48:49], 0, v[100:101]
	v_lshl_add_u64 v[100:101], s[42:43], 0, v[100:101]
	v_lshl_add_u64 v[108:109], s[48:49], 0, v[106:107]
	v_lshl_add_u64 v[106:107], s[42:43], 0, v[106:107]
	global_load_dwordx4 v[96:99], v[96:97], off
	v_lshl_add_u64 v[122:123], v[104:105], 2, s[36:37]
	v_lshl_add_u64 v[124:125], v[120:121], 0, s[10:11]
	v_lshl_add_u64 v[120:121], s[48:49], 0, v[124:125]
	v_lshl_add_u64 v[124:125], s[42:43], 0, v[124:125]
	v_lshl_add_u64 v[128:129], v[128:129], 2, s[52:53]
	s_waitcnt vmcnt(0) lgkmcnt(0)
; __device__ __forceinline__ u32x4 pack8(f32x4 a, f32x4 b) { u32x4 w; w.x = pk2(a[0], a[1]); w.y = pk2(a[2], a[3]); w.z = pk2(b[0], b[1]); w.w = pk2(b[2], b[3]); return w; }
;     __device__ __forceinline__ void operator()(const Acc& acc, const pg8::Unit& u, int wid) const {
;     ...
;                 for (int mm = 0; mm < 2; ++mm) {
;                     const int m = 2 * mp + mm, row = row0 + ai * 128 + m * 16; float sq = 0.f;
;                     const float sc = __builtin_amdgcn_rsqf(scv[mm] * (1.f / 1024.f) + EPS);
; #pragma unroll
;                     for (int bj = 0; bj < 2; ++bj) {
;                         const size_t off = (size_t)row * 1024 + col0 + bj * 128;
;                         const u32x4 pwv = pw[mm][bj], hw = hv[mm][bj];
;                         const f32x4 p0 = (f32x4){bflo(pwv.x), bfhi(pwv.x), bflo(pwv.y), bfhi(pwv.y)}, p1 = (f32x4){bflo(pwv.z), bfhi(pwv.z), bflo(pwv.w), bfhi(pwv.w)};
;                         f32x4 g0 = acc[ai][bj][m][0] * sc, g1 = acc[ai][bj][m][1] * sc;
; #pragma unroll
;                         for (int e = 0; e < 4; ++e) { g0[e] = __builtin_amdgcn_rcpf(1.f + __builtin_amdgcn_exp2f(-1.4426950408889634f * g0[e])); g1[e] = __builtin_amdgcn_rcpf(1.f + __builtin_amdgcn_exp2f(-1.4426950408889634f * g1[e])); }
;                         const f32x4 o0 = (f32x4){bflo(hw.x), bfhi(hw.x), bflo(hw.y), bfhi(hw.y)} + g0 * p0;
;                         const f32x4 o1 = (f32x4){bflo(hw.z), bfhi(hw.z), bflo(hw.w), bfhi(hw.w)} + g1 * p1;
;                         if (fout) { *(f32x4*)(fout + off) = o0; *(f32x4*)(fout + off + 4) = o1; }
;                         if (hb_out) *(u32x4*)(hb_out + off) = pack8(o0, o1);
;                         sq += (o0[0] * o0[0] + o0[1] * o0[1]) + (o0[2] * o0[2] + o0[3] * o0[3]) + (o1[0] * o1[0] + o1[1] * o1[1]) + (o1[2] * o1[2] + o1[3] * o1[3]);
;                     }
;                     if (ssq_out) { sq += __shfl_xor(sq, 16); sq += __shfl_xor(sq, 32); if (fq == 0) atomicAdd(ssq_out + row, sq); }
	v_fmamk_f32 v102, v102, 0x3a800000, v172
	v_rsq_f32_e32 v132, v102
	global_load_dwordx4 v[100:103], v[100:101], off
	s_nop 0
	global_load_dwordx4 v[108:111], v[108:109], off
	s_nop 0
	global_load_dwordx4 v[104:107], v[106:107], off
	s_nop 0
	global_load_dword v133, v[122:123], off
	v_lshlrev_b32_e32 v136, 16, v114
	global_load_dwordx4 v[120:123], v[120:121], off
	v_and_b32_e32 v137, 0xffff0000, v114
	global_load_dwordx4 v[124:127], v[124:125], off
	v_lshlrev_b32_e32 v114, 16, v118
	s_waitcnt vmcnt(0) lgkmcnt(0)
	v_pk_mul_f32 v[92:93], v[92:93], v[132:133] op_sel_hi:[1,0]
	s_nop 0
	v_mul_f32_e32 v92, 0xbfb8aa3b, v92
	v_exp_f32_e32 v134, v92
	v_mul_f32_e32 v92, 0xbfb8aa3b, v93
	v_exp_f32_e32 v135, v92
	v_pk_mul_f32 v[92:93], v[94:95], v[132:133] op_sel_hi:[1,0]
	v_add_f32_e32 v94, 1.0, v134
	v_mul_f32_e32 v92, 0xbfb8aa3b, v92
	v_mul_f32_e32 v93, 0xbfb8aa3b, v93
	v_exp_f32_e32 v92, v92
	v_exp_f32_e32 v93, v93
	v_rcp_f32_e32 v134, v94
	v_add_f32_e32 v94, 1.0, v135
	v_add_f32_e32 v92, 1.0, v92
	v_add_f32_e32 v93, 1.0, v93
	v_rcp_f32_e32 v135, v94
	v_rcp_f32_e32 v92, v92
	v_rcp_f32_e32 v93, v93
	v_pk_mul_f32 v[88:89], v[88:89], v[132:133] op_sel_hi:[1,0]
	v_lshlrev_b32_e32 v94, 16, v115
	v_and_b32_e32 v95, 0xffff0000, v115
	v_and_b32_e32 v115, 0xffff0000, v118
	v_lshlrev_b32_e32 v118, 16, v119
	v_and_b32_e32 v119, 0xffff0000, v119
	v_mul_f32_e32 v88, 0xbfb8aa3b, v88
	v_pk_fma_f32 v[94:95], v[92:93], v[94:95], v[118:119]
	v_pk_fma_f32 v[92:93], v[134:135], v[136:137], v[114:115]
	v_exp_f32_e32 v114, v88
	v_mul_f32_e32 v88, 0xbfb8aa3b, v89
	v_exp_f32_e32 v115, v88
	v_pk_mul_f32 v[88:89], v[90:91], v[132:133] op_sel_hi:[1,0]
	v_add_f32_e32 v90, 1.0, v114
	v_mul_f32_e32 v88, 0xbfb8aa3b, v88
	v_mul_f32_e32 v89, 0xbfb8aa3b, v89
	v_exp_f32_e32 v88, v88
	v_exp_f32_e32 v89, v89
	v_rcp_f32_e32 v114, v90
	v_add_f32_e32 v90, 1.0, v115
	v_add_f32_e32 v88, 1.0, v88
	v_add_f32_e32 v89, 1.0, v89
	v_rcp_f32_e32 v115, v90
	v_rcp_f32_e32 v88, v88
	v_rcp_f32_e32 v89, v89
	v_lshlrev_b32_e32 v118, 16, v112
	v_and_b32_e32 v119, 0xffff0000, v112
	v_lshlrev_b32_e32 v90, 16, v113
	v_and_b32_e32 v91, 0xffff0000, v113
	v_lshlrev_b32_e32 v112, 16, v116
	v_and_b32_e32 v113, 0xffff0000, v116
	v_lshlrev_b32_e32 v116, 16, v117
	v_and_b32_e32 v117, 0xffff0000, v117
	v_pk_mul_f32 v[84:85], v[84:85], v[132:133] op_sel_hi:[1,0]
	v_pk_fma_f32 v[90:91], v[88:89], v[90:91], v[116:117]
	v_pk_fma_f32 v[88:89], v[114:115], v[118:119], v[112:113]
	v_mul_f32_e32 v84, 0xbfb8aa3b, v84
	global_store_dwordx4 v[128:129], v[88:91], off
	global_store_dwordx4 v[128:129], v[92:95], off offset:16
	v_pk_mul_f32 v[80:81], v[80:81], v[132:133] op_sel_hi:[1,0]
	v_exp_f32_e32 v88, v84
	v_mul_f32_e32 v84, 0xbfb8aa3b, v85
	v_exp_f32_e32 v89, v84
	v_pk_mul_f32 v[84:85], v[86:87], v[132:133] op_sel_hi:[1,0]
	v_add_f32_e32 v86, 1.0, v88
	v_mul_f32_e32 v84, 0xbfb8aa3b, v84
	v_mul_f32_e32 v85, 0xbfb8aa3b, v85
	v_exp_f32_e32 v84, v84
	v_exp_f32_e32 v85, v85
	v_rcp_f32_e32 v88, v86
	v_add_f32_e32 v86, 1.0, v89
	v_add_f32_e32 v84, 1.0, v84
	v_add_f32_e32 v85, 1.0, v85
	v_rcp_f32_e32 v89, v86
	v_rcp_f32_e32 v84, v84
	v_rcp_f32_e32 v85, v85
	v_lshlrev_b32_e32 v90, 16, v122
	v_and_b32_e32 v91, 0xffff0000, v122
	v_lshlrev_b32_e32 v86, 16, v123
	v_and_b32_e32 v87, 0xffff0000, v123
	v_lshlrev_b32_e32 v92, 16, v126
	v_and_b32_e32 v93, 0xffff0000, v126
	v_lshlrev_b32_e32 v94, 16, v127
	v_and_b32_e32 v95, 0xffff0000, v127
	v_mul_f32_e32 v80, 0xbfb8aa3b, v80
	v_pk_fma_f32 v[86:87], v[84:85], v[86:87], v[94:95]
	v_pk_fma_f32 v[84:85], v[88:89], v[90:91], v[92:93]
	v_exp_f32_e32 v88, v80
	v_mul_f32_e32 v80, 0xbfb8aa3b, v81
	v_exp_f32_e32 v89, v80
	v_pk_mul_f32 v[80:81], v[82:83], v[132:133] op_sel_hi:[1,0]
	v_add_f32_e32 v82, 1.0, v88
	v_mul_f32_e32 v80, 0xbfb8aa3b, v80
	v_mul_f32_e32 v81, 0xbfb8aa3b, v81
	v_exp_f32_e32 v80, v80
	v_exp_f32_e32 v81, v81
	v_rcp_f32_e32 v88, v82
	v_add_f32_e32 v82, 1.0, v89
	v_add_f32_e32 v80, 1.0, v80
	v_add_f32_e32 v81, 1.0, v81
	v_rcp_f32_e32 v89, v82
	v_rcp_f32_e32 v80, v80
	v_rcp_f32_e32 v81, v81
	v_lshlrev_b32_e32 v90, 16, v120
	v_and_b32_e32 v91, 0xffff0000, v120
	v_lshlrev_b32_e32 v82, 16, v121
	v_and_b32_e32 v83, 0xffff0000, v121
	v_lshlrev_b32_e32 v92, 16, v124
	v_and_b32_e32 v93, 0xffff0000, v124
	v_lshlrev_b32_e32 v94, 16, v125
	v_and_b32_e32 v95, 0xffff0000, v125
	v_pk_fma_f32 v[82:83], v[80:81], v[82:83], v[94:95]
	v_pk_fma_f32 v[80:81], v[88:89], v[90:91], v[92:93]
	v_fmamk_f32 v88, v133, 0x3a800000, v172
	v_rsq_f32_e32 v88, v88
	global_store_dwordx4 v[128:129], v[80:83], off offset:512
	global_store_dwordx4 v[128:129], v[84:87], off offset:528
	v_lshlrev_b32_e32 v90, 16, v107
	v_and_b32_e32 v91, 0xffff0000, v107
	v_pk_mul_f32 v[76:77], v[76:77], v[88:89] op_sel_hi:[1,0]
	v_pk_mul_f32 v[72:73], v[72:73], v[88:89] op_sel_hi:[1,0]
	v_mul_f32_e32 v76, 0xbfb8aa3b, v76
	v_exp_f32_e32 v82, v76
	v_mul_f32_e32 v76, 0xbfb8aa3b, v77
	v_exp_f32_e32 v83, v76
	v_pk_mul_f32 v[76:77], v[78:79], v[88:89] op_sel_hi:[1,0]
	v_add_f32_e32 v78, 1.0, v82
	v_mul_f32_e32 v76, 0xbfb8aa3b, v76
	v_mul_f32_e32 v77, 0xbfb8aa3b, v77
	v_exp_f32_e32 v76, v76
	v_exp_f32_e32 v77, v77
	v_rcp_f32_e32 v82, v78
	v_add_f32_e32 v78, 1.0, v83
	v_add_f32_e32 v76, 1.0, v76
	v_add_f32_e32 v77, 1.0, v77
	v_rcp_f32_e32 v83, v78
	v_rcp_f32_e32 v76, v76
	v_rcp_f32_e32 v77, v77
	v_lshlrev_b32_e32 v84, 16, v110
	v_and_b32_e32 v85, 0xffff0000, v110
	v_lshlrev_b32_e32 v78, 16, v111
	v_and_b32_e32 v79, 0xffff0000, v111
	v_lshlrev_b32_e32 v86, 16, v106
	v_and_b32_e32 v87, 0xffff0000, v106
	v_mul_f32_e32 v72, 0xbfb8aa3b, v72
	v_pk_fma_f32 v[78:79], v[76:77], v[78:79], v[90:91]
	v_pk_fma_f32 v[76:77], v[82:83], v[84:85], v[86:87]
; __device__ __forceinline__ u32x4 pack8(f32x4 a, f32x4 b) { u32x4 w; w.x = pk2(a[0], a[1]); w.y = pk2(a[2], a[3]); w.z = pk2(b[0], b[1]); w.w = pk2(b[2], b[3]); return w; }
;     __device__ __forceinline__ void operator()(const Acc& acc, const pg8::Unit& u, int wid) const {
;     ...
;                 for (int mm = 0; mm < 2; ++mm) {
;                     const int m = 2 * mp + mm, row = row0 + ai * 128 + m * 16; float sq = 0.f;
;                     const float sc = __builtin_amdgcn_rsqf(scv[mm] * (1.f / 1024.f) + EPS);
; #pragma unroll
;                     for (int bj = 0; bj < 2; ++bj) {
;                         const size_t off = (size_t)row * 1024 + col0 + bj * 128;
;                         const u32x4 pwv = pw[mm][bj], hw = hv[mm][bj];
;                         const f32x4 p0 = (f32x4){bflo(pwv.x), bfhi(pwv.x), bflo(pwv.y), bfhi(pwv.y)}, p1 = (f32x4){bflo(pwv.z), bfhi(pwv.z), bflo(pwv.w), bfhi(pwv.w)};
;                         f32x4 g0 = acc[ai][bj][m][0] * sc, g1 = acc[ai][bj][m][1] * sc;
; #pragma unroll
;                         for (int e = 0; e < 4; ++e) { g0[e] = __builtin_amdgcn_rcpf(1.f + __builtin_amdgcn_exp2f(-1.4426950408889634f * g0[e])); g1[e] = __builtin_amdgcn_rcpf(1.f + __builtin_amdgcn_exp2f(-1.4426950408889634f * g1[e])); }
;                         const f32x4 o0 = (f32x4){bflo(hw.x), bfhi(hw.x), bflo(hw.y), bfhi(hw.y)} + g0 * p0;
;                         const f32x4 o1 = (f32x4){bflo(hw.z), bfhi(hw.z), bflo(hw.w), bfhi(hw.w)} + g1 * p1;
;                         if (fout) { *(f32x4*)(fout + off) = o0; *(f32x4*)(fout + off + 4) = o1; }
;                         if (hb_out) *(u32x4*)(hb_out + off) = pack8(o0, o1);
;                         sq += (o0[0] * o0[0] + o0[1] * o0[1]) + (o0[2] * o0[2] + o0[3] * o0[3]) + (o1[0] * o1[0] + o1[1] * o1[1]) + (o1[2] * o1[2] + o1[3] * o1[3]);
;                     }
;                     if (ssq_out) { sq += __shfl_xor(sq, 16); sq += __shfl_xor(sq, 32); if (fq == 0) atomicAdd(ssq_out + row, sq); }
	v_exp_f32_e32 v82, v72
	v_mul_f32_e32 v72, 0xbfb8aa3b, v73
	v_exp_f32_e32 v83, v72
	v_pk_mul_f32 v[72:73], v[74:75], v[88:89] op_sel_hi:[1,0]
	v_add_f32_e32 v74, 1.0, v82
	v_mul_f32_e32 v72, 0xbfb8aa3b, v72
	v_mul_f32_e32 v73, 0xbfb8aa3b, v73
	v_exp_f32_e32 v72, v72
	v_exp_f32_e32 v73, v73
	v_rcp_f32_e32 v82, v74
	v_add_f32_e32 v74, 1.0, v83
	v_add_f32_e32 v72, 1.0, v72
	v_add_f32_e32 v73, 1.0, v73
	v_rcp_f32_e32 v83, v74
	v_rcp_f32_e32 v72, v72
	v_rcp_f32_e32 v73, v73
	v_lshlrev_b32_e32 v84, 16, v108
	v_and_b32_e32 v85, 0xffff0000, v108
	v_lshlrev_b32_e32 v74, 16, v109
	v_and_b32_e32 v75, 0xffff0000, v109
	v_lshlrev_b32_e32 v86, 16, v104
	v_and_b32_e32 v87, 0xffff0000, v104
	v_lshlrev_b32_e32 v90, 16, v105
	v_and_b32_e32 v91, 0xffff0000, v105
	v_pk_mul_f32 v[68:69], v[68:69], v[88:89] op_sel_hi:[1,0]
	v_lshl_add_u64 v[80:81], v[130:131], 2, s[52:53]
	v_pk_fma_f32 v[74:75], v[72:73], v[74:75], v[90:91]
	v_pk_fma_f32 v[72:73], v[82:83], v[84:85], v[86:87]
	v_mul_f32_e32 v68, 0xbfb8aa3b, v68
	global_store_dwordx4 v[80:81], v[72:75], off
	global_store_dwordx4 v[80:81], v[76:79], off offset:16
	v_pk_mul_f32 v[64:65], v[64:65], v[88:89] op_sel_hi:[1,0]
	v_exp_f32_e32 v72, v68
	v_mul_f32_e32 v68, 0xbfb8aa3b, v69
	v_exp_f32_e32 v73, v68
	v_pk_mul_f32 v[68:69], v[70:71], v[88:89] op_sel_hi:[1,0]
	v_add_f32_e32 v70, 1.0, v72
	v_mul_f32_e32 v68, 0xbfb8aa3b, v68
	v_mul_f32_e32 v69, 0xbfb8aa3b, v69
	v_exp_f32_e32 v68, v68
	v_exp_f32_e32 v69, v69
	v_rcp_f32_e32 v72, v70
	v_add_f32_e32 v70, 1.0, v73
	v_add_f32_e32 v68, 1.0, v68
	v_add_f32_e32 v69, 1.0, v69
	v_rcp_f32_e32 v73, v70
	v_rcp_f32_e32 v68, v68
	v_rcp_f32_e32 v69, v69
	v_lshlrev_b32_e32 v74, 16, v98
	v_and_b32_e32 v75, 0xffff0000, v98
	v_lshlrev_b32_e32 v70, 16, v99
	v_and_b32_e32 v71, 0xffff0000, v99
	v_lshlrev_b32_e32 v76, 16, v102
	v_and_b32_e32 v77, 0xffff0000, v102
	v_lshlrev_b32_e32 v78, 16, v103
	v_and_b32_e32 v79, 0xffff0000, v103
	v_mul_f32_e32 v64, 0xbfb8aa3b, v64
	v_pk_fma_f32 v[70:71], v[68:69], v[70:71], v[78:79]
	v_pk_fma_f32 v[68:69], v[72:73], v[74:75], v[76:77]
	v_exp_f32_e32 v72, v64
	v_mul_f32_e32 v64, 0xbfb8aa3b, v65
	v_exp_f32_e32 v73, v64
	v_pk_mul_f32 v[64:65], v[66:67], v[88:89] op_sel_hi:[1,0]
	v_add_f32_e32 v66, 1.0, v72
	v_mul_f32_e32 v64, 0xbfb8aa3b, v64
	v_mul_f32_e32 v65, 0xbfb8aa3b, v65
	v_exp_f32_e32 v64, v64
	v_exp_f32_e32 v65, v65
	v_rcp_f32_e32 v72, v66
	v_add_f32_e32 v66, 1.0, v73
	v_add_f32_e32 v64, 1.0, v64
	v_add_f32_e32 v65, 1.0, v65
	v_rcp_f32_e32 v73, v66
	v_rcp_f32_e32 v64, v64
	v_rcp_f32_e32 v65, v65
	v_lshlrev_b32_e32 v74, 16, v96
	v_and_b32_e32 v75, 0xffff0000, v96
	v_lshlrev_b32_e32 v66, 16, v97
	v_and_b32_e32 v67, 0xffff0000, v97
	v_lshlrev_b32_e32 v76, 16, v100
	v_and_b32_e32 v77, 0xffff0000, v100
	v_lshlrev_b32_e32 v78, 16, v101
	v_and_b32_e32 v79, 0xffff0000, v101
	v_pk_fma_f32 v[66:67], v[64:65], v[66:67], v[78:79]
	v_pk_fma_f32 v[64:65], v[72:73], v[74:75], v[76:77]
	global_store_dwordx4 v[80:81], v[64:67], off offset:512
	global_store_dwordx4 v[80:81], v[68:71], off offset:528
	global_load_dword v74, v[160:161], off offset:512
	v_lshl_add_u64 v[96:97], v[162:163], 0, s[14:15]
	v_lshlrev_b64 v[64:65], 1, v[96:97]
	v_lshl_add_u64 v[98:99], v[162:163], 0, s[12:13]
	v_lshl_add_u64 v[66:67], s[48:49], 0, v[64:65]
	v_lshl_add_u64 v[68:69], v[64:65], 0, s[10:11]
	v_lshlrev_b64 v[70:71], 1, v[98:99]
	global_load_dwordx4 v[80:83], v[66:67], off
	v_lshl_add_u64 v[66:67], s[42:43], 0, v[64:65]
	v_lshl_add_u64 v[64:65], s[42:43], 0, v[68:69]
	v_lshl_add_u64 v[72:73], v[70:71], 0, s[10:11]
	global_load_dwordx4 v[84:87], v[66:67], off
	global_load_dwordx4 v[88:91], v[64:65], off
	v_lshl_add_u64 v[64:65], s[48:49], 0, v[72:73]
	global_load_dwordx4 v[64:67], v[64:65], off
	s_nop 0
	global_load_dword v101, v[160:161], off offset:576
	v_lshl_add_u64 v[76:77], s[42:43], 0, v[72:73]
	v_lshl_add_u64 v[78:79], s[48:49], 0, v[70:71]
	v_lshl_add_u64 v[70:71], s[42:43], 0, v[70:71]
	v_lshl_add_u64 v[68:69], s[48:49], 0, v[68:69]
	v_lshl_add_u64 v[96:97], v[96:97], 2, s[52:53]
	s_waitcnt vmcnt(0) lgkmcnt(0)
	v_fmamk_f32 v74, v74, 0x3a800000, v172
	v_rsq_f32_e32 v100, v74
	global_load_dwordx4 v[72:75], v[70:71], off
	global_load_dwordx4 v[92:95], v[68:69], off
	s_nop 0
	global_load_dwordx4 v[68:71], v[76:77], off
	s_nop 0
	global_load_dwordx4 v[76:79], v[78:79], off
	v_lshlrev_b32_e32 v104, 16, v82
	v_and_b32_e32 v105, 0xffff0000, v82
	v_lshlrev_b32_e32 v82, 16, v86
	v_pk_mul_f32 v[60:61], v[60:61], v[100:101] op_sel_hi:[1,0]
	s_nop 0
	v_mul_f32_e32 v60, 0xbfb8aa3b, v60
	v_exp_f32_e32 v102, v60
	v_mul_f32_e32 v60, 0xbfb8aa3b, v61
	v_exp_f32_e32 v103, v60
	v_pk_mul_f32 v[60:61], v[62:63], v[100:101] op_sel_hi:[1,0]
	v_add_f32_e32 v62, 1.0, v102
	v_mul_f32_e32 v60, 0xbfb8aa3b, v60
	v_mul_f32_e32 v61, 0xbfb8aa3b, v61
	v_exp_f32_e32 v60, v60
	v_exp_f32_e32 v61, v61
	v_rcp_f32_e32 v102, v62
	v_add_f32_e32 v62, 1.0, v103
	v_add_f32_e32 v60, 1.0, v60
	v_add_f32_e32 v61, 1.0, v61
	v_rcp_f32_e32 v103, v62
	v_rcp_f32_e32 v60, v60
	v_rcp_f32_e32 v61, v61
	v_pk_mul_f32 v[56:57], v[56:57], v[100:101] op_sel_hi:[1,0]
	v_lshlrev_b32_e32 v62, 16, v83
	v_and_b32_e32 v63, 0xffff0000, v83
	v_and_b32_e32 v83, 0xffff0000, v86
	v_lshlrev_b32_e32 v86, 16, v87
	v_and_b32_e32 v87, 0xffff0000, v87
	v_mul_f32_e32 v56, 0xbfb8aa3b, v56
	v_pk_fma_f32 v[62:63], v[60:61], v[62:63], v[86:87]
	v_pk_fma_f32 v[60:61], v[102:103], v[104:105], v[82:83]
	v_exp_f32_e32 v82, v56
	v_mul_f32_e32 v56, 0xbfb8aa3b, v57
	v_exp_f32_e32 v83, v56
	v_pk_mul_f32 v[56:57], v[58:59], v[100:101] op_sel_hi:[1,0]
	v_add_f32_e32 v58, 1.0, v82
	v_mul_f32_e32 v56, 0xbfb8aa3b, v56
	v_mul_f32_e32 v57, 0xbfb8aa3b, v57
	v_exp_f32_e32 v56, v56
	v_exp_f32_e32 v57, v57
	v_rcp_f32_e32 v82, v58
	v_add_f32_e32 v58, 1.0, v83
	v_add_f32_e32 v56, 1.0, v56
	v_add_f32_e32 v57, 1.0, v57
	v_rcp_f32_e32 v83, v58
	v_rcp_f32_e32 v56, v56
	v_rcp_f32_e32 v57, v57
	v_lshlrev_b32_e32 v86, 16, v80
	v_and_b32_e32 v87, 0xffff0000, v80
	v_lshlrev_b32_e32 v58, 16, v81
	v_and_b32_e32 v59, 0xffff0000, v81
	v_lshlrev_b32_e32 v80, 16, v84
	v_and_b32_e32 v81, 0xffff0000, v84
	v_lshlrev_b32_e32 v84, 16, v85
	v_and_b32_e32 v85, 0xffff0000, v85
	v_pk_mul_f32 v[52:53], v[52:53], v[100:101] op_sel_hi:[1,0]
	v_pk_fma_f32 v[58:59], v[56:57], v[58:59], v[84:85]
	v_pk_fma_f32 v[56:57], v[82:83], v[86:87], v[80:81]
	v_mul_f32_e32 v52, 0xbfb8aa3b, v52
	global_store_dwordx4 v[96:97], v[56:59], off
	global_store_dwordx4 v[96:97], v[60:63], off offset:16
	v_pk_mul_f32 v[48:49], v[48:49], v[100:101] op_sel_hi:[1,0]
	v_exp_f32_e32 v56, v52
	v_mul_f32_e32 v52, 0xbfb8aa3b, v53
	v_exp_f32_e32 v57, v52
	v_pk_mul_f32 v[52:53], v[54:55], v[100:101] op_sel_hi:[1,0]
	v_add_f32_e32 v54, 1.0, v56
	v_mul_f32_e32 v52, 0xbfb8aa3b, v52
	v_mul_f32_e32 v53, 0xbfb8aa3b, v53
	v_exp_f32_e32 v52, v52
	v_exp_f32_e32 v53, v53
	v_rcp_f32_e32 v56, v54
	v_add_f32_e32 v54, 1.0, v57
	v_add_f32_e32 v52, 1.0, v52
	v_add_f32_e32 v53, 1.0, v53
	v_rcp_f32_e32 v57, v54
	v_rcp_f32_e32 v52, v52
	v_rcp_f32_e32 v53, v53
	s_waitcnt vmcnt(0) lgkmcnt(0)
; __device__ __forceinline__ u32x4 pack8(f32x4 a, f32x4 b) { u32x4 w; w.x = pk2(a[0], a[1]); w.y = pk2(a[2], a[3]); w.z = pk2(b[0], b[1]); w.w = pk2(b[2], b[3]); return w; }
;     __device__ __forceinline__ void operator()(const Acc& acc, const pg8::Unit& u, int wid) const {
;     ...
;                 for (int mm = 0; mm < 2; ++mm) {
;                     const int m = 2 * mp + mm, row = row0 + ai * 128 + m * 16; float sq = 0.f;
;                     const float sc = __builtin_amdgcn_rsqf(scv[mm] * (1.f / 1024.f) + EPS);
; #pragma unroll
;                     for (int bj = 0; bj < 2; ++bj) {
;                         const size_t off = (size_t)row * 1024 + col0 + bj * 128;
;                         const u32x4 pwv = pw[mm][bj], hw = hv[mm][bj];
;                         const f32x4 p0 = (f32x4){bflo(pwv.x), bfhi(pwv.x), bflo(pwv.y), bfhi(pwv.y)}, p1 = (f32x4){bflo(pwv.z), bfhi(pwv.z), bflo(pwv.w), bfhi(pwv.w)};
;                         f32x4 g0 = acc[ai][bj][m][0] * sc, g1 = acc[ai][bj][m][1] * sc;
; #pragma unroll
;                         for (int e = 0; e < 4; ++e) { g0[e] = __builtin_amdgcn_rcpf(1.f + __builtin_amdgcn_exp2f(-1.4426950408889634f * g0[e])); g1[e] = __builtin_amdgcn_rcpf(1.f + __builtin_amdgcn_exp2f(-1.4426950408889634f * g1[e])); }
;                         const f32x4 o0 = (f32x4){bflo(hw.x), bfhi(hw.x), bflo(hw.y), bfhi(hw.y)} + g0 * p0;
;                         const f32x4 o1 = (f32x4){bflo(hw.z), bfhi(hw.z), bflo(hw.w), bfhi(hw.w)} + g1 * p1;
;                         if (fout) { *(f32x4*)(fout + off) = o0; *(f32x4*)(fout + off + 4) = o1; }
;                         if (hb_out) *(u32x4*)(hb_out + off) = pack8(o0, o1);
;                         sq += (o0[0] * o0[0] + o0[1] * o0[1]) + (o0[2] * o0[2] + o0[3] * o0[3]) + (o1[0] * o1[0] + o1[1] * o1[1]) + (o1[2] * o1[2] + o1[3] * o1[3]);
;                     }
;                     if (ssq_out) { sq += __shfl_xor(sq, 16); sq += __shfl_xor(sq, 32); if (fq == 0) atomicAdd(ssq_out + row, sq); }
	v_lshlrev_b32_e32 v58, 16, v94
	v_and_b32_e32 v59, 0xffff0000, v94
	v_lshlrev_b32_e32 v54, 16, v95
	v_and_b32_e32 v55, 0xffff0000, v95
	v_lshlrev_b32_e32 v60, 16, v90
	v_and_b32_e32 v61, 0xffff0000, v90
	v_lshlrev_b32_e32 v62, 16, v91
	v_and_b32_e32 v63, 0xffff0000, v91
	v_mul_f32_e32 v48, 0xbfb8aa3b, v48
	v_pk_fma_f32 v[54:55], v[52:53], v[54:55], v[62:63]
	v_pk_fma_f32 v[52:53], v[56:57], v[58:59], v[60:61]
	v_exp_f32_e32 v56, v48
	v_mul_f32_e32 v48, 0xbfb8aa3b, v49
	v_exp_f32_e32 v57, v48
	v_pk_mul_f32 v[48:49], v[50:51], v[100:101] op_sel_hi:[1,0]
	v_add_f32_e32 v50, 1.0, v56
	v_mul_f32_e32 v48, 0xbfb8aa3b, v48
	v_mul_f32_e32 v49, 0xbfb8aa3b, v49
	v_exp_f32_e32 v48, v48
	v_exp_f32_e32 v49, v49
	v_rcp_f32_e32 v56, v50
	v_add_f32_e32 v50, 1.0, v57
	v_add_f32_e32 v48, 1.0, v48
	v_add_f32_e32 v49, 1.0, v49
	v_rcp_f32_e32 v57, v50
	v_rcp_f32_e32 v48, v48
	v_rcp_f32_e32 v49, v49
	v_lshlrev_b32_e32 v58, 16, v92
	v_and_b32_e32 v59, 0xffff0000, v92
	v_lshlrev_b32_e32 v50, 16, v93
	v_and_b32_e32 v51, 0xffff0000, v93
	v_lshlrev_b32_e32 v60, 16, v88
	v_and_b32_e32 v61, 0xffff0000, v88
	v_lshlrev_b32_e32 v62, 16, v89
	v_and_b32_e32 v63, 0xffff0000, v89
	v_pk_fma_f32 v[50:51], v[48:49], v[50:51], v[62:63]
	v_pk_fma_f32 v[48:49], v[56:57], v[58:59], v[60:61]
	v_fmamk_f32 v56, v101, 0x3a800000, v172
	v_rsq_f32_e32 v56, v56
	global_store_dwordx4 v[96:97], v[48:51], off offset:512
	global_store_dwordx4 v[96:97], v[52:55], off offset:528
	v_lshlrev_b32_e32 v58, 16, v75
	v_and_b32_e32 v59, 0xffff0000, v75
	v_pk_mul_f32 v[44:45], v[44:45], v[56:57] op_sel_hi:[1,0]
	v_pk_mul_f32 v[40:41], v[40:41], v[56:57] op_sel_hi:[1,0]
	v_mul_f32_e32 v44, 0xbfb8aa3b, v44
	v_exp_f32_e32 v50, v44
	v_mul_f32_e32 v44, 0xbfb8aa3b, v45
	v_exp_f32_e32 v51, v44
	v_pk_mul_f32 v[44:45], v[46:47], v[56:57] op_sel_hi:[1,0]
	v_add_f32_e32 v46, 1.0, v50
	v_mul_f32_e32 v44, 0xbfb8aa3b, v44
	v_mul_f32_e32 v45, 0xbfb8aa3b, v45
	v_exp_f32_e32 v44, v44
	v_exp_f32_e32 v45, v45
	v_rcp_f32_e32 v50, v46
	v_add_f32_e32 v46, 1.0, v51
	v_add_f32_e32 v44, 1.0, v44
	v_add_f32_e32 v45, 1.0, v45
	v_rcp_f32_e32 v51, v46
	v_rcp_f32_e32 v44, v44
	v_rcp_f32_e32 v45, v45
	v_lshlrev_b32_e32 v52, 16, v78
	v_and_b32_e32 v53, 0xffff0000, v78
	v_lshlrev_b32_e32 v46, 16, v79
	v_and_b32_e32 v47, 0xffff0000, v79
	v_lshlrev_b32_e32 v54, 16, v74
	v_and_b32_e32 v55, 0xffff0000, v74
	v_mul_f32_e32 v40, 0xbfb8aa3b, v40
	v_pk_fma_f32 v[46:47], v[44:45], v[46:47], v[58:59]
	v_pk_fma_f32 v[44:45], v[50:51], v[52:53], v[54:55]
	v_exp_f32_e32 v50, v40
	v_mul_f32_e32 v40, 0xbfb8aa3b, v41
	v_exp_f32_e32 v51, v40
	v_pk_mul_f32 v[40:41], v[42:43], v[56:57] op_sel_hi:[1,0]
	v_add_f32_e32 v42, 1.0, v50
	v_mul_f32_e32 v40, 0xbfb8aa3b, v40
	v_mul_f32_e32 v41, 0xbfb8aa3b, v41
	v_exp_f32_e32 v40, v40
	v_exp_f32_e32 v41, v41
	v_rcp_f32_e32 v50, v42
	v_add_f32_e32 v42, 1.0, v51
	v_add_f32_e32 v40, 1.0, v40
	v_add_f32_e32 v41, 1.0, v41
	v_rcp_f32_e32 v51, v42
	v_rcp_f32_e32 v40, v40
	v_rcp_f32_e32 v41, v41
	v_lshlrev_b32_e32 v52, 16, v76
	v_and_b32_e32 v53, 0xffff0000, v76
	v_lshlrev_b32_e32 v42, 16, v77
	v_and_b32_e32 v43, 0xffff0000, v77
	v_lshlrev_b32_e32 v54, 16, v72
	v_and_b32_e32 v55, 0xffff0000, v72
	v_lshlrev_b32_e32 v58, 16, v73
	v_and_b32_e32 v59, 0xffff0000, v73
	v_pk_mul_f32 v[36:37], v[36:37], v[56:57] op_sel_hi:[1,0]
	v_lshl_add_u64 v[48:49], v[98:99], 2, s[52:53]
	v_pk_fma_f32 v[42:43], v[40:41], v[42:43], v[58:59]
	v_pk_fma_f32 v[40:41], v[50:51], v[52:53], v[54:55]
	v_mul_f32_e32 v36, 0xbfb8aa3b, v36
	global_store_dwordx4 v[48:49], v[40:43], off
	global_store_dwordx4 v[48:49], v[44:47], off offset:16
	v_pk_mul_f32 v[32:33], v[32:33], v[56:57] op_sel_hi:[1,0]
	v_exp_f32_e32 v40, v36
	v_mul_f32_e32 v36, 0xbfb8aa3b, v37
	v_exp_f32_e32 v41, v36
	v_pk_mul_f32 v[36:37], v[38:39], v[56:57] op_sel_hi:[1,0]
	v_add_f32_e32 v38, 1.0, v40
	v_mul_f32_e32 v36, 0xbfb8aa3b, v36
	v_mul_f32_e32 v37, 0xbfb8aa3b, v37
	v_exp_f32_e32 v36, v36
	v_exp_f32_e32 v37, v37
	v_rcp_f32_e32 v40, v38
	v_add_f32_e32 v38, 1.0, v41
	v_add_f32_e32 v36, 1.0, v36
	v_add_f32_e32 v37, 1.0, v37
	v_rcp_f32_e32 v41, v38
	v_rcp_f32_e32 v36, v36
	v_rcp_f32_e32 v37, v37
	v_lshlrev_b32_e32 v42, 16, v66
	v_and_b32_e32 v43, 0xffff0000, v66
	v_lshlrev_b32_e32 v38, 16, v67
	v_and_b32_e32 v39, 0xffff0000, v67
	v_lshlrev_b32_e32 v44, 16, v70
	v_and_b32_e32 v45, 0xffff0000, v70
	v_lshlrev_b32_e32 v46, 16, v71
	v_and_b32_e32 v47, 0xffff0000, v71
	v_mul_f32_e32 v32, 0xbfb8aa3b, v32
	v_pk_fma_f32 v[38:39], v[36:37], v[38:39], v[46:47]
	v_pk_fma_f32 v[36:37], v[40:41], v[42:43], v[44:45]
	v_exp_f32_e32 v40, v32
	v_mul_f32_e32 v32, 0xbfb8aa3b, v33
	v_exp_f32_e32 v41, v32
	v_pk_mul_f32 v[32:33], v[34:35], v[56:57] op_sel_hi:[1,0]
	v_add_f32_e32 v34, 1.0, v40
	v_mul_f32_e32 v32, 0xbfb8aa3b, v32
	v_mul_f32_e32 v33, 0xbfb8aa3b, v33
	v_exp_f32_e32 v32, v32
	v_exp_f32_e32 v33, v33
	v_rcp_f32_e32 v40, v34
	v_add_f32_e32 v34, 1.0, v41
	v_add_f32_e32 v32, 1.0, v32
	v_add_f32_e32 v33, 1.0, v33
	v_rcp_f32_e32 v41, v34
	v_rcp_f32_e32 v32, v32
	v_rcp_f32_e32 v33, v33
	v_lshlrev_b32_e32 v42, 16, v64
	v_and_b32_e32 v43, 0xffff0000, v64
	v_lshlrev_b32_e32 v34, 16, v65
	v_and_b32_e32 v35, 0xffff0000, v65
	v_lshlrev_b32_e32 v44, 16, v68
	v_and_b32_e32 v45, 0xffff0000, v68
	v_lshlrev_b32_e32 v46, 16, v69
	v_and_b32_e32 v47, 0xffff0000, v69
	v_pk_fma_f32 v[34:35], v[32:33], v[34:35], v[46:47]
	v_pk_fma_f32 v[32:33], v[40:41], v[42:43], v[44:45]
	global_store_dwordx4 v[48:49], v[32:35], off offset:512
	global_store_dwordx4 v[48:49], v[36:39], off offset:528
	global_load_dword v42, v[160:161], off offset:640
	v_lshl_add_u64 v[64:65], v[162:163], 0, s[18:19]
	v_lshlrev_b64 v[32:33], 1, v[64:65]
	v_lshl_add_u64 v[66:67], v[162:163], 0, s[16:17]
	v_lshl_add_u64 v[34:35], s[48:49], 0, v[32:33]
	v_lshl_add_u64 v[36:37], v[32:33], 0, s[10:11]
	v_lshlrev_b64 v[38:39], 1, v[66:67]
	global_load_dwordx4 v[48:51], v[34:35], off
	v_lshl_add_u64 v[34:35], s[42:43], 0, v[32:33]
	v_lshl_add_u64 v[32:33], s[42:43], 0, v[36:37]
	v_lshl_add_u64 v[40:41], v[38:39], 0, s[10:11]
	global_load_dwordx4 v[52:55], v[34:35], off
	global_load_dwordx4 v[56:59], v[32:33], off
	v_lshl_add_u64 v[32:33], s[48:49], 0, v[40:41]
	global_load_dwordx4 v[32:35], v[32:33], off
	s_nop 0
	global_load_dword v69, v[160:161], off offset:704
	v_lshl_add_u64 v[44:45], s[42:43], 0, v[40:41]
	v_lshl_add_u64 v[46:47], s[48:49], 0, v[38:39]
	v_lshl_add_u64 v[38:39], s[42:43], 0, v[38:39]
	v_lshl_add_u64 v[36:37], s[48:49], 0, v[36:37]
	v_lshl_add_u64 v[64:65], v[64:65], 2, s[52:53]
	s_waitcnt vmcnt(0) lgkmcnt(0)
; __device__ __forceinline__ u32x4 pack8(f32x4 a, f32x4 b) { u32x4 w; w.x = pk2(a[0], a[1]); w.y = pk2(a[2], a[3]); w.z = pk2(b[0], b[1]); w.w = pk2(b[2], b[3]); return w; }
;     __device__ __forceinline__ void operator()(const Acc& acc, const pg8::Unit& u, int wid) const {
;     ...
;                 for (int mm = 0; mm < 2; ++mm) {
;                     const int m = 2 * mp + mm, row = row0 + ai * 128 + m * 16; float sq = 0.f;
;                     const float sc = __builtin_amdgcn_rsqf(scv[mm] * (1.f / 1024.f) + EPS);
; #pragma unroll
;                     for (int bj = 0; bj < 2; ++bj) {
;                         const size_t off = (size_t)row * 1024 + col0 + bj * 128;
;                         const u32x4 pwv = pw[mm][bj], hw = hv[mm][bj];
;                         const f32x4 p0 = (f32x4){bflo(pwv.x), bfhi(pwv.x), bflo(pwv.y), bfhi(pwv.y)}, p1 = (f32x4){bflo(pwv.z), bfhi(pwv.z), bflo(pwv.w), bfhi(pwv.w)};
;                         f32x4 g0 = acc[ai][bj][m][0] * sc, g1 = acc[ai][bj][m][1] * sc;
; #pragma unroll
;                         for (int e = 0; e < 4; ++e) { g0[e] = __builtin_amdgcn_rcpf(1.f + __builtin_amdgcn_exp2f(-1.4426950408889634f * g0[e])); g1[e] = __builtin_amdgcn_rcpf(1.f + __builtin_amdgcn_exp2f(-1.4426950408889634f * g1[e])); }
;                         const f32x4 o0 = (f32x4){bflo(hw.x), bfhi(hw.x), bflo(hw.y), bfhi(hw.y)} + g0 * p0;
;                         const f32x4 o1 = (f32x4){bflo(hw.z), bfhi(hw.z), bflo(hw.w), bfhi(hw.w)} + g1 * p1;
;                         if (fout) { *(f32x4*)(fout + off) = o0; *(f32x4*)(fout + off + 4) = o1; }
;                         if (hb_out) *(u32x4*)(hb_out + off) = pack8(o0, o1);
;                         sq += (o0[0] * o0[0] + o0[1] * o0[1]) + (o0[2] * o0[2] + o0[3] * o0[3]) + (o1[0] * o1[0] + o1[1] * o1[1]) + (o1[2] * o1[2] + o1[3] * o1[3]);
;                     }
;                     if (ssq_out) { sq += __shfl_xor(sq, 16); sq += __shfl_xor(sq, 32); if (fq == 0) atomicAdd(ssq_out + row, sq); }
	v_fmamk_f32 v42, v42, 0x3a800000, v172
	v_rsq_f32_e32 v68, v42
	global_load_dwordx4 v[40:43], v[38:39], off
	global_load_dwordx4 v[60:63], v[36:37], off
	s_nop 0
	global_load_dwordx4 v[36:39], v[44:45], off
	s_nop 0
	global_load_dwordx4 v[44:47], v[46:47], off
	v_lshlrev_b32_e32 v72, 16, v50
	v_and_b32_e32 v73, 0xffff0000, v50
	v_lshlrev_b32_e32 v50, 16, v54
	v_pk_mul_f32 v[28:29], v[28:29], v[68:69] op_sel_hi:[1,0]
	s_nop 0
	v_mul_f32_e32 v28, 0xbfb8aa3b, v28
	v_exp_f32_e32 v70, v28
	v_mul_f32_e32 v28, 0xbfb8aa3b, v29
	v_exp_f32_e32 v71, v28
	v_pk_mul_f32 v[28:29], v[30:31], v[68:69] op_sel_hi:[1,0]
	v_add_f32_e32 v30, 1.0, v70
	v_mul_f32_e32 v28, 0xbfb8aa3b, v28
	v_mul_f32_e32 v29, 0xbfb8aa3b, v29
	v_exp_f32_e32 v28, v28
	v_exp_f32_e32 v29, v29
	v_rcp_f32_e32 v70, v30
	v_add_f32_e32 v30, 1.0, v71
	v_add_f32_e32 v28, 1.0, v28
	v_add_f32_e32 v29, 1.0, v29
	v_rcp_f32_e32 v71, v30
	v_rcp_f32_e32 v28, v28
	v_rcp_f32_e32 v29, v29
	v_pk_mul_f32 v[24:25], v[24:25], v[68:69] op_sel_hi:[1,0]
	v_lshlrev_b32_e32 v30, 16, v51
	v_and_b32_e32 v31, 0xffff0000, v51
	v_and_b32_e32 v51, 0xffff0000, v54
	v_lshlrev_b32_e32 v54, 16, v55
	v_and_b32_e32 v55, 0xffff0000, v55
	v_mul_f32_e32 v24, 0xbfb8aa3b, v24
	v_pk_fma_f32 v[30:31], v[28:29], v[30:31], v[54:55]
	v_pk_fma_f32 v[28:29], v[70:71], v[72:73], v[50:51]
	v_exp_f32_e32 v50, v24
	v_mul_f32_e32 v24, 0xbfb8aa3b, v25
	v_exp_f32_e32 v51, v24
	v_pk_mul_f32 v[24:25], v[26:27], v[68:69] op_sel_hi:[1,0]
	v_add_f32_e32 v26, 1.0, v50
	v_mul_f32_e32 v24, 0xbfb8aa3b, v24
	v_mul_f32_e32 v25, 0xbfb8aa3b, v25
	v_exp_f32_e32 v24, v24
	v_exp_f32_e32 v25, v25
	v_rcp_f32_e32 v50, v26
	v_add_f32_e32 v26, 1.0, v51
	v_add_f32_e32 v24, 1.0, v24
	v_add_f32_e32 v25, 1.0, v25
	v_rcp_f32_e32 v51, v26
	v_rcp_f32_e32 v24, v24
	v_rcp_f32_e32 v25, v25
	v_lshlrev_b32_e32 v54, 16, v48
	v_and_b32_e32 v55, 0xffff0000, v48
	v_lshlrev_b32_e32 v26, 16, v49
	v_and_b32_e32 v27, 0xffff0000, v49
	v_lshlrev_b32_e32 v48, 16, v52
	v_and_b32_e32 v49, 0xffff0000, v52
	v_lshlrev_b32_e32 v52, 16, v53
	v_and_b32_e32 v53, 0xffff0000, v53
	v_pk_mul_f32 v[20:21], v[20:21], v[68:69] op_sel_hi:[1,0]
	v_pk_fma_f32 v[26:27], v[24:25], v[26:27], v[52:53]
	v_pk_fma_f32 v[24:25], v[50:51], v[54:55], v[48:49]
	v_mul_f32_e32 v20, 0xbfb8aa3b, v20
	global_store_dwordx4 v[64:65], v[24:27], off
	global_store_dwordx4 v[64:65], v[28:31], off offset:16
	v_pk_mul_f32 v[16:17], v[16:17], v[68:69] op_sel_hi:[1,0]
	v_exp_f32_e32 v24, v20
	v_mul_f32_e32 v20, 0xbfb8aa3b, v21
	v_exp_f32_e32 v25, v20
	v_pk_mul_f32 v[20:21], v[22:23], v[68:69] op_sel_hi:[1,0]
	v_add_f32_e32 v22, 1.0, v24
	v_mul_f32_e32 v20, 0xbfb8aa3b, v20
	v_mul_f32_e32 v21, 0xbfb8aa3b, v21
	v_exp_f32_e32 v20, v20
	v_exp_f32_e32 v21, v21
	v_rcp_f32_e32 v24, v22
	v_add_f32_e32 v22, 1.0, v25
	v_add_f32_e32 v20, 1.0, v20
	v_add_f32_e32 v21, 1.0, v21
	v_rcp_f32_e32 v25, v22
	v_rcp_f32_e32 v20, v20
	v_rcp_f32_e32 v21, v21
	s_waitcnt vmcnt(0) lgkmcnt(0)
; __device__ __forceinline__ u32x4 pack8(f32x4 a, f32x4 b) { u32x4 w; w.x = pk2(a[0], a[1]); w.y = pk2(a[2], a[3]); w.z = pk2(b[0], b[1]); w.w = pk2(b[2], b[3]); return w; }
;     __device__ __forceinline__ void operator()(const Acc& acc, const pg8::Unit& u, int wid) const {
;     ...
;                 for (int mm = 0; mm < 2; ++mm) {
;                     const int m = 2 * mp + mm, row = row0 + ai * 128 + m * 16; float sq = 0.f;
;                     const float sc = __builtin_amdgcn_rsqf(scv[mm] * (1.f / 1024.f) + EPS);
; #pragma unroll
;                     for (int bj = 0; bj < 2; ++bj) {
;                         const size_t off = (size_t)row * 1024 + col0 + bj * 128;
;                         const u32x4 pwv = pw[mm][bj], hw = hv[mm][bj];
;                         const f32x4 p0 = (f32x4){bflo(pwv.x), bfhi(pwv.x), bflo(pwv.y), bfhi(pwv.y)}, p1 = (f32x4){bflo(pwv.z), bfhi(pwv.z), bflo(pwv.w), bfhi(pwv.w)};
;                         f32x4 g0 = acc[ai][bj][m][0] * sc, g1 = acc[ai][bj][m][1] * sc;
; #pragma unroll
;                         for (int e = 0; e < 4; ++e) { g0[e] = __builtin_amdgcn_rcpf(1.f + __builtin_amdgcn_exp2f(-1.4426950408889634f * g0[e])); g1[e] = __builtin_amdgcn_rcpf(1.f + __builtin_amdgcn_exp2f(-1.4426950408889634f * g1[e])); }
;                         const f32x4 o0 = (f32x4){bflo(hw.x), bfhi(hw.x), bflo(hw.y), bfhi(hw.y)} + g0 * p0;
;                         const f32x4 o1 = (f32x4){bflo(hw.z), bfhi(hw.z), bflo(hw.w), bfhi(hw.w)} + g1 * p1;
;                         if (fout) { *(f32x4*)(fout + off) = o0; *(f32x4*)(fout + off + 4) = o1; }
;                         if (hb_out) *(u32x4*)(hb_out + off) = pack8(o0, o1);
;                         sq += (o0[0] * o0[0] + o0[1] * o0[1]) + (o0[2] * o0[2] + o0[3] * o0[3]) + (o1[0] * o1[0] + o1[1] * o1[1]) + (o1[2] * o1[2] + o1[3] * o1[3]);
;                     }
;                     if (ssq_out) { sq += __shfl_xor(sq, 16); sq += __shfl_xor(sq, 32); if (fq == 0) atomicAdd(ssq_out + row, sq); }
	v_lshlrev_b32_e32 v26, 16, v62
	v_and_b32_e32 v27, 0xffff0000, v62
	v_lshlrev_b32_e32 v22, 16, v63
	v_and_b32_e32 v23, 0xffff0000, v63
	v_lshlrev_b32_e32 v28, 16, v58
	v_and_b32_e32 v29, 0xffff0000, v58
	v_lshlrev_b32_e32 v30, 16, v59
	v_and_b32_e32 v31, 0xffff0000, v59
	v_mul_f32_e32 v16, 0xbfb8aa3b, v16
	v_pk_fma_f32 v[22:23], v[20:21], v[22:23], v[30:31]
	v_pk_fma_f32 v[20:21], v[24:25], v[26:27], v[28:29]
	v_exp_f32_e32 v24, v16
	v_mul_f32_e32 v16, 0xbfb8aa3b, v17
	v_exp_f32_e32 v25, v16
	v_pk_mul_f32 v[16:17], v[18:19], v[68:69] op_sel_hi:[1,0]
	v_add_f32_e32 v18, 1.0, v24
	v_mul_f32_e32 v16, 0xbfb8aa3b, v16
	v_mul_f32_e32 v17, 0xbfb8aa3b, v17
	v_exp_f32_e32 v16, v16
	v_exp_f32_e32 v17, v17
	v_rcp_f32_e32 v24, v18
	v_add_f32_e32 v18, 1.0, v25
	v_add_f32_e32 v16, 1.0, v16
	v_add_f32_e32 v17, 1.0, v17
	v_rcp_f32_e32 v25, v18
	v_rcp_f32_e32 v16, v16
	v_rcp_f32_e32 v17, v17
	v_lshlrev_b32_e32 v26, 16, v60
	v_and_b32_e32 v27, 0xffff0000, v60
	v_lshlrev_b32_e32 v18, 16, v61
	v_and_b32_e32 v19, 0xffff0000, v61
	v_lshlrev_b32_e32 v28, 16, v56
	v_and_b32_e32 v29, 0xffff0000, v56
	v_lshlrev_b32_e32 v30, 16, v57
	v_and_b32_e32 v31, 0xffff0000, v57
	v_pk_fma_f32 v[18:19], v[16:17], v[18:19], v[30:31]
	v_pk_fma_f32 v[16:17], v[24:25], v[26:27], v[28:29]
	v_fmamk_f32 v24, v69, 0x3a800000, v172
	v_rsq_f32_e32 v24, v24
	global_store_dwordx4 v[64:65], v[16:19], off offset:512
	global_store_dwordx4 v[64:65], v[20:23], off offset:528
	v_lshlrev_b32_e32 v26, 16, v43
	v_and_b32_e32 v27, 0xffff0000, v43
	v_pk_mul_f32 v[12:13], v[12:13], v[24:25] op_sel_hi:[1,0]
	v_pk_mul_f32 v[8:9], v[8:9], v[24:25] op_sel_hi:[1,0]
	v_mul_f32_e32 v12, 0xbfb8aa3b, v12
	v_exp_f32_e32 v18, v12
	v_mul_f32_e32 v12, 0xbfb8aa3b, v13
	v_exp_f32_e32 v19, v12
	v_pk_mul_f32 v[12:13], v[14:15], v[24:25] op_sel_hi:[1,0]
	v_add_f32_e32 v14, 1.0, v18
	v_mul_f32_e32 v12, 0xbfb8aa3b, v12
	v_mul_f32_e32 v13, 0xbfb8aa3b, v13
	v_exp_f32_e32 v12, v12
	v_exp_f32_e32 v13, v13
	v_rcp_f32_e32 v18, v14
	v_add_f32_e32 v14, 1.0, v19
	v_add_f32_e32 v12, 1.0, v12
	v_add_f32_e32 v13, 1.0, v13
	v_rcp_f32_e32 v19, v14
	v_rcp_f32_e32 v12, v12
	v_rcp_f32_e32 v13, v13
	v_lshlrev_b32_e32 v20, 16, v46
	v_and_b32_e32 v21, 0xffff0000, v46
	v_lshlrev_b32_e32 v14, 16, v47
	v_and_b32_e32 v15, 0xffff0000, v47
	v_lshlrev_b32_e32 v22, 16, v42
	v_and_b32_e32 v23, 0xffff0000, v42
	v_mul_f32_e32 v8, 0xbfb8aa3b, v8
	v_pk_fma_f32 v[14:15], v[12:13], v[14:15], v[26:27]
	v_pk_fma_f32 v[12:13], v[18:19], v[20:21], v[22:23]
	v_exp_f32_e32 v18, v8
	v_mul_f32_e32 v8, 0xbfb8aa3b, v9
	v_exp_f32_e32 v19, v8
	v_pk_mul_f32 v[8:9], v[10:11], v[24:25] op_sel_hi:[1,0]
	v_add_f32_e32 v10, 1.0, v18
	v_mul_f32_e32 v8, 0xbfb8aa3b, v8
	v_mul_f32_e32 v9, 0xbfb8aa3b, v9
	v_exp_f32_e32 v8, v8
	v_exp_f32_e32 v9, v9
	v_rcp_f32_e32 v18, v10
	v_add_f32_e32 v10, 1.0, v19
	v_add_f32_e32 v8, 1.0, v8
	v_add_f32_e32 v9, 1.0, v9
	v_rcp_f32_e32 v19, v10
	v_rcp_f32_e32 v8, v8
	v_rcp_f32_e32 v9, v9
	v_lshlrev_b32_e32 v20, 16, v44
	v_and_b32_e32 v21, 0xffff0000, v44
	v_lshlrev_b32_e32 v10, 16, v45
	v_and_b32_e32 v11, 0xffff0000, v45
	v_lshlrev_b32_e32 v22, 16, v40
	v_and_b32_e32 v23, 0xffff0000, v40
	v_lshlrev_b32_e32 v26, 16, v41
	v_and_b32_e32 v27, 0xffff0000, v41
	v_pk_mul_f32 v[4:5], v[4:5], v[24:25] op_sel_hi:[1,0]
	v_lshl_add_u64 v[16:17], v[66:67], 2, s[52:53]
	v_pk_fma_f32 v[10:11], v[8:9], v[10:11], v[26:27]
	v_pk_fma_f32 v[8:9], v[18:19], v[20:21], v[22:23]
	v_mul_f32_e32 v4, 0xbfb8aa3b, v4
	global_store_dwordx4 v[16:17], v[8:11], off
	global_store_dwordx4 v[16:17], v[12:15], off offset:16
	v_pk_mul_f32 v[0:1], v[0:1], v[24:25] op_sel_hi:[1,0]
	v_exp_f32_e32 v8, v4
	v_mul_f32_e32 v4, 0xbfb8aa3b, v5
	v_exp_f32_e32 v9, v4
	v_pk_mul_f32 v[4:5], v[6:7], v[24:25] op_sel_hi:[1,0]
	v_add_f32_e32 v6, 1.0, v8
	v_mul_f32_e32 v4, 0xbfb8aa3b, v4
	v_mul_f32_e32 v5, 0xbfb8aa3b, v5
	v_exp_f32_e32 v4, v4
	v_exp_f32_e32 v5, v5
	v_rcp_f32_e32 v8, v6
	v_add_f32_e32 v6, 1.0, v9
	v_add_f32_e32 v4, 1.0, v4
	v_add_f32_e32 v5, 1.0, v5
	v_rcp_f32_e32 v9, v6
	v_rcp_f32_e32 v4, v4
	v_rcp_f32_e32 v5, v5
	v_lshlrev_b32_e32 v10, 16, v34
	v_and_b32_e32 v11, 0xffff0000, v34
	v_lshlrev_b32_e32 v6, 16, v35
	v_and_b32_e32 v7, 0xffff0000, v35
	v_lshlrev_b32_e32 v12, 16, v38
	v_and_b32_e32 v13, 0xffff0000, v38
	v_lshlrev_b32_e32 v14, 16, v39
	v_and_b32_e32 v15, 0xffff0000, v39
	v_mul_f32_e32 v0, 0xbfb8aa3b, v0
	v_pk_fma_f32 v[6:7], v[4:5], v[6:7], v[14:15]
	v_pk_fma_f32 v[4:5], v[8:9], v[10:11], v[12:13]
	v_exp_f32_e32 v8, v0
	v_mul_f32_e32 v0, 0xbfb8aa3b, v1
	v_exp_f32_e32 v9, v0
	v_pk_mul_f32 v[0:1], v[2:3], v[24:25] op_sel_hi:[1,0]
	v_add_f32_e32 v2, 1.0, v8
	v_mul_f32_e32 v0, 0xbfb8aa3b, v0
	v_mul_f32_e32 v1, 0xbfb8aa3b, v1
	v_exp_f32_e32 v0, v0
	v_exp_f32_e32 v1, v1
	v_rcp_f32_e32 v8, v2
	v_add_f32_e32 v2, 1.0, v9
	v_add_f32_e32 v0, 1.0, v0
	v_add_f32_e32 v1, 1.0, v1
	v_rcp_f32_e32 v9, v2
	v_rcp_f32_e32 v0, v0
	v_rcp_f32_e32 v1, v1
	v_lshlrev_b32_e32 v10, 16, v32
	v_and_b32_e32 v11, 0xffff0000, v32
	v_lshlrev_b32_e32 v2, 16, v33
	v_and_b32_e32 v3, 0xffff0000, v33
	v_lshlrev_b32_e32 v12, 16, v36
	v_and_b32_e32 v13, 0xffff0000, v36
	v_lshlrev_b32_e32 v14, 16, v37
	v_and_b32_e32 v15, 0xffff0000, v37
	v_pk_fma_f32 v[2:3], v[0:1], v[2:3], v[14:15]
	v_pk_fma_f32 v[0:1], v[8:9], v[10:11], v[12:13]
	global_store_dwordx4 v[16:17], v[0:3], off offset:512
	global_store_dwordx4 v[16:17], v[4:7], off offset:528
